# a+b plus: K-loop LDS-DMA nops replaced by moved ds_reads (DMA issue interleaved with the read burst), -16 instr per trip
# speedup vs baseline: 1.0066x; 1.0053x over previous
; #define PG8_STAGE(bufoff, gbase, voff) do { const char* _gb = (const char*)(gbase); asm volatile("" : "+s"(_gb)); _Pragma("unroll") for (int _i = 0; _i < 2; ++_i) { asm volatile("" : "+v"((voff)[_i])); \
;         __builtin_amdgcn_global_load_lds((const unsigned*)(_gb + (voff)[_i]), (PG8_LAS unsigned*)(lds + (bufoff) + ldsw + _i * 8192), 16, 0, 0); } } while (0)
; #define PG8_LDA(dst, b, h) do { _Pragma("unroll") for (int m = 0; m < 4; ++m) _Pragma("unroll") for (int k = 0; k < 2; ++k) dst[m][k] = *(const PG8_LAS bf16x8*)(lds + PG8_SA(b, h) + aoff + m * 2048 + k * 1024); } while (0)
; #define PG8_LDB(dst, b, h) do { _Pragma("unroll") for (int n = 0; n < 2; ++n) _Pragma("unroll") for (int k = 0; k < 2; ++k) dst[n][k] = *(const PG8_LAS bf16x8*)(lds + PG8_SB(b, h) + boff + n * 2048 + k * 1024); } while (0)
; #define PG8_WAIT_V(n) asm volatile("s_waitcnt vmcnt(" #n ")" ::: "memory")
; #define PG8_WAIT_L(n) asm volatile("s_waitcnt lgkmcnt(" #n ")" ::: "memory")
; #define PG8_BAR __builtin_amdgcn_s_barrier()
; #define PG8_SCHED __builtin_amdgcn_sched_barrier(0)
; #define PG8_LDA(dst, b, h) do { _Pragma("unroll") for (int m = 0; m < 4; ++m) _Pragma("unroll") for (int k = 0; k < 2; ++k) dst[m][k] = *(const PG8_LAS bf16x8*)(lds + PG8_SA(b, h) + aoff + m * 2048 + k * 1024); } while (0)
; #define PG8_BAR __builtin_amdgcn_s_barrier()
; template <class Epi, class Sched, bool ALIGN_EPI = false, bool SP2 = false>
; __device__ __forceinline__ void gemm_phase(PG8_LAS unsigned char* lds, const Gemm g, const Sched& S, const Epi& E) {
;     ...
;             const bool last = (t == nt - 2);
;             const char* a1 = cA + (size_t)(t + 1) * kstep;
;             const char* a2 = last ? nA : cA + (size_t)(t + 2) * kstep; const char* b2 = last ? nB : cB + (size_t)(t + 2) * kstep;
;             const char* a3 = a2 + kstep; const char* b3 = b2 + kstep;
;             if (last && has_next) S.a_ready(nxt);
;             if constexpr (SP2) {
;             PG8_LDB(B0, 0, 0); PG8_LDB(B1, 0, 1); PG8_SCHED; PG8_LDA(At, 0, 0); PG8_STAGE(PG8_SA(1, 1), a1 + hstep, voffA);
;             PG8_WAIT_V(8); PG8_WAIT_L(0); PG8_BAR; PG8_MMA2(0); PG8_BAR; PG8_SCHED;
;             PG8_LDA(At, 0, 1); PG8_STAGE(PG8_SB(0, 0), b2, voffB); PG8_STAGE(PG8_SB(0, 1), b2 + hstep, voffB); PG8_STAGE(PG8_SA(0, 0), a2, voffA);
;             PG8_WAIT_V(8); PG8_WAIT_L(0); PG8_BAR; PG8_MMA2(1); PG8_BAR; PG8_SCHED;
.LBB0_313:
	ds_read_b128 v[136:139], v150
	ds_read_b128 v[140:143], v150 offset:1024
	ds_read_b128 v[154:157], v150 offset:2048
	ds_read_b128 v[158:161], v150 offset:3072
	ds_read_b128 v[162:165], v151
	ds_read_b128 v[166:169], v151 offset:1024
	ds_read_b128 v[170:173], v151 offset:2048
	ds_read_b128 v[174:177], v151 offset:3072
	s_add_u32 s14, s8, 0x100
	s_addc_u32 s15, s9, 0
	s_cmp_eq_u32 s43, 60
	s_cselect_b32 s24, s13, s14
	s_cselect_b32 s25, s11, s15
	s_cselect_b32 s16, s36, s37
	s_cselect_b32 s17, s33, s42
	s_add_u32 s2, s24, 0x80
	s_addc_u32 s3, s25, 0
	s_add_u32 s8, s8, 0x100080
	s_addc_u32 s9, s9, 0
	s_add_i32 m0, s63, 0xc000
	ds_read_b128 v[178:181], v152
	ds_read_b128 v[182:185], v152 offset:1024
	ds_read_b128 v[186:189], v152 offset:2048
	ds_read_b128 v[190:193], v152 offset:3072
	ds_read_b128 v[194:197], v152 offset:4096
	ds_read_b128 v[198:201], v152 offset:5120
	ds_read_b128 v[202:205], v152 offset:6144
	global_load_lds_dwordx4 v1, s[8:9]
	s_add_i32 m0, s63, 0xe000
	ds_read_b128 v[206:209], v152 offset:7168
	global_load_lds_dwordx4 v145, s[8:9]
	s_waitcnt vmcnt(8)
	s_waitcnt lgkmcnt(0)
	s_setprio 1
	s_waitcnt lgkmcnt(0)
	s_barrier
	v_mfma_f32_16x16x32_bf16 v[126:129], v[136:139], v[178:181], v[126:129]
	v_mfma_f32_16x16x32_bf16 v[122:125], v[154:157], v[178:181], v[122:125]
	v_mfma_f32_16x16x32_bf16 v[110:113], v[136:139], v[186:189], v[110:113]
	v_mfma_f32_16x16x32_bf16 v[106:109], v[154:157], v[186:189], v[106:109]
	v_mfma_f32_16x16x32_bf16 v[94:97], v[136:139], v[194:197], v[94:97]
	v_mfma_f32_16x16x32_bf16 v[90:93], v[154:157], v[194:197], v[90:93]
	v_mfma_f32_16x16x32_bf16 v[78:81], v[136:139], v[202:205], v[78:81]
	v_mfma_f32_16x16x32_bf16 v[74:77], v[154:157], v[202:205], v[74:77]
	v_mfma_f32_16x16x32_bf16 v[118:121], v[162:165], v[178:181], v[118:121]
	v_mfma_f32_16x16x32_bf16 v[114:117], v[170:173], v[178:181], v[114:117]
	v_mfma_f32_16x16x32_bf16 v[102:105], v[162:165], v[186:189], v[102:105]
	v_mfma_f32_16x16x32_bf16 v[98:101], v[170:173], v[186:189], v[98:101]
	v_mfma_f32_16x16x32_bf16 v[86:89], v[162:165], v[194:197], v[86:89]
	v_mfma_f32_16x16x32_bf16 v[82:85], v[170:173], v[194:197], v[82:85]
	v_mfma_f32_16x16x32_bf16 v[70:73], v[162:165], v[202:205], v[70:73]
	v_mfma_f32_16x16x32_bf16 v[66:69], v[170:173], v[202:205], v[66:69]
	v_mfma_f32_16x16x32_bf16 v[126:129], v[140:143], v[182:185], v[126:129]
	v_mfma_f32_16x16x32_bf16 v[122:125], v[158:161], v[182:185], v[122:125]
	v_mfma_f32_16x16x32_bf16 v[110:113], v[140:143], v[190:193], v[110:113]
	v_mfma_f32_16x16x32_bf16 v[106:109], v[158:161], v[190:193], v[106:109]
	v_mfma_f32_16x16x32_bf16 v[94:97], v[140:143], v[198:201], v[94:97]
	v_mfma_f32_16x16x32_bf16 v[90:93], v[158:161], v[198:201], v[90:93]
	v_mfma_f32_16x16x32_bf16 v[78:81], v[140:143], v[206:209], v[78:81]
	v_mfma_f32_16x16x32_bf16 v[74:77], v[158:161], v[206:209], v[74:77]
	v_mfma_f32_16x16x32_bf16 v[118:121], v[166:169], v[182:185], v[118:121]
	v_mfma_f32_16x16x32_bf16 v[114:117], v[174:177], v[182:185], v[114:117]
	v_mfma_f32_16x16x32_bf16 v[102:105], v[166:169], v[190:193], v[102:105]
	v_mfma_f32_16x16x32_bf16 v[98:101], v[174:177], v[190:193], v[98:101]
	v_mfma_f32_16x16x32_bf16 v[86:89], v[166:169], v[198:201], v[86:89]
	v_mfma_f32_16x16x32_bf16 v[82:85], v[174:177], v[198:201], v[82:85]
	v_mfma_f32_16x16x32_bf16 v[70:73], v[166:169], v[206:209], v[70:73]
	v_mfma_f32_16x16x32_bf16 v[66:69], v[174:177], v[206:209], v[66:69]
	s_setprio 0
	s_barrier
	s_add_i32 s44, s95, s61
	s_mov_b64 s[8:9], s[16:17]
	s_mov_b32 m0, s44
	ds_read_b128 v[178:181], v152 offset:16384
	ds_read_b128 v[182:185], v152 offset:17408
	ds_read_b128 v[186:189], v152 offset:18432
	global_load_lds_dwordx4 v144, s[8:9]
	s_add_i32 m0, s44, 0x2000
	ds_read_b128 v[190:193], v152 offset:19456
	global_load_lds_dwordx4 v146, s[8:9]
	s_add_u32 s8, s16, 0x100000
	s_addc_u32 s9, s17, 0
	s_add_i32 s44, s96, s61
	s_mov_b32 m0, s44
	ds_read_b128 v[194:197], v152 offset:20480
	global_load_lds_dwordx4 v144, s[8:9]
	s_add_i32 m0, s44, 0x2000
	ds_read_b128 v[198:201], v152 offset:21504
	global_load_lds_dwordx4 v146, s[8:9]
	s_mov_b64 s[8:9], s[24:25]
	s_mov_b32 m0, s63
	ds_read_b128 v[202:205], v152 offset:22528
	global_load_lds_dwordx4 v1, s[8:9]
	s_mov_b32 m0, s65
	ds_read_b128 v[206:209], v152 offset:23552
	global_load_lds_dwordx4 v145, s[8:9]
	s_waitcnt vmcnt(8)
	s_waitcnt lgkmcnt(0)
	s_setprio 1
	s_waitcnt lgkmcnt(0)
	s_barrier
	v_mfma_f32_16x16x32_bf16 v[62:65], v[136:139], v[178:181], v[62:65]
	v_mfma_f32_16x16x32_bf16 v[58:61], v[154:157], v[178:181], v[58:61]
	v_mfma_f32_16x16x32_bf16 v[46:49], v[136:139], v[186:189], v[46:49]
	v_mfma_f32_16x16x32_bf16 v[42:45], v[154:157], v[186:189], v[42:45]
	v_mfma_f32_16x16x32_bf16 v[30:33], v[136:139], v[194:197], v[30:33]
	v_mfma_f32_16x16x32_bf16 v[26:29], v[154:157], v[194:197], v[26:29]
	v_mfma_f32_16x16x32_bf16 v[14:17], v[136:139], v[202:205], v[14:17]
	v_mfma_f32_16x16x32_bf16 v[10:13], v[154:157], v[202:205], v[10:13]
	v_mfma_f32_16x16x32_bf16 v[54:57], v[162:165], v[178:181], v[54:57]
	v_mfma_f32_16x16x32_bf16 v[50:53], v[170:173], v[178:181], v[50:53]
	v_mfma_f32_16x16x32_bf16 v[38:41], v[162:165], v[186:189], v[38:41]
	v_mfma_f32_16x16x32_bf16 v[34:37], v[170:173], v[186:189], v[34:37]
	v_mfma_f32_16x16x32_bf16 v[22:25], v[162:165], v[194:197], v[22:25]
	v_mfma_f32_16x16x32_bf16 v[18:21], v[170:173], v[194:197], v[18:21]
	v_mfma_f32_16x16x32_bf16 v[6:9], v[162:165], v[202:205], v[6:9]
	v_mfma_f32_16x16x32_bf16 v[2:5], v[170:173], v[202:205], v[2:5]
	v_mfma_f32_16x16x32_bf16 v[62:65], v[140:143], v[182:185], v[62:65]
	v_mfma_f32_16x16x32_bf16 v[58:61], v[158:161], v[182:185], v[58:61]
	v_mfma_f32_16x16x32_bf16 v[46:49], v[140:143], v[190:193], v[46:49]
	v_mfma_f32_16x16x32_bf16 v[42:45], v[158:161], v[190:193], v[42:45]
	v_mfma_f32_16x16x32_bf16 v[30:33], v[140:143], v[198:201], v[30:33]
	v_mfma_f32_16x16x32_bf16 v[26:29], v[158:161], v[198:201], v[26:29]
	v_mfma_f32_16x16x32_bf16 v[14:17], v[140:143], v[206:209], v[14:17]
	v_mfma_f32_16x16x32_bf16 v[10:13], v[158:161], v[206:209], v[10:13]
	v_mfma_f32_16x16x32_bf16 v[54:57], v[166:169], v[182:185], v[54:57]
	v_mfma_f32_16x16x32_bf16 v[50:53], v[174:177], v[182:185], v[50:53]
	v_mfma_f32_16x16x32_bf16 v[38:41], v[166:169], v[190:193], v[38:41]
	v_mfma_f32_16x16x32_bf16 v[34:37], v[174:177], v[190:193], v[34:37]
	v_mfma_f32_16x16x32_bf16 v[22:25], v[166:169], v[198:201], v[22:25]
	v_mfma_f32_16x16x32_bf16 v[18:21], v[174:177], v[198:201], v[18:21]
	v_mfma_f32_16x16x32_bf16 v[6:9], v[166:169], v[206:209], v[6:9]
	v_mfma_f32_16x16x32_bf16 v[2:5], v[174:177], v[206:209], v[2:5]
	s_setprio 0
	s_barrier
; #define PG8_STAGE(bufoff, gbase, voff) do { const char* _gb = (const char*)(gbase); asm volatile("" : "+s"(_gb)); _Pragma("unroll") for (int _i = 0; _i < 2; ++_i) { asm volatile("" : "+v"((voff)[_i])); \
;         __builtin_amdgcn_global_load_lds((const unsigned*)(_gb + (voff)[_i]), (PG8_LAS unsigned*)(lds + (bufoff) + ldsw + _i * 8192), 16, 0, 0); } } while (0)
; #define PG8_LDA(dst, b, h) do { _Pragma("unroll") for (int m = 0; m < 4; ++m) _Pragma("unroll") for (int k = 0; k < 2; ++k) dst[m][k] = *(const PG8_LAS bf16x8*)(lds + PG8_SA(b, h) + aoff + m * 2048 + k * 1024); } while (0)
; #define PG8_LDB(dst, b, h) do { _Pragma("unroll") for (int n = 0; n < 2; ++n) _Pragma("unroll") for (int k = 0; k < 2; ++k) dst[n][k] = *(const PG8_LAS bf16x8*)(lds + PG8_SB(b, h) + boff + n * 2048 + k * 1024); } while (0)
; #define PG8_WAIT_V(n) asm volatile("s_waitcnt vmcnt(" #n ")" ::: "memory")
; #define PG8_WAIT_L(n) asm volatile("s_waitcnt lgkmcnt(" #n ")" ::: "memory")
; #define PG8_BAR __builtin_amdgcn_s_barrier()
; #define PG8_SCHED __builtin_amdgcn_sched_barrier(0)
; #define PG8_STAGE(bufoff, gbase, voff) do { const char* _gb = (const char*)(gbase); asm volatile("" : "+s"(_gb)); _Pragma("unroll") for (int _i = 0; _i < 2; ++_i) { asm volatile("" : "+v"((voff)[_i])); \
;         __builtin_amdgcn_global_load_lds((const unsigned*)(_gb + (voff)[_i]), (PG8_LAS unsigned*)(lds + (bufoff) + ldsw + _i * 8192), 16, 0, 0); } } while (0)
; #define PG8_LDA(dst, b, h) do { _Pragma("unroll") for (int m = 0; m < 4; ++m) _Pragma("unroll") for (int k = 0; k < 2; ++k) dst[m][k] = *(const PG8_LAS bf16x8*)(lds + PG8_SA(b, h) + aoff + m * 2048 + k * 1024); } while (0)
; template <class Epi, class Sched, bool ALIGN_EPI = false, bool SP2 = false>
; __device__ __forceinline__ void gemm_phase(PG8_LAS unsigned char* lds, const Gemm g, const Sched& S, const Epi& E) {
;     ...
;             PG8_LDB(B0, 1, 0); PG8_LDB(B1, 1, 1); PG8_SCHED; PG8_LDA(At, 1, 0); PG8_STAGE(PG8_SA(0, 1), a2 + hstep, voffA);
;             PG8_WAIT_V(8); PG8_WAIT_L(0); PG8_BAR; PG8_MMA2(0); PG8_BAR; PG8_SCHED;
;             PG8_LDA(At, 1, 1); PG8_STAGE(PG8_SB(1, 0), b3, voffB); PG8_STAGE(PG8_SB(1, 1), b3 + hstep, voffB); PG8_STAGE(PG8_SA(1, 0), a3, voffA);
;             PG8_WAIT_V(8); PG8_WAIT_L(0); PG8_BAR; PG8_MMA2(1); PG8_BAR; PG8_SCHED;
;     ...
;         if constexpr (ALIGN_EPI) { if (wr == 0) PG8_BAR; }
	s_add_i32 s44, 0, 0x18000
	v_add_u32_e32 v135, s44, v148
	s_add_i32 s45, 0, 0x1c000
	ds_read_b128 v[136:139], v135
	ds_read_b128 v[140:143], v135 offset:1024
	ds_read_b128 v[154:157], v135 offset:2048
	ds_read_b128 v[158:161], v135 offset:3072
	v_add_u32_e32 v135, s45, v148
	ds_read_b128 v[162:165], v135
	ds_read_b128 v[166:169], v135 offset:1024
	ds_read_b128 v[170:173], v135 offset:2048
	ds_read_b128 v[174:177], v135 offset:3072
	s_add_u32 s8, s24, 0x100000
	s_addc_u32 s9, s25, 0
	s_mov_b32 m0, s88
	ds_read_b128 v[178:181], v152 offset:32768
	ds_read_b128 v[182:185], v152 offset:33792
	ds_read_b128 v[186:189], v152 offset:34816
	ds_read_b128 v[190:193], v152 offset:35840
	ds_read_b128 v[194:197], v152 offset:36864
	ds_read_b128 v[198:201], v152 offset:37888
	ds_read_b128 v[202:205], v152 offset:38912
	global_load_lds_dwordx4 v1, s[8:9]
	s_mov_b32 m0, s89
	ds_read_b128 v[206:209], v152 offset:39936
	global_load_lds_dwordx4 v145, s[8:9]
	s_waitcnt vmcnt(8)
	s_waitcnt lgkmcnt(0)
	s_setprio 1
	s_waitcnt lgkmcnt(0)
	s_barrier
	v_mfma_f32_16x16x32_bf16 v[126:129], v[136:139], v[178:181], v[126:129]
	v_mfma_f32_16x16x32_bf16 v[122:125], v[154:157], v[178:181], v[122:125]
	v_mfma_f32_16x16x32_bf16 v[110:113], v[136:139], v[186:189], v[110:113]
	v_mfma_f32_16x16x32_bf16 v[106:109], v[154:157], v[186:189], v[106:109]
	v_mfma_f32_16x16x32_bf16 v[94:97], v[136:139], v[194:197], v[94:97]
	v_mfma_f32_16x16x32_bf16 v[90:93], v[154:157], v[194:197], v[90:93]
	v_mfma_f32_16x16x32_bf16 v[78:81], v[136:139], v[202:205], v[78:81]
	v_mfma_f32_16x16x32_bf16 v[74:77], v[154:157], v[202:205], v[74:77]
	v_mfma_f32_16x16x32_bf16 v[118:121], v[162:165], v[178:181], v[118:121]
	v_mfma_f32_16x16x32_bf16 v[114:117], v[170:173], v[178:181], v[114:117]
	v_mfma_f32_16x16x32_bf16 v[102:105], v[162:165], v[186:189], v[102:105]
	v_mfma_f32_16x16x32_bf16 v[98:101], v[170:173], v[186:189], v[98:101]
	v_mfma_f32_16x16x32_bf16 v[86:89], v[162:165], v[194:197], v[86:89]
	v_mfma_f32_16x16x32_bf16 v[82:85], v[170:173], v[194:197], v[82:85]
	v_mfma_f32_16x16x32_bf16 v[70:73], v[162:165], v[202:205], v[70:73]
	v_mfma_f32_16x16x32_bf16 v[66:69], v[170:173], v[202:205], v[66:69]
	v_mfma_f32_16x16x32_bf16 v[126:129], v[140:143], v[182:185], v[126:129]
	v_mfma_f32_16x16x32_bf16 v[122:125], v[158:161], v[182:185], v[122:125]
	v_mfma_f32_16x16x32_bf16 v[110:113], v[140:143], v[190:193], v[110:113]
	v_mfma_f32_16x16x32_bf16 v[106:109], v[158:161], v[190:193], v[106:109]
	v_mfma_f32_16x16x32_bf16 v[94:97], v[140:143], v[198:201], v[94:97]
	v_mfma_f32_16x16x32_bf16 v[90:93], v[158:161], v[198:201], v[90:93]
	v_mfma_f32_16x16x32_bf16 v[78:81], v[140:143], v[206:209], v[78:81]
	v_mfma_f32_16x16x32_bf16 v[74:77], v[158:161], v[206:209], v[74:77]
	v_mfma_f32_16x16x32_bf16 v[118:121], v[166:169], v[182:185], v[118:121]
	v_mfma_f32_16x16x32_bf16 v[114:117], v[174:177], v[182:185], v[114:117]
	v_mfma_f32_16x16x32_bf16 v[102:105], v[166:169], v[190:193], v[102:105]
	v_mfma_f32_16x16x32_bf16 v[98:101], v[174:177], v[190:193], v[98:101]
	v_mfma_f32_16x16x32_bf16 v[86:89], v[166:169], v[198:201], v[86:89]
	v_mfma_f32_16x16x32_bf16 v[82:85], v[174:177], v[198:201], v[82:85]
	v_mfma_f32_16x16x32_bf16 v[70:73], v[166:169], v[206:209], v[70:73]
	v_mfma_f32_16x16x32_bf16 v[66:69], v[174:177], v[206:209], v[66:69]
	s_setprio 0
	s_barrier
	s_add_u32 s8, s16, 0x80
	s_addc_u32 s9, s17, 0
	s_add_i32 s24, s44, s61
	s_mov_b32 m0, s24
	ds_read_b128 v[178:181], v152 offset:49152
	ds_read_b128 v[182:185], v152 offset:50176
	ds_read_b128 v[186:189], v152 offset:51200
	global_load_lds_dwordx4 v144, s[8:9]
	s_add_i32 m0, s24, 0x2000
	ds_read_b128 v[190:193], v152 offset:52224
	global_load_lds_dwordx4 v146, s[8:9]
	s_add_u32 s8, s16, 0x100080
	s_addc_u32 s9, s17, 0
	s_add_i32 s16, s45, s61
	s_mov_b32 m0, s16
	ds_read_b128 v[194:197], v152 offset:53248
	global_load_lds_dwordx4 v144, s[8:9]
	s_add_i32 m0, s16, 0x2000
	ds_read_b128 v[198:201], v152 offset:54272
	global_load_lds_dwordx4 v146, s[8:9]
	s_mov_b32 m0, s91
	ds_read_b128 v[202:205], v152 offset:55296
	global_load_lds_dwordx4 v1, s[2:3]
	s_mov_b32 m0, s92
	ds_read_b128 v[206:209], v152 offset:56320
	global_load_lds_dwordx4 v145, s[2:3]
	s_waitcnt vmcnt(8)
	s_waitcnt lgkmcnt(0)
	s_setprio 1
	s_waitcnt lgkmcnt(0)
	s_barrier
	v_mfma_f32_16x16x32_bf16 v[62:65], v[136:139], v[178:181], v[62:65]
	v_mfma_f32_16x16x32_bf16 v[58:61], v[154:157], v[178:181], v[58:61]
	v_mfma_f32_16x16x32_bf16 v[46:49], v[136:139], v[186:189], v[46:49]
	v_mfma_f32_16x16x32_bf16 v[42:45], v[154:157], v[186:189], v[42:45]
	v_mfma_f32_16x16x32_bf16 v[30:33], v[136:139], v[194:197], v[30:33]
	v_mfma_f32_16x16x32_bf16 v[26:29], v[154:157], v[194:197], v[26:29]
	v_mfma_f32_16x16x32_bf16 v[14:17], v[136:139], v[202:205], v[14:17]
	v_mfma_f32_16x16x32_bf16 v[10:13], v[154:157], v[202:205], v[10:13]
	v_mfma_f32_16x16x32_bf16 v[54:57], v[162:165], v[178:181], v[54:57]
	v_mfma_f32_16x16x32_bf16 v[50:53], v[170:173], v[178:181], v[50:53]
	v_mfma_f32_16x16x32_bf16 v[38:41], v[162:165], v[186:189], v[38:41]
	v_mfma_f32_16x16x32_bf16 v[34:37], v[170:173], v[186:189], v[34:37]
	v_mfma_f32_16x16x32_bf16 v[22:25], v[162:165], v[194:197], v[22:25]
	v_mfma_f32_16x16x32_bf16 v[18:21], v[170:173], v[194:197], v[18:21]
	v_mfma_f32_16x16x32_bf16 v[6:9], v[162:165], v[202:205], v[6:9]
	v_mfma_f32_16x16x32_bf16 v[2:5], v[170:173], v[202:205], v[2:5]
	v_mfma_f32_16x16x32_bf16 v[62:65], v[140:143], v[182:185], v[62:65]
	v_mfma_f32_16x16x32_bf16 v[58:61], v[158:161], v[182:185], v[58:61]
	v_mfma_f32_16x16x32_bf16 v[46:49], v[140:143], v[190:193], v[46:49]
	v_mfma_f32_16x16x32_bf16 v[42:45], v[158:161], v[190:193], v[42:45]
	v_mfma_f32_16x16x32_bf16 v[30:33], v[140:143], v[198:201], v[30:33]
	v_mfma_f32_16x16x32_bf16 v[26:29], v[158:161], v[198:201], v[26:29]
	v_mfma_f32_16x16x32_bf16 v[14:17], v[140:143], v[206:209], v[14:17]
	v_mfma_f32_16x16x32_bf16 v[10:13], v[158:161], v[206:209], v[10:13]
	v_mfma_f32_16x16x32_bf16 v[54:57], v[166:169], v[182:185], v[54:57]
	v_mfma_f32_16x16x32_bf16 v[50:53], v[174:177], v[182:185], v[50:53]
	v_mfma_f32_16x16x32_bf16 v[38:41], v[166:169], v[190:193], v[38:41]
	v_mfma_f32_16x16x32_bf16 v[34:37], v[174:177], v[190:193], v[34:37]
	v_mfma_f32_16x16x32_bf16 v[22:25], v[166:169], v[198:201], v[22:25]
	v_mfma_f32_16x16x32_bf16 v[18:21], v[174:177], v[198:201], v[18:21]
	v_mfma_f32_16x16x32_bf16 v[6:9], v[166:169], v[206:209], v[6:9]
	v_mfma_f32_16x16x32_bf16 v[2:5], v[174:177], v[206:209], v[2:5]
	s_setprio 0
	s_barrier
	s_add_i32 s43, s43, 2
	s_add_u32 s37, s37, 0x100
	s_addc_u32 s42, s42, 0
	s_cmp_gt_u32 s43, 61
	s_mov_b64 s[8:9], s[14:15]
	s_cbranch_scc0 .LBB0_313
	s_and_b64 vcc, exec, s[58:59]
	s_cbranch_vccz .LBB0_333
	s_barrier
	s_cmp_lt_i32 s12, 24
	s_cbranch_scc0 .LBB0_334

.LBB0_746:
	ds_read_b128 v[118:121], v172
	ds_read_b128 v[134:137], v172 offset:1024
	ds_read_b128 v[138:141], v172 offset:2048
	ds_read_b128 v[142:145], v172 offset:3072
	ds_read_b128 v[146:149], v173
	ds_read_b128 v[150:153], v173 offset:1024
	ds_read_b128 v[154:157], v173 offset:2048
	ds_read_b128 v[176:179], v173 offset:3072
	s_add_u32 s16, s0, 0x100
	s_addc_u32 s17, s1, 0
	s_cmp_eq_u32 s33, 28
	s_cselect_b32 s26, s30, s16
	s_cselect_b32 s27, s31, s17
	s_cselect_b32 s24, s78, s5
	s_cselect_b32 s25, s79, s21
	s_add_u32 s2, s26, 0x80
	s_addc_u32 s3, s27, 0
	s_add_u32 s0, s0, 0x100080
	s_addc_u32 s1, s1, 0
	s_add_i32 s76, s46, 0xc000
	s_mov_b32 m0, s76
	s_add_i32 s77, s46, 0xe000
	ds_read_b128 v[180:183], v174
	ds_read_b128 v[184:187], v174 offset:1024
	ds_read_b128 v[188:191], v174 offset:2048
	ds_read_b128 v[192:195], v174 offset:3072
	ds_read_b128 v[196:199], v174 offset:4096
	ds_read_b128 v[200:203], v174 offset:5120
	ds_read_b128 v[204:207], v174 offset:6144
	global_load_lds_dwordx4 v1, s[0:1]
	s_mov_b32 m0, s77
	ds_read_b128 v[208:211], v174 offset:7168
	global_load_lds_dwordx4 v165, s[0:1]
	s_waitcnt vmcnt(8)
	s_waitcnt lgkmcnt(0)
	s_setprio 1
	s_waitcnt lgkmcnt(0)
	s_barrier
	v_mfma_f32_16x16x32_bf16 v[34:37], v[118:121], v[180:183], v[34:37]
	v_mfma_f32_16x16x32_bf16 v[30:33], v[138:141], v[180:183], v[30:33]
	v_mfma_f32_16x16x32_bf16 v[46:49], v[118:121], v[188:191], v[46:49]
	v_mfma_f32_16x16x32_bf16 v[62:65], v[138:141], v[188:191], v[62:65]
	v_mfma_f32_16x16x32_bf16 v[78:81], v[118:121], v[196:199], v[78:81]
	v_mfma_f32_16x16x32_bf16 v[90:93], v[138:141], v[196:199], v[90:93]
	v_mfma_f32_16x16x32_bf16 v[130:133], v[118:121], v[204:207], v[130:133]
	v_mfma_f32_16x16x32_bf16 v[114:117], v[138:141], v[204:207], v[114:117]
	v_mfma_f32_16x16x32_bf16 v[26:29], v[146:149], v[180:183], v[26:29]
	v_mfma_f32_16x16x32_bf16 v[50:53], v[154:157], v[180:183], v[50:53]
	v_mfma_f32_16x16x32_bf16 v[58:61], v[146:149], v[188:191], v[58:61]
	v_mfma_f32_16x16x32_bf16 v[82:85], v[154:157], v[188:191], v[82:85]
	v_mfma_f32_16x16x32_bf16 v[110:113], v[146:149], v[196:199], v[110:113]
	v_mfma_f32_16x16x32_bf16 v[106:109], v[154:157], v[196:199], v[106:109]
	v_mfma_f32_16x16x32_bf16 v[122:125], v[146:149], v[204:207], v[122:125]
	v_mfma_f32_16x16x32_bf16 v[126:129], v[154:157], v[204:207], v[126:129]
	v_mfma_f32_16x16x32_bf16 v[34:37], v[134:137], v[184:187], v[34:37]
	v_mfma_f32_16x16x32_bf16 v[30:33], v[142:145], v[184:187], v[30:33]
	v_mfma_f32_16x16x32_bf16 v[46:49], v[134:137], v[192:195], v[46:49]
	v_mfma_f32_16x16x32_bf16 v[62:65], v[142:145], v[192:195], v[62:65]
	v_mfma_f32_16x16x32_bf16 v[78:81], v[134:137], v[200:203], v[78:81]
	v_mfma_f32_16x16x32_bf16 v[90:93], v[142:145], v[200:203], v[90:93]
	v_mfma_f32_16x16x32_bf16 v[130:133], v[134:137], v[208:211], v[130:133]
	v_mfma_f32_16x16x32_bf16 v[114:117], v[142:145], v[208:211], v[114:117]
	v_mfma_f32_16x16x32_bf16 v[26:29], v[150:153], v[184:187], v[26:29]
	v_mfma_f32_16x16x32_bf16 v[50:53], v[176:179], v[184:187], v[50:53]
	v_mfma_f32_16x16x32_bf16 v[58:61], v[150:153], v[192:195], v[58:61]
	v_mfma_f32_16x16x32_bf16 v[82:85], v[176:179], v[192:195], v[82:85]
	v_mfma_f32_16x16x32_bf16 v[110:113], v[150:153], v[200:203], v[110:113]
	v_mfma_f32_16x16x32_bf16 v[106:109], v[176:179], v[200:203], v[106:109]
	v_mfma_f32_16x16x32_bf16 v[122:125], v[150:153], v[208:211], v[122:125]
	v_mfma_f32_16x16x32_bf16 v[126:129], v[176:179], v[208:211], v[126:129]
	s_setprio 0
	s_barrier
	s_add_i32 s80, s72, s45
	s_mov_b64 s[0:1], s[24:25]
	s_mov_b32 m0, s80
	s_add_i32 s81, s80, 0x2000
	ds_read_b128 v[180:183], v174 offset:16384
	ds_read_b128 v[184:187], v174 offset:17408
	ds_read_b128 v[188:191], v174 offset:18432
	global_load_lds_dwordx4 v164, s[0:1]
	s_mov_b32 m0, s81
	ds_read_b128 v[192:195], v174 offset:19456
	global_load_lds_dwordx4 v166, s[0:1]
	s_add_u32 s0, s24, 0x100000
	s_addc_u32 s1, s25, 0
	s_add_i32 s82, s73, s45
	s_mov_b32 m0, s82
	s_add_i32 s83, s82, 0x2000
	ds_read_b128 v[196:199], v174 offset:20480
	global_load_lds_dwordx4 v164, s[0:1]
	s_mov_b32 m0, s83
	ds_read_b128 v[200:203], v174 offset:21504
	global_load_lds_dwordx4 v166, s[0:1]
	s_mov_b64 s[0:1], s[26:27]
	s_mov_b32 m0, s46
	ds_read_b128 v[204:207], v174 offset:22528
	global_load_lds_dwordx4 v1, s[0:1]
	s_mov_b32 m0, s47
	ds_read_b128 v[208:211], v174 offset:23552
	global_load_lds_dwordx4 v165, s[0:1]
	s_waitcnt vmcnt(8)
	s_waitcnt lgkmcnt(0)
	s_setprio 1
	s_waitcnt lgkmcnt(0)
	s_barrier
	v_mfma_f32_16x16x32_bf16 v[102:105], v[118:121], v[180:183], v[102:105]
	v_mfma_f32_16x16x32_bf16 v[98:101], v[138:141], v[180:183], v[98:101]
	v_mfma_f32_16x16x32_bf16 v[74:77], v[118:121], v[188:191], v[74:77]
	v_mfma_f32_16x16x32_bf16 v[70:73], v[138:141], v[188:191], v[70:73]
	v_mfma_f32_16x16x32_bf16 v[42:45], v[118:121], v[196:199], v[42:45]
	v_mfma_f32_16x16x32_bf16 v[38:41], v[138:141], v[196:199], v[38:41]
	v_mfma_f32_16x16x32_bf16 v[18:21], v[118:121], v[204:207], v[18:21]
	v_mfma_f32_16x16x32_bf16 v[10:13], v[138:141], v[204:207], v[10:13]
	v_mfma_f32_16x16x32_bf16 v[94:97], v[146:149], v[180:183], v[94:97]
	v_mfma_f32_16x16x32_bf16 v[86:89], v[154:157], v[180:183], v[86:89]
	v_mfma_f32_16x16x32_bf16 v[66:69], v[146:149], v[188:191], v[66:69]
	v_mfma_f32_16x16x32_bf16 v[54:57], v[154:157], v[188:191], v[54:57]
	v_mfma_f32_16x16x32_bf16 v[22:25], v[146:149], v[196:199], v[22:25]
	v_mfma_f32_16x16x32_bf16 v[14:17], v[154:157], v[196:199], v[14:17]
	v_mfma_f32_16x16x32_bf16 v[6:9], v[146:149], v[204:207], v[6:9]
	v_mfma_f32_16x16x32_bf16 v[2:5], v[154:157], v[204:207], v[2:5]
	v_mfma_f32_16x16x32_bf16 v[102:105], v[134:137], v[184:187], v[102:105]
	v_mfma_f32_16x16x32_bf16 v[98:101], v[142:145], v[184:187], v[98:101]
	v_mfma_f32_16x16x32_bf16 v[74:77], v[134:137], v[192:195], v[74:77]
	v_mfma_f32_16x16x32_bf16 v[70:73], v[142:145], v[192:195], v[70:73]
	v_mfma_f32_16x16x32_bf16 v[42:45], v[134:137], v[200:203], v[42:45]
	v_mfma_f32_16x16x32_bf16 v[38:41], v[142:145], v[200:203], v[38:41]
	v_mfma_f32_16x16x32_bf16 v[18:21], v[134:137], v[208:211], v[18:21]
	v_mfma_f32_16x16x32_bf16 v[10:13], v[142:145], v[208:211], v[10:13]
	v_mfma_f32_16x16x32_bf16 v[94:97], v[150:153], v[184:187], v[94:97]
	v_mfma_f32_16x16x32_bf16 v[86:89], v[176:179], v[184:187], v[86:89]
	v_mfma_f32_16x16x32_bf16 v[66:69], v[150:153], v[192:195], v[66:69]
	v_mfma_f32_16x16x32_bf16 v[54:57], v[176:179], v[192:195], v[54:57]
	v_mfma_f32_16x16x32_bf16 v[22:25], v[150:153], v[200:203], v[22:25]
	v_mfma_f32_16x16x32_bf16 v[14:17], v[176:179], v[200:203], v[14:17]
	v_mfma_f32_16x16x32_bf16 v[6:9], v[150:153], v[208:211], v[6:9]
	v_mfma_f32_16x16x32_bf16 v[2:5], v[176:179], v[208:211], v[2:5]
	s_setprio 0
	s_barrier
	s_add_i32 s84, 0, 0x18000
	s_add_i32 s86, 0, 0x1c000
	v_add_u32_e32 v175, s84, v170
	v_add_u32_e32 v176, s86, v170
	ds_read_b128 v[118:121], v175
	ds_read_b128 v[134:137], v175 offset:1024
	ds_read_b128 v[138:141], v175 offset:2048
	ds_read_b128 v[142:145], v175 offset:3072
	ds_read_b128 v[146:149], v176
	ds_read_b128 v[150:153], v176 offset:1024
	ds_read_b128 v[154:157], v176 offset:2048
	ds_read_b128 v[178:181], v176 offset:3072
	s_add_u32 s0, s26, 0x100000
	s_addc_u32 s1, s27, 0
	s_mov_b32 m0, s48
	ds_read_b128 v[182:185], v174 offset:32768
	ds_read_b128 v[186:189], v174 offset:33792
	ds_read_b128 v[190:193], v174 offset:34816
	ds_read_b128 v[194:197], v174 offset:35840
	ds_read_b128 v[198:201], v174 offset:36864
	ds_read_b128 v[202:205], v174 offset:37888
	ds_read_b128 v[206:209], v174 offset:38912
	global_load_lds_dwordx4 v1, s[0:1]
	s_mov_b32 m0, s49
	ds_read_b128 v[210:213], v174 offset:39936
	global_load_lds_dwordx4 v165, s[0:1]
	s_waitcnt vmcnt(8)
	s_waitcnt lgkmcnt(0)
	s_setprio 1
	s_waitcnt lgkmcnt(0)
	s_barrier
	v_mfma_f32_16x16x32_bf16 v[34:37], v[118:121], v[182:185], v[34:37]
	v_mfma_f32_16x16x32_bf16 v[30:33], v[138:141], v[182:185], v[30:33]
	v_mfma_f32_16x16x32_bf16 v[46:49], v[118:121], v[190:193], v[46:49]
	v_mfma_f32_16x16x32_bf16 v[62:65], v[138:141], v[190:193], v[62:65]
	v_mfma_f32_16x16x32_bf16 v[78:81], v[118:121], v[198:201], v[78:81]
	v_mfma_f32_16x16x32_bf16 v[90:93], v[138:141], v[198:201], v[90:93]
	v_mfma_f32_16x16x32_bf16 v[130:133], v[118:121], v[206:209], v[130:133]
	v_mfma_f32_16x16x32_bf16 v[114:117], v[138:141], v[206:209], v[114:117]
	v_mfma_f32_16x16x32_bf16 v[26:29], v[146:149], v[182:185], v[26:29]
	v_mfma_f32_16x16x32_bf16 v[50:53], v[154:157], v[182:185], v[50:53]
	v_mfma_f32_16x16x32_bf16 v[58:61], v[146:149], v[190:193], v[58:61]
	v_mfma_f32_16x16x32_bf16 v[82:85], v[154:157], v[190:193], v[82:85]
	v_mfma_f32_16x16x32_bf16 v[110:113], v[146:149], v[198:201], v[110:113]
	v_mfma_f32_16x16x32_bf16 v[106:109], v[154:157], v[198:201], v[106:109]
	v_mfma_f32_16x16x32_bf16 v[122:125], v[146:149], v[206:209], v[122:125]
	v_mfma_f32_16x16x32_bf16 v[126:129], v[154:157], v[206:209], v[126:129]
	v_mfma_f32_16x16x32_bf16 v[34:37], v[134:137], v[186:189], v[34:37]
	v_mfma_f32_16x16x32_bf16 v[30:33], v[142:145], v[186:189], v[30:33]
	v_mfma_f32_16x16x32_bf16 v[46:49], v[134:137], v[194:197], v[46:49]
	v_mfma_f32_16x16x32_bf16 v[62:65], v[142:145], v[194:197], v[62:65]
	v_mfma_f32_16x16x32_bf16 v[78:81], v[134:137], v[202:205], v[78:81]
	v_mfma_f32_16x16x32_bf16 v[90:93], v[142:145], v[202:205], v[90:93]
	v_mfma_f32_16x16x32_bf16 v[130:133], v[134:137], v[210:213], v[130:133]
	v_mfma_f32_16x16x32_bf16 v[114:117], v[142:145], v[210:213], v[114:117]
	v_mfma_f32_16x16x32_bf16 v[26:29], v[150:153], v[186:189], v[26:29]
	v_mfma_f32_16x16x32_bf16 v[50:53], v[178:181], v[186:189], v[50:53]
	v_mfma_f32_16x16x32_bf16 v[58:61], v[150:153], v[194:197], v[58:61]
	v_mfma_f32_16x16x32_bf16 v[82:85], v[178:181], v[194:197], v[82:85]
	v_mfma_f32_16x16x32_bf16 v[110:113], v[150:153], v[202:205], v[110:113]
	v_mfma_f32_16x16x32_bf16 v[106:109], v[178:181], v[202:205], v[106:109]
	v_mfma_f32_16x16x32_bf16 v[122:125], v[150:153], v[210:213], v[122:125]
	v_mfma_f32_16x16x32_bf16 v[126:129], v[178:181], v[210:213], v[126:129]
	s_setprio 0
	s_barrier
	s_add_u32 s0, s24, 0x80
	s_addc_u32 s1, s25, 0
	s_add_i32 s84, s84, s45
	s_mov_b32 m0, s84
	s_add_i32 s85, s84, 0x2000
	ds_read_b128 v[182:185], v174 offset:49152
	ds_read_b128 v[186:189], v174 offset:50176
	ds_read_b128 v[190:193], v174 offset:51200
	global_load_lds_dwordx4 v164, s[0:1]
	s_mov_b32 m0, s85
	ds_read_b128 v[194:197], v174 offset:52224
	global_load_lds_dwordx4 v166, s[0:1]
	s_add_u32 s0, s24, 0x100080
	s_addc_u32 s1, s25, 0
	s_add_i32 s86, s86, s45
	s_mov_b32 m0, s86
	s_add_i32 s87, s86, 0x2000
	ds_read_b128 v[198:201], v174 offset:53248
	global_load_lds_dwordx4 v164, s[0:1]
	s_mov_b32 m0, s87
	ds_read_b128 v[202:205], v174 offset:54272
	global_load_lds_dwordx4 v166, s[0:1]
	s_mov_b32 m0, s57
	ds_read_b128 v[206:209], v174 offset:55296
	global_load_lds_dwordx4 v1, s[2:3]
	s_mov_b32 m0, s62
	ds_read_b128 v[210:213], v174 offset:56320
	global_load_lds_dwordx4 v165, s[2:3]
	s_waitcnt vmcnt(8)
	s_waitcnt lgkmcnt(0)
	s_setprio 1
	s_waitcnt lgkmcnt(0)
	s_barrier
	v_mfma_f32_16x16x32_bf16 v[102:105], v[118:121], v[182:185], v[102:105]
	v_mfma_f32_16x16x32_bf16 v[98:101], v[138:141], v[182:185], v[98:101]
	v_mfma_f32_16x16x32_bf16 v[74:77], v[118:121], v[190:193], v[74:77]
	v_mfma_f32_16x16x32_bf16 v[70:73], v[138:141], v[190:193], v[70:73]
	v_mfma_f32_16x16x32_bf16 v[42:45], v[118:121], v[198:201], v[42:45]
	v_mfma_f32_16x16x32_bf16 v[38:41], v[138:141], v[198:201], v[38:41]
	v_mfma_f32_16x16x32_bf16 v[18:21], v[118:121], v[206:209], v[18:21]
	v_mfma_f32_16x16x32_bf16 v[10:13], v[138:141], v[206:209], v[10:13]
	v_mfma_f32_16x16x32_bf16 v[94:97], v[146:149], v[182:185], v[94:97]
	v_mfma_f32_16x16x32_bf16 v[86:89], v[154:157], v[182:185], v[86:89]
	v_mfma_f32_16x16x32_bf16 v[66:69], v[146:149], v[190:193], v[66:69]
	v_mfma_f32_16x16x32_bf16 v[54:57], v[154:157], v[190:193], v[54:57]
	v_mfma_f32_16x16x32_bf16 v[22:25], v[146:149], v[198:201], v[22:25]
	v_mfma_f32_16x16x32_bf16 v[14:17], v[154:157], v[198:201], v[14:17]
	v_mfma_f32_16x16x32_bf16 v[6:9], v[146:149], v[206:209], v[6:9]
	v_mfma_f32_16x16x32_bf16 v[2:5], v[154:157], v[206:209], v[2:5]
	v_mfma_f32_16x16x32_bf16 v[102:105], v[134:137], v[186:189], v[102:105]
	v_mfma_f32_16x16x32_bf16 v[98:101], v[142:145], v[186:189], v[98:101]
	v_mfma_f32_16x16x32_bf16 v[74:77], v[134:137], v[194:197], v[74:77]
	v_mfma_f32_16x16x32_bf16 v[70:73], v[142:145], v[194:197], v[70:73]
	v_mfma_f32_16x16x32_bf16 v[42:45], v[134:137], v[202:205], v[42:45]
	v_mfma_f32_16x16x32_bf16 v[38:41], v[142:145], v[202:205], v[38:41]
	v_mfma_f32_16x16x32_bf16 v[18:21], v[134:137], v[210:213], v[18:21]
	v_mfma_f32_16x16x32_bf16 v[10:13], v[142:145], v[210:213], v[10:13]
	v_mfma_f32_16x16x32_bf16 v[94:97], v[150:153], v[186:189], v[94:97]
	v_mfma_f32_16x16x32_bf16 v[86:89], v[178:181], v[186:189], v[86:89]
	v_mfma_f32_16x16x32_bf16 v[66:69], v[150:153], v[194:197], v[66:69]
	v_mfma_f32_16x16x32_bf16 v[54:57], v[178:181], v[194:197], v[54:57]
	v_mfma_f32_16x16x32_bf16 v[22:25], v[150:153], v[202:205], v[22:25]
	v_mfma_f32_16x16x32_bf16 v[14:17], v[178:181], v[202:205], v[14:17]
	v_mfma_f32_16x16x32_bf16 v[6:9], v[150:153], v[210:213], v[6:9]
	v_mfma_f32_16x16x32_bf16 v[2:5], v[178:181], v[210:213], v[2:5]
	s_setprio 0
	s_barrier
; __device__ __forceinline__ float bf_lo(unsigned w) { return __uint_as_float(w << 16); }
; __device__ __forceinline__ float bf_hi(unsigned w) { return __uint_as_float(w & 0xffff0000u); }
;     __device__ __forceinline__ void mid(f32x4 (&acc)[2][2][4][2], const Unit& u, int wr, int wc, int fr, int fq) const {
;         asm volatile("" : "+v"(fr), "+v"(fq));
;         const int row0 = u.pm * BM + wr * 64 + fr, col0 = u.pn * BM + wc * 32 + 8 * fq;
; #pragma unroll
;         for (int ai = 0; ai < 2; ++ai)
; #pragma unroll
;             for (int m = 0; m < 4; ++m) { const size_t off = (size_t)(row0 + ai * HALF + m * 16) * 4096 + col0;
; #pragma unroll
;                 for (int bj = 0; bj < 2; ++bj) { const u32x4 ga = *(const u32x4*)(SGA + off + bj * HALF), gb = *(const u32x4*)(SGB + off + bj * HALF);
;                     const unsigned wa[4] = {ga.x, ga.y, ga.z, ga.w}, wb[4] = {gb.x, gb.y, gb.z, gb.w};
; #pragma unroll
;                     for (int p = 0; p < 4; ++p) { const float rl = bf_lo(wa[p]) * __builtin_amdgcn_rcpf(fmaxf(bf_lo(wb[p]), 1e-20f)), rh = bf_hi(wa[p]) * __builtin_amdgcn_rcpf(fmaxf(bf_hi(wb[p]), 1e-20f));
;                         acc[ai][bj][m][p >> 1][(p & 1) * 2] *= rl; acc[ai][bj][m][p >> 1][(p & 1) * 2 + 1] *= rh; } }
	s_add_i32 s33, s33, 2
	s_add_u32 s5, s5, 0x100
	s_addc_u32 s21, s21, 0
	s_cmp_gt_u32 s33, 29
	s_mov_b64 s[0:1], s[16:17]
	s_cbranch_scc0 .LBB0_746
	v_mov_b32_e32 v119, v167
	v_mov_b32_e32 v118, v168
	s_lshl_b32 s89, s20, 8
	s_lshl_b32 s88, s4, 8
	s_or_b32 s0, s89, s56
	v_lshl_add_u32 v118, v118, 3, s0
	s_add_i32 s0, s88, s55
	v_add_u32_e32 v120, s0, v119
	v_ashrrev_i32_e32 v121, 31, v120
	v_ashrrev_i32_e32 v119, 31, v118
	v_lshlrev_b64 v[120:121], 12, v[120:121]
	v_lshl_add_u64 v[118:119], v[120:121], 0, v[118:119]
	v_lshlrev_b64 v[162:163], 1, v[118:119]
	v_lshl_add_u64 v[138:139], s[12:13], 0, v[162:163]
	global_load_dwordx4 v[134:137], v[138:139], off
	v_lshl_add_u64 v[140:141], s[10:11], 0, v[162:163]
	global_load_dwordx4 v[118:121], v[140:141], off
	global_load_dwordx4 v[150:153], v[138:139], off offset:256
	global_load_dwordx4 v[146:149], v[140:141], off offset:256
	s_mov_b64 s[0:1], 0x20000
	v_lshl_add_u64 v[138:139], v[162:163], 0, s[0:1]
	v_lshl_add_u64 v[154:155], s[10:11], 0, v[138:139]
	v_lshl_add_u64 v[156:157], s[12:13], 0, v[138:139]
	global_load_dwordx4 v[138:141], v[154:155], off
	global_load_dwordx4 v[142:145], v[156:157], off
	s_mov_b64 s[0:1], 0x40000
	s_add_i32 s50, s50, 1
	v_readlane_b32 s2, v238, 45
	s_waitcnt vmcnt(0)
	v_lshlrev_b32_e32 v178, 16, v118
	v_and_b32_e32 v180, 0xffff0000, v134
	v_lshlrev_b32_e32 v181, 16, v135
	v_and_b32_e32 v182, 0xffff0000, v135
	v_lshlrev_b32_e32 v183, 16, v136
	v_and_b32_e32 v184, 0xffff0000, v136
	v_lshlrev_b32_e32 v185, 16, v137
	v_and_b32_e32 v186, 0xffff0000, v137
	v_lshlrev_b32_e32 v187, 16, v150
	v_and_b32_e32 v150, 0xffff0000, v150
	v_lshlrev_b32_e32 v188, 16, v151
	v_and_b32_e32 v151, 0xffff0000, v151
	v_max_f32_e32 v180, v180, v180
	v_max_f32_e32 v181, v181, v181
	v_max_f32_e32 v182, v182, v182
	v_max_f32_e32 v183, v183, v183
	v_max_f32_e32 v184, v184, v184
	v_max_f32_e32 v185, v185, v185
	v_max_f32_e32 v186, v186, v186
	v_max_f32_e32 v187, v187, v187
	v_max_f32_e32 v150, v150, v150
	v_max_f32_e32 v188, v188, v188
	v_max_f32_e32 v151, v151, v151
	v_max_f32_e32 v180, 0x1e3ce508, v180
	v_max_f32_e32 v181, 0x1e3ce508, v181
	v_max_f32_e32 v182, 0x1e3ce508, v182
	v_max_f32_e32 v183, 0x1e3ce508, v183
	v_max_f32_e32 v184, 0x1e3ce508, v184
	v_max_f32_e32 v185, 0x1e3ce508, v185
	v_max_f32_e32 v186, 0x1e3ce508, v186
	v_max_f32_e32 v187, 0x1e3ce508, v187
	v_max_f32_e32 v189, 0x1e3ce508, v150
	v_max_f32_e32 v188, 0x1e3ce508, v188
	v_max_f32_e32 v190, 0x1e3ce508, v151
	v_rcp_f32_e32 v151, v180
	v_rcp_f32_e32 v180, v181
	v_rcp_f32_e32 v181, v182
	v_rcp_f32_e32 v182, v183
	v_rcp_f32_e32 v183, v184
	v_rcp_f32_e32 v184, v185
	v_rcp_f32_e32 v185, v186
	v_rcp_f32_e32 v186, v187
	v_rcp_f32_e32 v187, v189
	v_rcp_f32_e32 v188, v188
	v_rcp_f32_e32 v189, v190
	v_and_b32_e32 v179, 0xffff0000, v118
	v_lshlrev_b32_e32 v118, 16, v119
	v_and_b32_e32 v119, 0xffff0000, v119
	v_lshlrev_b32_e32 v177, 16, v134
	v_lshlrev_b32_e32 v134, 16, v120
	v_and_b32_e32 v135, 0xffff0000, v120
	v_lshlrev_b32_e32 v120, 16, v121
	v_and_b32_e32 v121, 0xffff0000, v121
	v_lshlrev_b32_e32 v136, 16, v146
	v_and_b32_e32 v137, 0xffff0000, v146
	v_lshlrev_b32_e32 v146, 16, v147
	v_and_b32_e32 v147, 0xffff0000, v147
	v_pk_mul_f32 v[118:119], v[180:181], v[118:119]
	v_pk_mul_f32 v[134:135], v[182:183], v[134:135]
	v_pk_mul_f32 v[120:121], v[184:185], v[120:121]
	v_pk_mul_f32 v[36:37], v[36:37], v[118:119]
	v_pk_mul_f32 v[118:119], v[188:189], v[146:147]
	v_pk_mul_f32 v[30:31], v[30:31], v[134:135]
	v_pk_mul_f32 v[32:33], v[32:33], v[120:121]
	v_pk_mul_f32 v[28:29], v[28:29], v[118:119]
	global_load_dwordx4 v[118:121], v[156:157], off offset:256
	v_lshlrev_b32_e32 v134, 16, v152
	v_max_f32_e32 v134, v134, v134
	v_max_f32_e32 v134, 0x1e3ce508, v134
	v_rcp_f32_e32 v146, v134
	v_and_b32_e32 v134, 0xffff0000, v152
	v_max_f32_e32 v134, v134, v134
	v_pk_mul_f32 v[136:137], v[186:187], v[136:137]
	v_max_f32_e32 v134, 0x1e3ce508, v134
	v_pk_mul_f32 v[26:27], v[26:27], v[136:137]
	v_rcp_f32_e32 v147, v134
	global_load_dwordx4 v[134:137], v[154:155], off offset:256
	v_max_f32_e32 v177, v177, v177
	v_max_f32_e32 v177, 0x1e3ce508, v177
	v_rcp_f32_e32 v150, v177
	s_nop 0
	v_pk_mul_f32 v[150:151], v[150:151], v[178:179]
	s_nop 0
	v_pk_mul_f32 v[34:35], v[34:35], v[150:151]
	v_lshlrev_b32_e32 v150, 16, v148
	v_and_b32_e32 v151, 0xffff0000, v148
	v_lshlrev_b32_e32 v148, 16, v153
	v_max_f32_e32 v148, v148, v148
	v_max_f32_e32 v148, 0x1e3ce508, v148
	v_pk_mul_f32 v[146:147], v[146:147], v[150:151]
	v_rcp_f32_e32 v150, v148
	v_and_b32_e32 v148, 0xffff0000, v153
	v_max_f32_e32 v148, v148, v148
	v_max_f32_e32 v148, 0x1e3ce508, v148
	v_rcp_f32_e32 v151, v148
	v_pk_mul_f32 v[50:51], v[50:51], v[146:147]
	v_lshlrev_b32_e32 v146, 16, v149
	v_and_b32_e32 v147, 0xffff0000, v149
	v_pk_mul_f32 v[146:147], v[150:151], v[146:147]
	v_lshlrev_b32_e32 v148, 16, v142
	v_and_b32_e32 v142, 0xffff0000, v142
	v_pk_mul_f32 v[52:53], v[52:53], v[146:147]
	v_lshlrev_b32_e32 v146, 16, v138
	v_and_b32_e32 v147, 0xffff0000, v138
	v_lshlrev_b32_e32 v138, 16, v143
	v_max_f32_e32 v148, v148, v148
	v_max_f32_e32 v142, v142, v142
	v_max_f32_e32 v138, v138, v138
	v_max_f32_e32 v148, 0x1e3ce508, v148
	v_max_f32_e32 v142, 0x1e3ce508, v142
	v_max_f32_e32 v138, 0x1e3ce508, v138
	v_rcp_f32_e32 v148, v148
	v_rcp_f32_e32 v149, v142
	v_rcp_f32_e32 v142, v138
	v_and_b32_e32 v138, 0xffff0000, v143
	v_max_f32_e32 v138, v138, v138
	v_max_f32_e32 v138, 0x1e3ce508, v138
	v_rcp_f32_e32 v143, v138
	v_lshl_add_u64 v[150:151], v[162:163], 0, s[0:1]
	v_pk_mul_f32 v[146:147], v[148:149], v[146:147]
	v_lshl_add_u64 v[154:155], s[12:13], 0, v[150:151]
	v_pk_mul_f32 v[46:47], v[46:47], v[146:147]
	global_load_dwordx4 v[146:149], v[154:155], off
	v_lshlrev_b32_e32 v138, 16, v139
	v_and_b32_e32 v139, 0xffff0000, v139
	v_pk_mul_f32 v[138:139], v[142:143], v[138:139]
	v_lshlrev_b32_e32 v142, 16, v144
	v_max_f32_e32 v142, v142, v142
	v_max_f32_e32 v142, 0x1e3ce508, v142
	v_rcp_f32_e32 v156, v142
	v_lshl_add_u64 v[142:143], s[10:11], 0, v[150:151]
	global_load_dwordx4 v[150:153], v[142:143], off
	v_and_b32_e32 v144, 0xffff0000, v144
	v_pk_mul_f32 v[48:49], v[48:49], v[138:139]
	v_lshlrev_b32_e32 v138, 16, v140
	v_and_b32_e32 v139, 0xffff0000, v140
	v_lshlrev_b32_e32 v140, 16, v145
	v_max_f32_e32 v144, v144, v144
	v_max_f32_e32 v140, v140, v140
	v_max_f32_e32 v144, 0x1e3ce508, v144
	v_max_f32_e32 v140, 0x1e3ce508, v140
	v_rcp_f32_e32 v157, v144
	v_rcp_f32_e32 v144, v140
	v_and_b32_e32 v140, 0xffff0000, v145
	v_max_f32_e32 v140, v140, v140
	v_max_f32_e32 v140, 0x1e3ce508, v140
	v_rcp_f32_e32 v145, v140
	s_waitcnt vmcnt(3)
; __device__ __forceinline__ float bf_lo(unsigned w) { return __uint_as_float(w << 16); }
; __device__ __forceinline__ float bf_hi(unsigned w) { return __uint_as_float(w & 0xffff0000u); }
;     __device__ __forceinline__ void mid(f32x4 (&acc)[2][2][4][2], const Unit& u, int wr, int wc, int fr, int fq) const {
;     ...
;             for (int m = 0; m < 4; ++m) { const size_t off = (size_t)(row0 + ai * HALF + m * 16) * 4096 + col0;
; #pragma unroll
;                 for (int bj = 0; bj < 2; ++bj) { const u32x4 ga = *(const u32x4*)(SGA + off + bj * HALF), gb = *(const u32x4*)(SGB + off + bj * HALF);
;                     const unsigned wa[4] = {ga.x, ga.y, ga.z, ga.w}, wb[4] = {gb.x, gb.y, gb.z, gb.w};
; #pragma unroll
;                     for (int p = 0; p < 4; ++p) { const float rl = bf_lo(wa[p]) * __builtin_amdgcn_rcpf(fmaxf(bf_lo(wb[p]), 1e-20f)), rh = bf_hi(wa[p]) * __builtin_amdgcn_rcpf(fmaxf(bf_hi(wb[p]), 1e-20f));
;                         acc[ai][bj][m][p >> 1][(p & 1) * 2] *= rl; acc[ai][bj][m][p >> 1][(p & 1) * 2 + 1] *= rh; } }
;                 if (m == 3) asm volatile("" : "+v"(acc[ai][0][0][0]), "+v"(acc[ai][0][0][1]), "+v"(acc[ai][1][0][0]), "+v"(acc[ai][1][0][1]), "+v"(acc[ai][0][1][0]), "+v"(acc[ai][0][1][1]), "+v"(acc[ai][1][1][0]), "+v"(acc[ai][1][1][1]), "+v"(acc[ai][0][2][0]), "+v"(acc[ai][0][2][1]), "+v"(acc[ai][1][2][0]), "+v"(acc[ai][1][2][1]), "+v"(acc[ai][0][3][0]), "+v"(acc[ai][0][3][1]), "+v"(acc[ai][1][3][0]), "+v"(acc[ai][1][3][1]) :: "memory"); }
	v_lshlrev_b32_e32 v140, 16, v118
	v_and_b32_e32 v118, 0xffff0000, v118
	v_max_f32_e32 v140, v140, v140
	v_max_f32_e32 v118, v118, v118
	v_pk_mul_f32 v[138:139], v[156:157], v[138:139]
	v_max_f32_e32 v140, 0x1e3ce508, v140
	v_max_f32_e32 v118, 0x1e3ce508, v118
	v_pk_mul_f32 v[62:63], v[62:63], v[138:139]
	v_lshlrev_b32_e32 v138, 16, v141
	v_and_b32_e32 v139, 0xffff0000, v141
	v_rcp_f32_e32 v140, v140
	v_rcp_f32_e32 v141, v118
	v_pk_mul_f32 v[138:139], v[144:145], v[138:139]
	global_load_dwordx4 v[142:145], v[142:143], off offset:256
	v_pk_mul_f32 v[64:65], v[64:65], v[138:139]
	s_waitcnt vmcnt(3)
	v_lshlrev_b32_e32 v138, 16, v134
	v_and_b32_e32 v139, 0xffff0000, v134
	v_pk_mul_f32 v[138:139], v[140:141], v[138:139]
	v_lshlrev_b32_e32 v118, 16, v119
	v_pk_mul_f32 v[58:59], v[58:59], v[138:139]
	global_load_dwordx4 v[138:141], v[154:155], off offset:256
	v_and_b32_e32 v119, 0xffff0000, v119
	v_max_f32_e32 v118, v118, v118
	v_max_f32_e32 v119, v119, v119
	v_max_f32_e32 v118, 0x1e3ce508, v118
	v_max_f32_e32 v119, 0x1e3ce508, v119
	v_rcp_f32_e32 v118, v118
	v_rcp_f32_e32 v119, v119
	v_lshlrev_b32_e32 v134, 16, v135
	v_and_b32_e32 v135, 0xffff0000, v135
	s_mov_b64 s[0:1], 0x60000
	v_pk_mul_f32 v[118:119], v[118:119], v[134:135]
	v_lshlrev_b32_e32 v134, 16, v136
	v_pk_mul_f32 v[60:61], v[60:61], v[118:119]
	v_lshlrev_b32_e32 v118, 16, v120
	v_and_b32_e32 v119, 0xffff0000, v120
	v_max_f32_e32 v118, v118, v118
	v_max_f32_e32 v119, v119, v119
	v_max_f32_e32 v118, 0x1e3ce508, v118
	v_max_f32_e32 v119, 0x1e3ce508, v119
	v_lshlrev_b32_e32 v120, 16, v121
	v_and_b32_e32 v121, 0xffff0000, v121
	v_rcp_f32_e32 v118, v118
	v_rcp_f32_e32 v119, v119
	v_max_f32_e32 v120, v120, v120
	v_max_f32_e32 v121, v121, v121
	v_max_f32_e32 v120, 0x1e3ce508, v120
	v_max_f32_e32 v121, 0x1e3ce508, v121
	v_rcp_f32_e32 v120, v120
	v_rcp_f32_e32 v121, v121
	v_and_b32_e32 v135, 0xffff0000, v136
	v_pk_mul_f32 v[118:119], v[118:119], v[134:135]
	s_nop 0
	v_pk_mul_f32 v[82:83], v[82:83], v[118:119]
	v_lshlrev_b32_e32 v118, 16, v137
	v_and_b32_e32 v119, 0xffff0000, v137
	v_pk_mul_f32 v[118:119], v[120:121], v[118:119]
	s_waitcnt vmcnt(3)
	v_lshlrev_b32_e32 v120, 16, v146
	v_and_b32_e32 v121, 0xffff0000, v146
	v_max_f32_e32 v120, v120, v120
	v_max_f32_e32 v121, v121, v121
	v_max_f32_e32 v120, 0x1e3ce508, v120
	v_max_f32_e32 v121, 0x1e3ce508, v121
	v_rcp_f32_e32 v120, v120
	v_rcp_f32_e32 v121, v121
	v_pk_mul_f32 v[84:85], v[84:85], v[118:119]
	s_waitcnt vmcnt(2)
	v_lshlrev_b32_e32 v118, 16, v150
	v_and_b32_e32 v119, 0xffff0000, v150
	v_pk_mul_f32 v[118:119], v[120:121], v[118:119]
	v_lshlrev_b32_e32 v150, 16, v151
	v_pk_mul_f32 v[78:79], v[78:79], v[118:119]
	v_lshlrev_b32_e32 v118, 16, v147
	v_and_b32_e32 v119, 0xffff0000, v147
	v_lshl_add_u64 v[146:147], v[162:163], 0, s[0:1]
	v_lshl_add_u64 v[120:121], s[12:13], 0, v[146:147]
	v_max_f32_e32 v118, v118, v118
	v_max_f32_e32 v119, v119, v119
	global_load_dwordx4 v[134:137], v[120:121], off
	v_max_f32_e32 v118, 0x1e3ce508, v118
	v_max_f32_e32 v119, 0x1e3ce508, v119
	v_rcp_f32_e32 v118, v118
	v_rcp_f32_e32 v119, v119
	v_and_b32_e32 v151, 0xffff0000, v151
	s_mov_b64 s[0:1], 0x120000
	v_pk_mul_f32 v[150:151], v[118:119], v[150:151]
	v_lshlrev_b32_e32 v118, 16, v148
	v_max_f32_e32 v118, v118, v118
	v_max_f32_e32 v118, 0x1e3ce508, v118
	v_rcp_f32_e32 v178, v118
	v_lshl_add_u64 v[118:119], s[10:11], 0, v[146:147]
	global_load_dwordx4 v[154:157], v[118:119], off
	v_and_b32_e32 v146, 0xffff0000, v148
	v_max_f32_e32 v146, v146, v146
	v_max_f32_e32 v146, 0x1e3ce508, v146
	v_lshlrev_b32_e32 v148, 16, v149
	v_and_b32_e32 v149, 0xffff0000, v149
	v_rcp_f32_e32 v179, v146
	v_max_f32_e32 v148, v148, v148
	v_max_f32_e32 v149, v149, v149
	v_max_f32_e32 v148, 0x1e3ce508, v148
	v_max_f32_e32 v149, 0x1e3ce508, v149
	v_rcp_f32_e32 v148, v148
	v_rcp_f32_e32 v149, v149
	v_lshlrev_b32_e32 v146, 16, v152
	v_and_b32_e32 v147, 0xffff0000, v152
	v_pk_mul_f32 v[146:147], v[178:179], v[146:147]
	v_pk_mul_f32 v[80:81], v[80:81], v[150:151]
	v_pk_mul_f32 v[90:91], v[90:91], v[146:147]
	v_lshlrev_b32_e32 v146, 16, v153
	v_and_b32_e32 v147, 0xffff0000, v153
	v_pk_mul_f32 v[146:147], v[148:149], v[146:147]
	s_waitcnt vmcnt(2)
	v_lshlrev_b32_e32 v148, 16, v138
	v_and_b32_e32 v138, 0xffff0000, v138
	v_max_f32_e32 v148, v148, v148
	v_max_f32_e32 v138, v138, v138
	v_max_f32_e32 v148, 0x1e3ce508, v148
	v_max_f32_e32 v138, 0x1e3ce508, v138
	global_load_dwordx4 v[150:153], v[120:121], off offset:256
	v_rcp_f32_e32 v148, v148
	v_rcp_f32_e32 v149, v138
	v_pk_mul_f32 v[92:93], v[92:93], v[146:147]
	v_lshlrev_b32_e32 v146, 16, v142
	v_and_b32_e32 v147, 0xffff0000, v142
	v_pk_mul_f32 v[146:147], v[148:149], v[146:147]
	v_lshlrev_b32_e32 v138, 16, v139
	v_pk_mul_f32 v[110:111], v[110:111], v[146:147]
	global_load_dwordx4 v[146:149], v[118:119], off offset:256
	v_and_b32_e32 v139, 0xffff0000, v139
	v_max_f32_e32 v138, v138, v138
	v_max_f32_e32 v139, v139, v139
	v_max_f32_e32 v138, 0x1e3ce508, v138
	v_max_f32_e32 v120, 0x1e3ce508, v139
	v_rcp_f32_e32 v138, v138
	v_rcp_f32_e32 v139, v120
	v_lshlrev_b32_e32 v120, 16, v143
	v_and_b32_e32 v121, 0xffff0000, v143
	v_and_b32_e32 v119, 0xffff0000, v140
	v_pk_mul_f32 v[120:121], v[138:139], v[120:121]
	v_lshlrev_b32_e32 v138, 16, v140
	v_max_f32_e32 v138, v138, v138
	v_max_f32_e32 v119, v119, v119
	v_max_f32_e32 v118, 0x1e3ce508, v138
	v_max_f32_e32 v119, 0x1e3ce508, v119
	v_rcp_f32_e32 v118, v118
	v_rcp_f32_e32 v119, v119
	v_pk_mul_f32 v[112:113], v[112:113], v[120:121]
	v_lshlrev_b32_e32 v120, 16, v144
	v_and_b32_e32 v121, 0xffff0000, v144
	v_pk_mul_f32 v[118:119], v[118:119], v[120:121]
	v_lshlrev_b32_e32 v120, 16, v141
	v_and_b32_e32 v121, 0xffff0000, v141
	v_max_f32_e32 v120, v120, v120
	v_max_f32_e32 v121, v121, v121
	v_max_f32_e32 v120, 0x1e3ce508, v120
	v_max_f32_e32 v121, 0x1e3ce508, v121
	v_rcp_f32_e32 v120, v120
	v_rcp_f32_e32 v121, v121
	v_pk_mul_f32 v[118:119], v[106:107], v[118:119]
	v_lshlrev_b32_e32 v106, 16, v145
	v_and_b32_e32 v107, 0xffff0000, v145
	v_pk_mul_f32 v[106:107], v[120:121], v[106:107]
	s_waitcnt vmcnt(3)
; __device__ __forceinline__ float bf_lo(unsigned w) { return __uint_as_float(w << 16); }
; __device__ __forceinline__ float bf_hi(unsigned w) { return __uint_as_float(w & 0xffff0000u); }
;     __device__ __forceinline__ void mid(f32x4 (&acc)[2][2][4][2], const Unit& u, int wr, int wc, int fr, int fq) const {
;     ...
;             for (int m = 0; m < 4; ++m) { const size_t off = (size_t)(row0 + ai * HALF + m * 16) * 4096 + col0;
; #pragma unroll
;                 for (int bj = 0; bj < 2; ++bj) { const u32x4 ga = *(const u32x4*)(SGA + off + bj * HALF), gb = *(const u32x4*)(SGB + off + bj * HALF);
;                     const unsigned wa[4] = {ga.x, ga.y, ga.z, ga.w}, wb[4] = {gb.x, gb.y, gb.z, gb.w};
; #pragma unroll
;                     for (int p = 0; p < 4; ++p) { const float rl = bf_lo(wa[p]) * __builtin_amdgcn_rcpf(fmaxf(bf_lo(wb[p]), 1e-20f)), rh = bf_hi(wa[p]) * __builtin_amdgcn_rcpf(fmaxf(bf_hi(wb[p]), 1e-20f));
;                         acc[ai][bj][m][p >> 1][(p & 1) * 2] *= rl; acc[ai][bj][m][p >> 1][(p & 1) * 2 + 1] *= rh; } }
;                 if (m == 3) asm volatile("" : "+v"(acc[ai][0][0][0]), "+v"(acc[ai][0][0][1]), "+v"(acc[ai][1][0][0]), "+v"(acc[ai][1][0][1]), "+v"(acc[ai][0][1][0]), "+v"(acc[ai][0][1][1]), "+v"(acc[ai][1][1][0]), "+v"(acc[ai][1][1][1]), "+v"(acc[ai][0][2][0]), "+v"(acc[ai][0][2][1]), "+v"(acc[ai][1][2][0]), "+v"(acc[ai][1][2][1]), "+v"(acc[ai][0][3][0]), "+v"(acc[ai][0][3][1]), "+v"(acc[ai][1][3][0]), "+v"(acc[ai][1][3][1]) :: "memory"); }
	v_lshlrev_b32_e32 v120, 16, v134
	v_max_f32_e32 v120, v120, v120
	v_max_f32_e32 v120, 0x1e3ce508, v120
	v_rcp_f32_e32 v138, v120
	v_and_b32_e32 v120, 0xffff0000, v134
	v_max_f32_e32 v120, v120, v120
	v_max_f32_e32 v120, 0x1e3ce508, v120
	v_rcp_f32_e32 v139, v120
	v_pk_mul_f32 v[120:121], v[108:109], v[106:107]
	v_lshlrev_b32_e32 v108, 16, v135
	v_and_b32_e32 v109, 0xffff0000, v135
	v_max_f32_e32 v108, v108, v108
	v_max_f32_e32 v109, v109, v109
	v_max_f32_e32 v108, 0x1e3ce508, v108
	v_max_f32_e32 v109, 0x1e3ce508, v109
	v_rcp_f32_e32 v108, v108
	v_rcp_f32_e32 v109, v109
	s_waitcnt vmcnt(2)
	v_lshlrev_b32_e32 v106, 16, v154
	v_and_b32_e32 v107, 0xffff0000, v154
	v_pk_mul_f32 v[106:107], v[138:139], v[106:107]
	v_lshl_add_u64 v[140:141], v[162:163], 0, s[0:1]
	v_pk_mul_f32 v[106:107], v[130:131], v[106:107]
	v_lshlrev_b32_e32 v130, 16, v155
	v_and_b32_e32 v131, 0xffff0000, v155
	v_pk_mul_f32 v[108:109], v[108:109], v[130:131]
	v_lshlrev_b32_e32 v130, 16, v136
	v_and_b32_e32 v131, 0xffff0000, v136
	v_max_f32_e32 v130, v130, v130
	v_max_f32_e32 v131, v131, v131
	v_max_f32_e32 v130, 0x1e3ce508, v130
	v_max_f32_e32 v131, 0x1e3ce508, v131
	v_rcp_f32_e32 v130, v130
	v_rcp_f32_e32 v131, v131
	v_pk_mul_f32 v[108:109], v[132:133], v[108:109]
	v_lshlrev_b32_e32 v132, 16, v156
	v_and_b32_e32 v133, 0xffff0000, v156
	v_pk_mul_f32 v[130:131], v[130:131], v[132:133]
	v_lshlrev_b32_e32 v132, 16, v137
	v_and_b32_e32 v133, 0xffff0000, v137
	v_max_f32_e32 v132, v132, v132
	v_max_f32_e32 v133, v133, v133
	v_max_f32_e32 v132, 0x1e3ce508, v132
	v_max_f32_e32 v133, 0x1e3ce508, v133
	v_rcp_f32_e32 v132, v132
	v_rcp_f32_e32 v133, v133
	v_pk_mul_f32 v[114:115], v[114:115], v[130:131]
	v_lshlrev_b32_e32 v130, 16, v157
	v_and_b32_e32 v131, 0xffff0000, v157
	v_pk_mul_f32 v[130:131], v[132:133], v[130:131]
	s_waitcnt vmcnt(1)
	v_lshlrev_b32_e32 v132, 16, v150
	v_and_b32_e32 v133, 0xffff0000, v150
	v_max_f32_e32 v132, v132, v132
	v_max_f32_e32 v133, v133, v133
	v_max_f32_e32 v132, 0x1e3ce508, v132
	v_max_f32_e32 v133, 0x1e3ce508, v133
	v_rcp_f32_e32 v132, v132
	v_rcp_f32_e32 v133, v133
	v_pk_mul_f32 v[116:117], v[116:117], v[130:131]
	s_waitcnt vmcnt(0)
	v_lshlrev_b32_e32 v130, 16, v146
	v_and_b32_e32 v131, 0xffff0000, v146
	v_pk_mul_f32 v[130:131], v[132:133], v[130:131]
	v_lshlrev_b32_e32 v132, 16, v151
	v_and_b32_e32 v133, 0xffff0000, v151
	v_max_f32_e32 v132, v132, v132
	v_max_f32_e32 v133, v133, v133
	v_max_f32_e32 v132, 0x1e3ce508, v132
	v_max_f32_e32 v133, 0x1e3ce508, v133
	v_rcp_f32_e32 v132, v132
	v_rcp_f32_e32 v133, v133
	v_pk_mul_f32 v[122:123], v[122:123], v[130:131]
	v_lshlrev_b32_e32 v130, 16, v147
	v_and_b32_e32 v131, 0xffff0000, v147
	v_pk_mul_f32 v[130:131], v[132:133], v[130:131]
	v_lshlrev_b32_e32 v132, 16, v152
	v_and_b32_e32 v133, 0xffff0000, v152
	v_max_f32_e32 v132, v132, v132
	v_max_f32_e32 v133, v133, v133
	v_max_f32_e32 v132, 0x1e3ce508, v132
	v_max_f32_e32 v133, 0x1e3ce508, v133
	v_rcp_f32_e32 v132, v132
	v_rcp_f32_e32 v133, v133
	v_pk_mul_f32 v[124:125], v[124:125], v[130:131]
	v_lshlrev_b32_e32 v130, 16, v148
	v_and_b32_e32 v131, 0xffff0000, v148
	v_pk_mul_f32 v[130:131], v[132:133], v[130:131]
	v_lshlrev_b32_e32 v132, 16, v153
	v_and_b32_e32 v133, 0xffff0000, v153
	v_max_f32_e32 v132, v132, v132
	v_max_f32_e32 v133, v133, v133
	v_max_f32_e32 v132, 0x1e3ce508, v132
	v_max_f32_e32 v133, 0x1e3ce508, v133
	v_rcp_f32_e32 v132, v132
	v_rcp_f32_e32 v133, v133
	v_pk_mul_f32 v[126:127], v[126:127], v[130:131]
	v_lshlrev_b32_e32 v130, 16, v149
	v_and_b32_e32 v131, 0xffff0000, v149
	v_pk_mul_f32 v[130:131], v[132:133], v[130:131]
	v_lshl_add_u64 v[154:155], s[12:13], 0, v[140:141]
	v_pk_mul_f32 v[128:129], v[128:129], v[130:131]
	v_lshl_add_u64 v[130:131], v[162:163], 0, s[8:9]
	v_lshl_add_u64 v[132:133], s[12:13], 0, v[130:131]
	global_load_dwordx4 v[150:153], v[132:133], off
	v_lshl_add_u64 v[130:131], s[10:11], 0, v[130:131]
	global_load_dwordx4 v[146:149], v[130:131], off
	global_load_dwordx4 v[142:145], v[132:133], off offset:256
	global_load_dwordx4 v[134:137], v[130:131], off offset:256
	s_mov_b64 s[0:1], 0x140000
	s_waitcnt vmcnt(3)
	v_lshlrev_b32_e32 v130, 16, v150
	v_and_b32_e32 v131, 0xffff0000, v150
	v_max_f32_e32 v130, v130, v130
	v_max_f32_e32 v131, v131, v131
	v_max_f32_e32 v130, 0x1e3ce508, v130
	v_max_f32_e32 v131, 0x1e3ce508, v131
	v_rcp_f32_e32 v130, v130
	v_rcp_f32_e32 v131, v131
	s_waitcnt vmcnt(2)
	v_lshlrev_b32_e32 v132, 16, v146
	v_and_b32_e32 v133, 0xffff0000, v146
	v_lshlrev_b32_e32 v146, 16, v147
	v_pk_mul_f32 v[130:131], v[130:131], v[132:133]
	v_and_b32_e32 v147, 0xffff0000, v147
	v_pk_mul_f32 v[102:103], v[102:103], v[130:131]
	v_lshlrev_b32_e32 v130, 16, v151
	v_max_f32_e32 v130, v130, v130
	v_max_f32_e32 v130, 0x1e3ce508, v130
	v_rcp_f32_e32 v138, v130
	v_and_b32_e32 v130, 0xffff0000, v151
	v_max_f32_e32 v130, v130, v130
	v_max_f32_e32 v130, 0x1e3ce508, v130
	v_rcp_f32_e32 v139, v130
	global_load_dwordx4 v[130:133], v[154:155], off
	v_lshl_add_u64 v[150:151], s[10:11], 0, v[140:141]
	v_pk_mul_f32 v[146:147], v[138:139], v[146:147]
	v_lshlrev_b32_e32 v138, 16, v152
	v_max_f32_e32 v138, v138, v138
	v_max_f32_e32 v138, 0x1e3ce508, v138
	v_rcp_f32_e32 v156, v138
	global_load_dwordx4 v[138:141], v[150:151], off
	v_and_b32_e32 v152, 0xffff0000, v152
	v_pk_mul_f32 v[104:105], v[104:105], v[146:147]
	v_lshlrev_b32_e32 v146, 16, v148
	v_and_b32_e32 v147, 0xffff0000, v148
	v_lshlrev_b32_e32 v148, 16, v153
	v_max_f32_e32 v152, v152, v152
	v_max_f32_e32 v148, v148, v148
	v_max_f32_e32 v152, 0x1e3ce508, v152
	v_max_f32_e32 v148, 0x1e3ce508, v148
	v_rcp_f32_e32 v157, v152
	v_rcp_f32_e32 v152, v148
	v_and_b32_e32 v148, 0xffff0000, v153
	v_max_f32_e32 v148, v148, v148
	v_max_f32_e32 v148, 0x1e3ce508, v148
	v_rcp_f32_e32 v153, v148
	s_waitcnt vmcnt(3)
; __device__ __forceinline__ float bf_lo(unsigned w) { return __uint_as_float(w << 16); }
; __device__ __forceinline__ float bf_hi(unsigned w) { return __uint_as_float(w & 0xffff0000u); }
;     __device__ __forceinline__ void mid(f32x4 (&acc)[2][2][4][2], const Unit& u, int wr, int wc, int fr, int fq) const {
;     ...
;             for (int m = 0; m < 4; ++m) { const size_t off = (size_t)(row0 + ai * HALF + m * 16) * 4096 + col0;
; #pragma unroll
;                 for (int bj = 0; bj < 2; ++bj) { const u32x4 ga = *(const u32x4*)(SGA + off + bj * HALF), gb = *(const u32x4*)(SGB + off + bj * HALF);
;                     const unsigned wa[4] = {ga.x, ga.y, ga.z, ga.w}, wb[4] = {gb.x, gb.y, gb.z, gb.w};
; #pragma unroll
;                     for (int p = 0; p < 4; ++p) { const float rl = bf_lo(wa[p]) * __builtin_amdgcn_rcpf(fmaxf(bf_lo(wb[p]), 1e-20f)), rh = bf_hi(wa[p]) * __builtin_amdgcn_rcpf(fmaxf(bf_hi(wb[p]), 1e-20f));
;                         acc[ai][bj][m][p >> 1][(p & 1) * 2] *= rl; acc[ai][bj][m][p >> 1][(p & 1) * 2 + 1] *= rh; } }
;                 if (m == 3) asm volatile("" : "+v"(acc[ai][0][0][0]), "+v"(acc[ai][0][0][1]), "+v"(acc[ai][1][0][0]), "+v"(acc[ai][1][0][1]), "+v"(acc[ai][0][1][0]), "+v"(acc[ai][0][1][1]), "+v"(acc[ai][1][1][0]), "+v"(acc[ai][1][1][1]), "+v"(acc[ai][0][2][0]), "+v"(acc[ai][0][2][1]), "+v"(acc[ai][1][2][0]), "+v"(acc[ai][1][2][1]), "+v"(acc[ai][0][3][0]), "+v"(acc[ai][0][3][1]), "+v"(acc[ai][1][3][0]), "+v"(acc[ai][1][3][1]) :: "memory"); }
	v_lshlrev_b32_e32 v148, 16, v142
	v_and_b32_e32 v142, 0xffff0000, v142
	v_max_f32_e32 v148, v148, v148
	v_max_f32_e32 v142, v142, v142
	v_pk_mul_f32 v[146:147], v[156:157], v[146:147]
	v_max_f32_e32 v148, 0x1e3ce508, v148
	v_max_f32_e32 v142, 0x1e3ce508, v142
	v_pk_mul_f32 v[98:99], v[98:99], v[146:147]
	v_lshlrev_b32_e32 v146, 16, v149
	v_and_b32_e32 v147, 0xffff0000, v149
	v_rcp_f32_e32 v148, v148
	v_rcp_f32_e32 v149, v142
	v_pk_mul_f32 v[146:147], v[152:153], v[146:147]
	global_load_dwordx4 v[150:153], v[150:151], off offset:256
	v_pk_mul_f32 v[100:101], v[100:101], v[146:147]
	s_waitcnt vmcnt(3)
	v_lshlrev_b32_e32 v146, 16, v134
	v_and_b32_e32 v147, 0xffff0000, v134
	v_pk_mul_f32 v[146:147], v[148:149], v[146:147]
	v_lshlrev_b32_e32 v134, 16, v143
	v_pk_mul_f32 v[94:95], v[94:95], v[146:147]
	global_load_dwordx4 v[146:149], v[154:155], off offset:256
	v_max_f32_e32 v134, v134, v134
	v_max_f32_e32 v134, 0x1e3ce508, v134
	v_rcp_f32_e32 v142, v134
	v_and_b32_e32 v134, 0xffff0000, v143
	v_max_f32_e32 v134, v134, v134
	v_max_f32_e32 v134, 0x1e3ce508, v134
	v_rcp_f32_e32 v143, v134
	v_lshlrev_b32_e32 v134, 16, v135
	v_and_b32_e32 v135, 0xffff0000, v135
	v_pk_mul_f32 v[134:135], v[142:143], v[134:135]
	s_nop 0
	v_pk_mul_f32 v[96:97], v[96:97], v[134:135]
	v_lshlrev_b32_e32 v134, 16, v144
	v_and_b32_e32 v135, 0xffff0000, v144
	v_max_f32_e32 v134, v134, v134
	v_max_f32_e32 v135, v135, v135
	v_max_f32_e32 v134, 0x1e3ce508, v134
	v_max_f32_e32 v135, 0x1e3ce508, v135
	v_rcp_f32_e32 v134, v134
	v_rcp_f32_e32 v135, v135
	v_lshlrev_b32_e32 v142, 16, v136
	v_and_b32_e32 v143, 0xffff0000, v136
	v_lshlrev_b32_e32 v136, 16, v145
	v_max_f32_e32 v136, v136, v136
	v_max_f32_e32 v136, 0x1e3ce508, v136
	v_pk_mul_f32 v[134:135], v[134:135], v[142:143]
	v_rcp_f32_e32 v142, v136
	v_and_b32_e32 v136, 0xffff0000, v145
	v_max_f32_e32 v136, v136, v136
	v_max_f32_e32 v136, 0x1e3ce508, v136
	v_rcp_f32_e32 v143, v136
	v_pk_mul_f32 v[86:87], v[86:87], v[134:135]
	v_lshlrev_b32_e32 v134, 16, v137
	v_and_b32_e32 v135, 0xffff0000, v137
	v_pk_mul_f32 v[134:135], v[142:143], v[134:135]
	s_waitcnt vmcnt(3)
	v_lshlrev_b32_e32 v136, 16, v130
	v_and_b32_e32 v130, 0xffff0000, v130
	v_max_f32_e32 v130, v130, v130
	v_max_f32_e32 v130, 0x1e3ce508, v130
	v_rcp_f32_e32 v137, v130
	v_lshlrev_b32_e32 v130, 16, v131
	v_max_f32_e32 v136, v136, v136
	v_max_f32_e32 v130, v130, v130
	v_max_f32_e32 v136, 0x1e3ce508, v136
	v_max_f32_e32 v130, 0x1e3ce508, v130
	v_rcp_f32_e32 v136, v136
	v_rcp_f32_e32 v142, v130
	v_and_b32_e32 v130, 0xffff0000, v131
	v_max_f32_e32 v130, v130, v130
	v_max_f32_e32 v130, 0x1e3ce508, v130
	v_pk_mul_f32 v[88:89], v[88:89], v[134:135]
	s_waitcnt vmcnt(2)
	v_lshlrev_b32_e32 v134, 16, v138
	v_and_b32_e32 v135, 0xffff0000, v138
	v_rcp_f32_e32 v143, v130
	v_lshl_add_u64 v[144:145], v[162:163], 0, s[0:1]
	v_pk_mul_f32 v[134:135], v[136:137], v[134:135]
	v_lshl_add_u64 v[130:131], s[12:13], 0, v[144:145]
	v_pk_mul_f32 v[74:75], v[74:75], v[134:135]
	global_load_dwordx4 v[134:137], v[130:131], off
	v_lshlrev_b32_e32 v138, 16, v139
	v_and_b32_e32 v139, 0xffff0000, v139
	v_pk_mul_f32 v[154:155], v[142:143], v[138:139]
	v_lshlrev_b32_e32 v138, 16, v132
	v_max_f32_e32 v138, v138, v138
	v_and_b32_e32 v132, 0xffff0000, v132
	v_max_f32_e32 v138, 0x1e3ce508, v138
	v_max_f32_e32 v132, v132, v132
	v_rcp_f32_e32 v156, v138
	v_lshl_add_u64 v[138:139], s[10:11], 0, v[144:145]
	v_max_f32_e32 v132, 0x1e3ce508, v132
	global_load_dwordx4 v[142:145], v[138:139], off
	v_rcp_f32_e32 v157, v132
	v_lshlrev_b32_e32 v132, 16, v133
	v_and_b32_e32 v133, 0xffff0000, v133
	v_max_f32_e32 v132, v132, v132
	v_max_f32_e32 v133, v133, v133
	v_max_f32_e32 v132, 0x1e3ce508, v132
	v_max_f32_e32 v133, 0x1e3ce508, v133
	v_rcp_f32_e32 v132, v132
	v_rcp_f32_e32 v133, v133
	v_pk_mul_f32 v[76:77], v[76:77], v[154:155]
	v_lshlrev_b32_e32 v154, 16, v140
	v_and_b32_e32 v155, 0xffff0000, v140
	v_lshlrev_b32_e32 v140, 16, v141
	v_and_b32_e32 v141, 0xffff0000, v141
	v_pk_mul_f32 v[132:133], v[132:133], v[140:141]
	s_waitcnt vmcnt(2)
	v_lshlrev_b32_e32 v140, 16, v146
	v_and_b32_e32 v141, 0xffff0000, v146
	v_max_f32_e32 v140, v140, v140
	v_max_f32_e32 v141, v141, v141
	v_max_f32_e32 v140, 0x1e3ce508, v140
	v_max_f32_e32 v141, 0x1e3ce508, v141
	v_rcp_f32_e32 v140, v140
	v_rcp_f32_e32 v141, v141
	v_pk_mul_f32 v[72:73], v[72:73], v[132:133]
	v_lshlrev_b32_e32 v132, 16, v150
	v_and_b32_e32 v133, 0xffff0000, v150
	v_pk_mul_f32 v[132:133], v[140:141], v[132:133]
	v_lshlrev_b32_e32 v140, 16, v147
	v_and_b32_e32 v141, 0xffff0000, v147
	v_max_f32_e32 v140, v140, v140
	v_max_f32_e32 v141, v141, v141
	v_max_f32_e32 v140, 0x1e3ce508, v140
	v_max_f32_e32 v141, 0x1e3ce508, v141
	v_rcp_f32_e32 v140, v140
	v_rcp_f32_e32 v141, v141
	v_pk_mul_f32 v[66:67], v[66:67], v[132:133]
	v_lshlrev_b32_e32 v132, 16, v151
	v_and_b32_e32 v133, 0xffff0000, v151
	v_pk_mul_f32 v[132:133], v[140:141], v[132:133]
	v_lshlrev_b32_e32 v140, 16, v148
	v_pk_mul_f32 v[68:69], v[68:69], v[132:133]
	global_load_dwordx4 v[130:133], v[130:131], off offset:256
	v_max_f32_e32 v140, v140, v140
	v_max_f32_e32 v140, 0x1e3ce508, v140
	v_rcp_f32_e32 v146, v140
	v_and_b32_e32 v140, 0xffff0000, v148
	v_max_f32_e32 v140, v140, v140
	v_max_f32_e32 v140, 0x1e3ce508, v140
	v_rcp_f32_e32 v147, v140
	global_load_dwordx4 v[138:141], v[138:139], off offset:256
	v_lshlrev_b32_e32 v148, 16, v149
	v_and_b32_e32 v149, 0xffff0000, v149
	v_max_f32_e32 v148, v148, v148
	v_max_f32_e32 v149, v149, v149
	v_max_f32_e32 v148, 0x1e3ce508, v148
	v_max_f32_e32 v149, 0x1e3ce508, v149
	v_rcp_f32_e32 v148, v148
	v_rcp_f32_e32 v149, v149
	v_lshlrev_b32_e32 v150, 16, v152
	v_and_b32_e32 v151, 0xffff0000, v152
	v_pk_mul_f32 v[146:147], v[146:147], v[150:151]
	s_mov_b64 s[0:1], 0x160000
	v_pk_mul_f32 v[54:55], v[54:55], v[146:147]
	v_lshlrev_b32_e32 v146, 16, v153
	v_and_b32_e32 v147, 0xffff0000, v153
	v_pk_mul_f32 v[146:147], v[148:149], v[146:147]
	v_pk_mul_f32 v[154:155], v[156:157], v[154:155]
	s_waitcnt vmcnt(3)
; __device__ __forceinline__ float bf_lo(unsigned w) { return __uint_as_float(w << 16); }
; __device__ __forceinline__ float bf_hi(unsigned w) { return __uint_as_float(w & 0xffff0000u); }
;     __device__ __forceinline__ void mid(f32x4 (&acc)[2][2][4][2], const Unit& u, int wr, int wc, int fr, int fq) const {
;     ...
;             for (int m = 0; m < 4; ++m) { const size_t off = (size_t)(row0 + ai * HALF + m * 16) * 4096 + col0;
; #pragma unroll
;                 for (int bj = 0; bj < 2; ++bj) { const u32x4 ga = *(const u32x4*)(SGA + off + bj * HALF), gb = *(const u32x4*)(SGB + off + bj * HALF);
;                     const unsigned wa[4] = {ga.x, ga.y, ga.z, ga.w}, wb[4] = {gb.x, gb.y, gb.z, gb.w};
; #pragma unroll
;                     for (int p = 0; p < 4; ++p) { const float rl = bf_lo(wa[p]) * __builtin_amdgcn_rcpf(fmaxf(bf_lo(wb[p]), 1e-20f)), rh = bf_hi(wa[p]) * __builtin_amdgcn_rcpf(fmaxf(bf_hi(wb[p]), 1e-20f));
;                         acc[ai][bj][m][p >> 1][(p & 1) * 2] *= rl; acc[ai][bj][m][p >> 1][(p & 1) * 2 + 1] *= rh; } }
;                 if (m == 3) asm volatile("" : "+v"(acc[ai][0][0][0]), "+v"(acc[ai][0][0][1]), "+v"(acc[ai][1][0][0]), "+v"(acc[ai][1][0][1]), "+v"(acc[ai][0][1][0]), "+v"(acc[ai][0][1][1]), "+v"(acc[ai][1][1][0]), "+v"(acc[ai][1][1][1]), "+v"(acc[ai][0][2][0]), "+v"(acc[ai][0][2][1]), "+v"(acc[ai][1][2][0]), "+v"(acc[ai][1][2][1]), "+v"(acc[ai][0][3][0]), "+v"(acc[ai][0][3][1]), "+v"(acc[ai][1][3][0]), "+v"(acc[ai][1][3][1]) :: "memory"); }
	v_lshlrev_b32_e32 v148, 16, v134
	v_and_b32_e32 v134, 0xffff0000, v134
	v_max_f32_e32 v148, v148, v148
	v_max_f32_e32 v134, v134, v134
	v_max_f32_e32 v148, 0x1e3ce508, v148
	v_max_f32_e32 v134, 0x1e3ce508, v134
	v_rcp_f32_e32 v148, v148
	v_rcp_f32_e32 v149, v134
	v_pk_mul_f32 v[56:57], v[56:57], v[146:147]
	v_lshl_add_u64 v[150:151], v[162:163], 0, s[0:1]
	v_pk_mul_f32 v[70:71], v[70:71], v[154:155]
	v_lshlrev_b32_e32 v134, 16, v135
	s_waitcnt vmcnt(2)
	v_lshlrev_b32_e32 v146, 16, v142
	v_and_b32_e32 v147, 0xffff0000, v142
	v_pk_mul_f32 v[146:147], v[148:149], v[146:147]
	v_and_b32_e32 v135, 0xffff0000, v135
	v_lshl_add_u64 v[154:155], s[12:13], 0, v[150:151]
	v_pk_mul_f32 v[42:43], v[42:43], v[146:147]
	v_max_f32_e32 v134, v134, v134
	v_max_f32_e32 v135, v135, v135
	global_load_dwordx4 v[146:149], v[154:155], off
	v_max_f32_e32 v134, 0x1e3ce508, v134
	v_max_f32_e32 v135, 0x1e3ce508, v135
	v_rcp_f32_e32 v134, v134
	v_rcp_f32_e32 v135, v135
	v_lshlrev_b32_e32 v142, 16, v143
	v_and_b32_e32 v143, 0xffff0000, v143
	s_mul_i32 s0, s50, s63
	v_pk_mul_f32 v[142:143], v[134:135], v[142:143]
	v_lshlrev_b32_e32 v134, 16, v136
	v_max_f32_e32 v134, v134, v134
	v_max_f32_e32 v134, 0x1e3ce508, v134
	v_rcp_f32_e32 v156, v134
	v_lshl_add_u64 v[134:135], s[10:11], 0, v[150:151]
	global_load_dwordx4 v[150:153], v[134:135], off
	v_and_b32_e32 v136, 0xffff0000, v136
	v_max_f32_e32 v136, v136, v136
	v_max_f32_e32 v136, 0x1e3ce508, v136
	v_rcp_f32_e32 v157, v136
	v_lshlrev_b32_e32 v136, 16, v137
	v_and_b32_e32 v137, 0xffff0000, v137
	v_max_f32_e32 v136, v136, v136
	v_max_f32_e32 v137, v137, v137
	v_max_f32_e32 v136, 0x1e3ce508, v136
	v_max_f32_e32 v137, 0x1e3ce508, v137
	v_rcp_f32_e32 v136, v136
	v_rcp_f32_e32 v137, v137
	v_pk_mul_f32 v[44:45], v[44:45], v[142:143]
	v_lshlrev_b32_e32 v142, 16, v144
	v_and_b32_e32 v143, 0xffff0000, v144
	v_pk_mul_f32 v[142:143], v[156:157], v[142:143]
	s_mul_hi_u32 s1, s50, s2
	v_pk_mul_f32 v[38:39], v[38:39], v[142:143]
	v_lshlrev_b32_e32 v142, 16, v145
	v_and_b32_e32 v143, 0xffff0000, v145
	v_pk_mul_f32 v[136:137], v[136:137], v[142:143]
	s_waitcnt vmcnt(3)
	v_lshlrev_b32_e32 v142, 16, v130
	v_and_b32_e32 v130, 0xffff0000, v130
	v_max_f32_e32 v142, v142, v142
	v_max_f32_e32 v130, v130, v130
	v_max_f32_e32 v142, 0x1e3ce508, v142
	v_max_f32_e32 v130, 0x1e3ce508, v130
	v_rcp_f32_e32 v142, v142
	v_rcp_f32_e32 v143, v130
	v_lshlrev_b32_e32 v130, 16, v131
	v_and_b32_e32 v131, 0xffff0000, v131
	v_pk_mul_f32 v[40:41], v[40:41], v[136:137]
	s_waitcnt vmcnt(2)
	v_lshlrev_b32_e32 v136, 16, v138
	v_and_b32_e32 v137, 0xffff0000, v138
	v_max_f32_e32 v130, v130, v130
	v_max_f32_e32 v131, v131, v131
	v_pk_mul_f32 v[136:137], v[142:143], v[136:137]
	v_max_f32_e32 v130, 0x1e3ce508, v130
	global_load_dwordx4 v[142:145], v[154:155], off offset:256
	v_max_f32_e32 v131, 0x1e3ce508, v131
	v_rcp_f32_e32 v130, v130
	v_rcp_f32_e32 v131, v131
	v_pk_mul_f32 v[22:23], v[22:23], v[136:137]
	v_lshlrev_b32_e32 v136, 16, v139
	v_and_b32_e32 v137, 0xffff0000, v139
	v_pk_mul_f32 v[130:131], v[130:131], v[136:137]
	v_lshlrev_b32_e32 v136, 16, v132
	v_max_f32_e32 v138, v136, v136
	global_load_dwordx4 v[134:137], v[134:135], off offset:256
	v_and_b32_e32 v132, 0xffff0000, v132
	v_max_f32_e32 v132, v132, v132
	v_max_f32_e32 v132, 0x1e3ce508, v132
	v_max_f32_e32 v138, 0x1e3ce508, v138
	v_rcp_f32_e32 v139, v132
	v_lshlrev_b32_e32 v132, 16, v133
	v_and_b32_e32 v133, 0xffff0000, v133
	v_rcp_f32_e32 v138, v138
	v_max_f32_e32 v132, v132, v132
	v_max_f32_e32 v133, v133, v133
	v_max_f32_e32 v132, 0x1e3ce508, v132
	v_max_f32_e32 v133, 0x1e3ce508, v133
	v_rcp_f32_e32 v132, v132
	v_rcp_f32_e32 v133, v133
	v_pk_mul_f32 v[24:25], v[24:25], v[130:131]
	v_lshlrev_b32_e32 v130, 16, v140
	v_and_b32_e32 v131, 0xffff0000, v140
	v_pk_mul_f32 v[130:131], v[138:139], v[130:131]
	s_add_i32 s1, s1, s0
	v_pk_mul_f32 v[130:131], v[14:15], v[130:131]
	v_lshlrev_b32_e32 v14, 16, v141
	v_and_b32_e32 v15, 0xffff0000, v141
	v_pk_mul_f32 v[14:15], v[132:133], v[14:15]
	s_waitcnt vmcnt(3)
; __device__ __forceinline__ float bf_lo(unsigned w) { return __uint_as_float(w << 16); }
; __device__ __forceinline__ float bf_hi(unsigned w) { return __uint_as_float(w & 0xffff0000u); }
;     __host__ __device__ bool next(int i, Unit& u) const {
;         const long L = (long)i * G + c; if (L >= nwg) return false;
;         int wgid = (int)L; { const int q = nwg / NXCD, r = nwg % NXCD, xcd = wgid % NXCD, off = wgid / NXCD; wgid = (xcd < r ? xcd * (q + 1) : r * (q + 1) + (xcd - r) * q) + off; }
;     __device__ __forceinline__ void mid(f32x4 (&acc)[2][2][4][2], const Unit& u, int wr, int wc, int fr, int fq) const {
;     ...
;                 for (int bj = 0; bj < 2; ++bj) { const u32x4 ga = *(const u32x4*)(SGA + off + bj * HALF), gb = *(const u32x4*)(SGB + off + bj * HALF);
;                     const unsigned wa[4] = {ga.x, ga.y, ga.z, ga.w}, wb[4] = {gb.x, gb.y, gb.z, gb.w};
; #pragma unroll
;                     for (int p = 0; p < 4; ++p) { const float rl = bf_lo(wa[p]) * __builtin_amdgcn_rcpf(fmaxf(bf_lo(wb[p]), 1e-20f)), rh = bf_hi(wa[p]) * __builtin_amdgcn_rcpf(fmaxf(bf_hi(wb[p]), 1e-20f));
;                         acc[ai][bj][m][p >> 1][(p & 1) * 2] *= rl; acc[ai][bj][m][p >> 1][(p & 1) * 2 + 1] *= rh; } }
;                 if (m == 3) asm volatile("" : "+v"(acc[ai][0][0][0]), "+v"(acc[ai][0][0][1]), "+v"(acc[ai][1][0][0]), "+v"(acc[ai][1][0][1]), "+v"(acc[ai][0][1][0]), "+v"(acc[ai][0][1][1]), "+v"(acc[ai][1][1][0]), "+v"(acc[ai][1][1][1]), "+v"(acc[ai][0][2][0]), "+v"(acc[ai][0][2][1]), "+v"(acc[ai][1][2][0]), "+v"(acc[ai][1][2][1]), "+v"(acc[ai][0][3][0]), "+v"(acc[ai][0][3][1]), "+v"(acc[ai][1][3][0]), "+v"(acc[ai][1][3][1]) :: "memory"); }
	v_lshlrev_b32_e32 v132, 16, v146
	v_max_f32_e32 v132, v132, v132
	v_max_f32_e32 v132, 0x1e3ce508, v132
	v_rcp_f32_e32 v138, v132
	v_and_b32_e32 v132, 0xffff0000, v146
	v_max_f32_e32 v132, v132, v132
	v_max_f32_e32 v132, 0x1e3ce508, v132
	v_rcp_f32_e32 v139, v132
	v_pk_mul_f32 v[132:133], v[16:17], v[14:15]
	v_lshlrev_b32_e32 v16, 16, v147
	v_and_b32_e32 v17, 0xffff0000, v147
	v_max_f32_e32 v16, v16, v16
	v_max_f32_e32 v17, v17, v17
	v_max_f32_e32 v16, 0x1e3ce508, v16
	v_max_f32_e32 v17, 0x1e3ce508, v17
	v_rcp_f32_e32 v16, v16
	v_rcp_f32_e32 v17, v17
	s_waitcnt vmcnt(2)
	v_lshlrev_b32_e32 v14, 16, v150
	v_and_b32_e32 v15, 0xffff0000, v150
	v_pk_mul_f32 v[14:15], v[138:139], v[14:15]
	s_mul_i32 s0, s50, s2
	v_pk_mul_f32 v[14:15], v[18:19], v[14:15]
	v_lshlrev_b32_e32 v18, 16, v151
	v_and_b32_e32 v19, 0xffff0000, v151
	v_pk_mul_f32 v[16:17], v[16:17], v[18:19]
	v_lshlrev_b32_e32 v18, 16, v148
	v_and_b32_e32 v19, 0xffff0000, v148
	v_max_f32_e32 v18, v18, v18
	v_max_f32_e32 v19, v19, v19
	v_max_f32_e32 v18, 0x1e3ce508, v18
	v_max_f32_e32 v19, 0x1e3ce508, v19
	v_rcp_f32_e32 v18, v18
	v_rcp_f32_e32 v19, v19
	v_pk_mul_f32 v[16:17], v[20:21], v[16:17]
	v_lshlrev_b32_e32 v20, 16, v152
	v_and_b32_e32 v21, 0xffff0000, v152
	v_pk_mul_f32 v[18:19], v[18:19], v[20:21]
	v_lshlrev_b32_e32 v20, 16, v149
	v_and_b32_e32 v21, 0xffff0000, v149
	v_max_f32_e32 v20, v20, v20
	v_max_f32_e32 v21, v21, v21
	v_max_f32_e32 v20, 0x1e3ce508, v20
	v_max_f32_e32 v21, 0x1e3ce508, v21
	v_rcp_f32_e32 v20, v20
	v_rcp_f32_e32 v21, v21
	v_pk_mul_f32 v[10:11], v[10:11], v[18:19]
	v_lshlrev_b32_e32 v18, 16, v153
	v_and_b32_e32 v19, 0xffff0000, v153
	v_pk_mul_f32 v[18:19], v[20:21], v[18:19]
	s_waitcnt vmcnt(1)
	v_lshlrev_b32_e32 v20, 16, v142
	v_and_b32_e32 v21, 0xffff0000, v142
	v_max_f32_e32 v20, v20, v20
	v_max_f32_e32 v21, v21, v21
	v_max_f32_e32 v20, 0x1e3ce508, v20
	v_max_f32_e32 v21, 0x1e3ce508, v21
	v_rcp_f32_e32 v20, v20
	v_rcp_f32_e32 v21, v21
	v_pk_mul_f32 v[12:13], v[12:13], v[18:19]
	s_waitcnt vmcnt(0)
	v_lshlrev_b32_e32 v18, 16, v134
	v_and_b32_e32 v19, 0xffff0000, v134
	v_pk_mul_f32 v[18:19], v[20:21], v[18:19]
	v_lshlrev_b32_e32 v20, 16, v143
	v_and_b32_e32 v21, 0xffff0000, v143
	v_max_f32_e32 v20, v20, v20
	v_max_f32_e32 v21, v21, v21
	v_max_f32_e32 v20, 0x1e3ce508, v20
	v_max_f32_e32 v21, 0x1e3ce508, v21
	v_rcp_f32_e32 v20, v20
	v_rcp_f32_e32 v21, v21
	v_pk_mul_f32 v[6:7], v[6:7], v[18:19]
	v_lshlrev_b32_e32 v18, 16, v135
	v_and_b32_e32 v19, 0xffff0000, v135
	v_pk_mul_f32 v[18:19], v[20:21], v[18:19]
	v_lshlrev_b32_e32 v20, 16, v144
	v_and_b32_e32 v21, 0xffff0000, v144
	v_max_f32_e32 v20, v20, v20
	v_max_f32_e32 v21, v21, v21
	v_max_f32_e32 v20, 0x1e3ce508, v20
	v_max_f32_e32 v21, 0x1e3ce508, v21
	v_rcp_f32_e32 v20, v20
	v_rcp_f32_e32 v21, v21
	v_pk_mul_f32 v[8:9], v[8:9], v[18:19]
	v_lshlrev_b32_e32 v18, 16, v136
	v_and_b32_e32 v19, 0xffff0000, v136
	v_pk_mul_f32 v[18:19], v[20:21], v[18:19]
	v_lshlrev_b32_e32 v20, 16, v145
	v_and_b32_e32 v21, 0xffff0000, v145
	v_max_f32_e32 v20, v20, v20
	v_max_f32_e32 v21, v21, v21
	v_max_f32_e32 v20, 0x1e3ce508, v20
	v_max_f32_e32 v21, 0x1e3ce508, v21
	v_rcp_f32_e32 v20, v20
	v_rcp_f32_e32 v21, v21
	v_pk_mul_f32 v[2:3], v[2:3], v[18:19]
	v_lshlrev_b32_e32 v18, 16, v137
	v_and_b32_e32 v19, 0xffff0000, v137
	v_pk_mul_f32 v[18:19], v[20:21], v[18:19]
	v_readlane_b32 s2, v238, 44
	v_pk_mul_f32 v[4:5], v[4:5], v[18:19]
	s_add_u32 s2, s0, s2
	s_addc_u32 s3, s1, s28
	v_cmp_gt_i64_e32 vcc, s[2:3], v[160:161]
	v_cmp_lt_i64_e64 s[0:1], s[2:3], v[158:159]
	s_cbranch_vccnz .LBB0_753
	s_ashr_i32 s3, s2, 31
	s_lshr_b32 s3, s3, 29
	s_add_i32 s4, s2, s3
	s_and_b32 s3, s4, -8
	s_sub_i32 s5, s2, s3
	s_cmp_gt_i32 s5, -1
	s_mov_b64 s[2:3], -1
	s_cbranch_scc0 .LBB0_750
	s_lshl_b32 s16, s5, 6
	s_mov_b64 s[2:3], 0

.LBB0_754:
	ds_read_b128 v[18:21], v172
	ds_read_b128 v[134:137], v172 offset:1024
	ds_read_b128 v[138:141], v172 offset:2048
	ds_read_b128 v[142:145], v172 offset:3072
	ds_read_b128 v[146:149], v173
	ds_read_b128 v[150:153], v173 offset:1024
	ds_read_b128 v[154:157], v173 offset:2048
	ds_read_b128 v[178:181], v173 offset:3072
	s_add_u32 s2, s30, 0x100
	s_addc_u32 s3, s31, 0
	s_cmp_eq_u32 s37, 60
	s_cselect_b32 s26, s33, s2
	s_cselect_b32 s27, s5, s3
	s_cselect_b32 s24, s36, s34
	s_cselect_b32 s25, s21, s35
	s_add_u32 s16, s26, 0x80
	s_addc_u32 s17, s27, 0
	s_add_u32 s30, s30, 0x100080
	s_addc_u32 s31, s31, 0
	s_mov_b32 m0, s76
	ds_read_b128 v[182:185], v174
	ds_read_b128 v[186:189], v174 offset:1024
	ds_read_b128 v[190:193], v174 offset:2048
	ds_read_b128 v[194:197], v174 offset:3072
	ds_read_b128 v[198:201], v174 offset:4096
	ds_read_b128 v[202:205], v174 offset:5120
	ds_read_b128 v[206:209], v174 offset:6144
	global_load_lds_dwordx4 v1, s[30:31]
	s_mov_b32 m0, s77
	ds_read_b128 v[210:213], v174 offset:7168
	global_load_lds_dwordx4 v165, s[30:31]
	s_waitcnt vmcnt(8)
	s_waitcnt lgkmcnt(0)
	s_setprio 1
	s_waitcnt lgkmcnt(0)
	s_barrier
	v_mfma_f32_16x16x32_bf16 v[34:37], v[18:21], v[182:185], v[34:37]
	v_mfma_f32_16x16x32_bf16 v[30:33], v[138:141], v[182:185], v[30:33]
	v_mfma_f32_16x16x32_bf16 v[46:49], v[18:21], v[190:193], v[46:49]
	v_mfma_f32_16x16x32_bf16 v[62:65], v[138:141], v[190:193], v[62:65]
	v_mfma_f32_16x16x32_bf16 v[78:81], v[18:21], v[198:201], v[78:81]
	v_mfma_f32_16x16x32_bf16 v[90:93], v[138:141], v[198:201], v[90:93]
	v_mfma_f32_16x16x32_bf16 v[106:109], v[18:21], v[206:209], v[106:109]
	v_mfma_f32_16x16x32_bf16 v[114:117], v[138:141], v[206:209], v[114:117]
	v_mfma_f32_16x16x32_bf16 v[26:29], v[146:149], v[182:185], v[26:29]
	v_mfma_f32_16x16x32_bf16 v[50:53], v[154:157], v[182:185], v[50:53]
	v_mfma_f32_16x16x32_bf16 v[58:61], v[146:149], v[190:193], v[58:61]
	v_mfma_f32_16x16x32_bf16 v[82:85], v[154:157], v[190:193], v[82:85]
	v_mfma_f32_16x16x32_bf16 v[110:113], v[146:149], v[198:201], v[110:113]
	v_mfma_f32_16x16x32_bf16 v[118:121], v[154:157], v[198:201], v[118:121]
	v_mfma_f32_16x16x32_bf16 v[122:125], v[146:149], v[206:209], v[122:125]
	v_mfma_f32_16x16x32_bf16 v[126:129], v[154:157], v[206:209], v[126:129]
	v_mfma_f32_16x16x32_bf16 v[34:37], v[134:137], v[186:189], v[34:37]
	v_mfma_f32_16x16x32_bf16 v[30:33], v[142:145], v[186:189], v[30:33]
	v_mfma_f32_16x16x32_bf16 v[46:49], v[134:137], v[194:197], v[46:49]
	v_mfma_f32_16x16x32_bf16 v[62:65], v[142:145], v[194:197], v[62:65]
	v_mfma_f32_16x16x32_bf16 v[78:81], v[134:137], v[202:205], v[78:81]
	v_mfma_f32_16x16x32_bf16 v[90:93], v[142:145], v[202:205], v[90:93]
	v_mfma_f32_16x16x32_bf16 v[106:109], v[134:137], v[210:213], v[106:109]
	v_mfma_f32_16x16x32_bf16 v[114:117], v[142:145], v[210:213], v[114:117]
	v_mfma_f32_16x16x32_bf16 v[26:29], v[150:153], v[186:189], v[26:29]
	v_mfma_f32_16x16x32_bf16 v[50:53], v[178:181], v[186:189], v[50:53]
	v_mfma_f32_16x16x32_bf16 v[58:61], v[150:153], v[194:197], v[58:61]
	v_mfma_f32_16x16x32_bf16 v[82:85], v[178:181], v[194:197], v[82:85]
	v_mfma_f32_16x16x32_bf16 v[110:113], v[150:153], v[202:205], v[110:113]
	v_mfma_f32_16x16x32_bf16 v[118:121], v[178:181], v[202:205], v[118:121]
	v_mfma_f32_16x16x32_bf16 v[122:125], v[150:153], v[210:213], v[122:125]
	v_mfma_f32_16x16x32_bf16 v[126:129], v[178:181], v[210:213], v[126:129]
	s_setprio 0
	s_barrier
	s_mov_b32 m0, s80
	s_mov_b64 s[30:31], s[24:25]
	ds_read_b128 v[182:185], v174 offset:16384
	ds_read_b128 v[186:189], v174 offset:17408
	ds_read_b128 v[190:193], v174 offset:18432
	global_load_lds_dwordx4 v164, s[30:31]
	s_mov_b32 m0, s81
	ds_read_b128 v[194:197], v174 offset:19456
	global_load_lds_dwordx4 v166, s[30:31]
	s_add_u32 s30, s24, 0x100000
	s_addc_u32 s31, s25, 0
	s_mov_b32 m0, s82
	ds_read_b128 v[198:201], v174 offset:20480
	global_load_lds_dwordx4 v164, s[30:31]
	s_mov_b32 m0, s83
	ds_read_b128 v[202:205], v174 offset:21504
	global_load_lds_dwordx4 v166, s[30:31]
	s_mov_b64 s[30:31], s[26:27]
	s_mov_b32 m0, s46
	ds_read_b128 v[206:209], v174 offset:22528
	global_load_lds_dwordx4 v1, s[30:31]
	s_mov_b32 m0, s47
	ds_read_b128 v[210:213], v174 offset:23552
	global_load_lds_dwordx4 v165, s[30:31]
	s_waitcnt vmcnt(8)
	s_waitcnt lgkmcnt(0)
	s_setprio 1
	s_waitcnt lgkmcnt(0)
	s_barrier
	v_mfma_f32_16x16x32_bf16 v[102:105], v[18:21], v[182:185], v[102:105]
	v_mfma_f32_16x16x32_bf16 v[98:101], v[138:141], v[182:185], v[98:101]
	v_mfma_f32_16x16x32_bf16 v[74:77], v[18:21], v[190:193], v[74:77]
	v_mfma_f32_16x16x32_bf16 v[70:73], v[138:141], v[190:193], v[70:73]
	v_mfma_f32_16x16x32_bf16 v[42:45], v[18:21], v[198:201], v[42:45]
	v_mfma_f32_16x16x32_bf16 v[38:41], v[138:141], v[198:201], v[38:41]
	v_mfma_f32_16x16x32_bf16 v[14:17], v[18:21], v[206:209], v[14:17]
	v_mfma_f32_16x16x32_bf16 v[10:13], v[138:141], v[206:209], v[10:13]
	v_mfma_f32_16x16x32_bf16 v[18:21], v[146:149], v[182:185], v[94:97]
	v_mfma_f32_16x16x32_bf16 v[86:89], v[154:157], v[182:185], v[86:89]
	v_mfma_f32_16x16x32_bf16 v[66:69], v[146:149], v[190:193], v[66:69]
	v_mfma_f32_16x16x32_bf16 v[54:57], v[154:157], v[190:193], v[54:57]
	v_mfma_f32_16x16x32_bf16 v[22:25], v[146:149], v[198:201], v[22:25]
	v_mfma_f32_16x16x32_bf16 v[94:97], v[154:157], v[198:201], v[130:133]
	v_mfma_f32_16x16x32_bf16 v[6:9], v[146:149], v[206:209], v[6:9]
	v_mfma_f32_16x16x32_bf16 v[2:5], v[154:157], v[206:209], v[2:5]
	v_mfma_f32_16x16x32_bf16 v[102:105], v[134:137], v[186:189], v[102:105]
	v_mfma_f32_16x16x32_bf16 v[98:101], v[142:145], v[186:189], v[98:101]
	v_mfma_f32_16x16x32_bf16 v[74:77], v[134:137], v[194:197], v[74:77]
	v_mfma_f32_16x16x32_bf16 v[70:73], v[142:145], v[194:197], v[70:73]
	v_mfma_f32_16x16x32_bf16 v[42:45], v[134:137], v[202:205], v[42:45]
	v_mfma_f32_16x16x32_bf16 v[38:41], v[142:145], v[202:205], v[38:41]
	v_mfma_f32_16x16x32_bf16 v[14:17], v[134:137], v[210:213], v[14:17]
	v_mfma_f32_16x16x32_bf16 v[10:13], v[142:145], v[210:213], v[10:13]
	v_mfma_f32_16x16x32_bf16 v[86:89], v[178:181], v[186:189], v[86:89]
	v_mfma_f32_16x16x32_bf16 v[66:69], v[150:153], v[194:197], v[66:69]
	v_mfma_f32_16x16x32_bf16 v[54:57], v[178:181], v[194:197], v[54:57]
	v_mfma_f32_16x16x32_bf16 v[22:25], v[150:153], v[202:205], v[22:25]
	v_mfma_f32_16x16x32_bf16 v[130:133], v[178:181], v[202:205], v[94:97]
	v_mfma_f32_16x16x32_bf16 v[6:9], v[150:153], v[210:213], v[6:9]
	v_mfma_f32_16x16x32_bf16 v[2:5], v[178:181], v[210:213], v[2:5]
	v_mfma_f32_16x16x32_bf16 v[18:21], v[150:153], v[186:189], v[18:21]
	s_setprio 0
	s_barrier
; #define PG8_BAR __builtin_amdgcn_s_barrier()
; #define PG8_BAR __builtin_amdgcn_s_barrier()
; template <class Epi, class Sched>
; __device__ __forceinline__ void gemm_phase_dual(PG8_LAS unsigned char* lds, const Gemm g  , const bf16_t* A0, const bf16_t* Bt0, int K0, const Sched& S, const Epi& E) {
;     ...
;         if (wr == 0) PG8_BAR;
	ds_read_b128 v[94:97], v175
	ds_read_b128 v[134:137], v175 offset:1024
	ds_read_b128 v[138:141], v175 offset:2048
	ds_read_b128 v[142:145], v175 offset:3072
	ds_read_b128 v[146:149], v176
	ds_read_b128 v[150:153], v176 offset:1024
	ds_read_b128 v[154:157], v176 offset:2048
	ds_read_b128 v[178:181], v176 offset:3072
	s_add_u32 s26, s26, 0x100000
	s_addc_u32 s27, s27, 0
	s_mov_b32 m0, s48
	ds_read_b128 v[182:185], v174 offset:32768
	ds_read_b128 v[186:189], v174 offset:33792
	ds_read_b128 v[190:193], v174 offset:34816
	ds_read_b128 v[194:197], v174 offset:35840
	ds_read_b128 v[198:201], v174 offset:36864
	ds_read_b128 v[202:205], v174 offset:37888
	ds_read_b128 v[206:209], v174 offset:38912
	global_load_lds_dwordx4 v1, s[26:27]
	s_mov_b32 m0, s49
	ds_read_b128 v[210:213], v174 offset:39936
	global_load_lds_dwordx4 v165, s[26:27]
	s_waitcnt vmcnt(8)
	s_waitcnt lgkmcnt(0)
	s_setprio 1
	s_waitcnt lgkmcnt(0)
	s_barrier
	v_mfma_f32_16x16x32_bf16 v[34:37], v[94:97], v[182:185], v[34:37]
	v_mfma_f32_16x16x32_bf16 v[30:33], v[138:141], v[182:185], v[30:33]
	v_mfma_f32_16x16x32_bf16 v[46:49], v[94:97], v[190:193], v[46:49]
	v_mfma_f32_16x16x32_bf16 v[62:65], v[138:141], v[190:193], v[62:65]
	v_mfma_f32_16x16x32_bf16 v[78:81], v[94:97], v[198:201], v[78:81]
	v_mfma_f32_16x16x32_bf16 v[90:93], v[138:141], v[198:201], v[90:93]
	v_mfma_f32_16x16x32_bf16 v[106:109], v[94:97], v[206:209], v[106:109]
	v_mfma_f32_16x16x32_bf16 v[114:117], v[138:141], v[206:209], v[114:117]
	v_mfma_f32_16x16x32_bf16 v[26:29], v[146:149], v[182:185], v[26:29]
	v_mfma_f32_16x16x32_bf16 v[50:53], v[154:157], v[182:185], v[50:53]
	v_mfma_f32_16x16x32_bf16 v[58:61], v[146:149], v[190:193], v[58:61]
	v_mfma_f32_16x16x32_bf16 v[82:85], v[154:157], v[190:193], v[82:85]
	v_mfma_f32_16x16x32_bf16 v[110:113], v[146:149], v[198:201], v[110:113]
	v_mfma_f32_16x16x32_bf16 v[118:121], v[154:157], v[198:201], v[118:121]
	v_mfma_f32_16x16x32_bf16 v[122:125], v[146:149], v[206:209], v[122:125]
	v_mfma_f32_16x16x32_bf16 v[126:129], v[154:157], v[206:209], v[126:129]
	v_mfma_f32_16x16x32_bf16 v[34:37], v[134:137], v[186:189], v[34:37]
	v_mfma_f32_16x16x32_bf16 v[30:33], v[142:145], v[186:189], v[30:33]
	v_mfma_f32_16x16x32_bf16 v[46:49], v[134:137], v[194:197], v[46:49]
	v_mfma_f32_16x16x32_bf16 v[62:65], v[142:145], v[194:197], v[62:65]
	v_mfma_f32_16x16x32_bf16 v[78:81], v[134:137], v[202:205], v[78:81]
	v_mfma_f32_16x16x32_bf16 v[90:93], v[142:145], v[202:205], v[90:93]
	v_mfma_f32_16x16x32_bf16 v[106:109], v[134:137], v[210:213], v[106:109]
	v_mfma_f32_16x16x32_bf16 v[114:117], v[142:145], v[210:213], v[114:117]
	v_mfma_f32_16x16x32_bf16 v[26:29], v[150:153], v[186:189], v[26:29]
	v_mfma_f32_16x16x32_bf16 v[50:53], v[178:181], v[186:189], v[50:53]
	v_mfma_f32_16x16x32_bf16 v[58:61], v[150:153], v[194:197], v[58:61]
	v_mfma_f32_16x16x32_bf16 v[82:85], v[178:181], v[194:197], v[82:85]
	v_mfma_f32_16x16x32_bf16 v[110:113], v[150:153], v[202:205], v[110:113]
	v_mfma_f32_16x16x32_bf16 v[118:121], v[178:181], v[202:205], v[118:121]
	v_mfma_f32_16x16x32_bf16 v[122:125], v[150:153], v[210:213], v[122:125]
	v_mfma_f32_16x16x32_bf16 v[126:129], v[178:181], v[210:213], v[126:129]
	s_setprio 0
	s_barrier
	s_add_u32 s26, s24, 0x80
	s_mov_b32 m0, s84
	s_addc_u32 s27, s25, 0
	ds_read_b128 v[182:185], v174 offset:49152
	ds_read_b128 v[186:189], v174 offset:50176
	ds_read_b128 v[190:193], v174 offset:51200
	ds_read_b128 v[194:197], v174 offset:52224
	s_add_u32 s24, s24, 0x100080
	global_load_lds_dwordx4 v164, s[26:27]
	s_mov_b32 m0, s85
	s_addc_u32 s25, s25, 0
	global_load_lds_dwordx4 v166, s[26:27]
	s_mov_b32 m0, s86
	ds_read_b128 v[198:201], v174 offset:53248
	global_load_lds_dwordx4 v164, s[24:25]
	s_mov_b32 m0, s87
	ds_read_b128 v[202:205], v174 offset:54272
	global_load_lds_dwordx4 v166, s[24:25]
	s_mov_b32 m0, s57
	ds_read_b128 v[206:209], v174 offset:55296
	global_load_lds_dwordx4 v1, s[16:17]
	s_mov_b32 m0, s62
	ds_read_b128 v[210:213], v174 offset:56320
	global_load_lds_dwordx4 v165, s[16:17]
	s_waitcnt vmcnt(8)
	s_waitcnt lgkmcnt(0)
	s_setprio 1
	s_waitcnt lgkmcnt(0)
	s_barrier
	v_mfma_f32_16x16x32_bf16 v[18:21], v[146:149], v[182:185], v[18:21]
	v_mfma_f32_16x16x32_bf16 v[102:105], v[94:97], v[182:185], v[102:105]
	v_mfma_f32_16x16x32_bf16 v[74:77], v[94:97], v[190:193], v[74:77]
	v_mfma_f32_16x16x32_bf16 v[42:45], v[94:97], v[198:201], v[42:45]
	v_mfma_f32_16x16x32_bf16 v[14:17], v[94:97], v[206:209], v[14:17]
	v_mfma_f32_16x16x32_bf16 v[94:97], v[150:153], v[186:189], v[18:21]
	v_mfma_f32_16x16x32_bf16 v[18:21], v[154:157], v[182:185], v[86:89]
	v_mfma_f32_16x16x32_bf16 v[86:89], v[178:181], v[186:189], v[18:21]
	v_mfma_f32_16x16x32_bf16 v[18:21], v[146:149], v[190:193], v[66:69]
	v_mfma_f32_16x16x32_bf16 v[66:69], v[150:153], v[194:197], v[18:21]
	v_mfma_f32_16x16x32_bf16 v[18:21], v[154:157], v[190:193], v[54:57]
	v_mfma_f32_16x16x32_bf16 v[54:57], v[178:181], v[194:197], v[18:21]
	v_mfma_f32_16x16x32_bf16 v[18:21], v[146:149], v[198:201], v[22:25]
	v_mfma_f32_16x16x32_bf16 v[98:101], v[138:141], v[182:185], v[98:101]
	v_mfma_f32_16x16x32_bf16 v[70:73], v[138:141], v[190:193], v[70:73]
	v_mfma_f32_16x16x32_bf16 v[38:41], v[138:141], v[198:201], v[38:41]
	v_mfma_f32_16x16x32_bf16 v[10:13], v[138:141], v[206:209], v[10:13]
	v_mfma_f32_16x16x32_bf16 v[22:25], v[150:153], v[202:205], v[18:21]
	v_mfma_f32_16x16x32_bf16 v[18:21], v[154:157], v[198:201], v[130:133]
	v_mfma_f32_16x16x32_bf16 v[6:9], v[146:149], v[206:209], v[6:9]
	v_mfma_f32_16x16x32_bf16 v[2:5], v[154:157], v[206:209], v[2:5]
	v_mfma_f32_16x16x32_bf16 v[102:105], v[134:137], v[186:189], v[102:105]
	v_mfma_f32_16x16x32_bf16 v[98:101], v[142:145], v[186:189], v[98:101]
	v_mfma_f32_16x16x32_bf16 v[74:77], v[134:137], v[194:197], v[74:77]
	v_mfma_f32_16x16x32_bf16 v[70:73], v[142:145], v[194:197], v[70:73]
	v_mfma_f32_16x16x32_bf16 v[42:45], v[134:137], v[202:205], v[42:45]
	v_mfma_f32_16x16x32_bf16 v[38:41], v[142:145], v[202:205], v[38:41]
	v_mfma_f32_16x16x32_bf16 v[14:17], v[134:137], v[210:213], v[14:17]
	v_mfma_f32_16x16x32_bf16 v[10:13], v[142:145], v[210:213], v[10:13]
	v_mfma_f32_16x16x32_bf16 v[130:133], v[178:181], v[202:205], v[18:21]
	v_mfma_f32_16x16x32_bf16 v[6:9], v[150:153], v[210:213], v[6:9]
	v_mfma_f32_16x16x32_bf16 v[2:5], v[178:181], v[210:213], v[2:5]
	s_setprio 0
	s_barrier
	s_add_i32 s37, s37, 2
	s_add_u32 s34, s34, 0x100
	s_addc_u32 s35, s35, 0
	s_cmp_gt_u32 s37, 61
	s_mov_b64 s[30:31], s[2:3]
	s_cbranch_scc0 .LBB0_754
	s_nop 0
	s_nop 0
	s_nop 0
	s_nop 0
	s_nop 0
	s_nop 0
	s_nop 0
	s_nop 0
	s_nop 0
	s_nop 0
	s_nop 0
	s_nop 0
	s_nop 0
	s_nop 0
	s_and_b64 vcc, exec, s[18:19]
	s_cbranch_vccz .LBB0_757
	s_barrier

; #define PG8_STAGE(bufoff, gbase, voff) do { const char* _gb = (const char*)(gbase); asm volatile("" : "+s"(_gb)); _Pragma("unroll") for (int _i = 0; _i < 2; ++_i) { asm volatile("" : "+v"((voff)[_i])); \
;         __builtin_amdgcn_global_load_lds((const unsigned*)(_gb + (voff)[_i]), (PG8_LAS unsigned*)(lds + (bufoff) + ldsw + _i * 8192), 16, 0, 0); } } while (0)
; #define PG8_LDA(dst, b, h) do { _Pragma("unroll") for (int m = 0; m < 4; ++m) _Pragma("unroll") for (int k = 0; k < 2; ++k) dst[m][k] = *(const PG8_LAS bf16x8*)(lds + PG8_SA(b, h) + aoff + m * 2048 + k * 1024); } while (0)
; #define PG8_LDB(dst, b, h) do { _Pragma("unroll") for (int n = 0; n < 2; ++n) _Pragma("unroll") for (int k = 0; k < 2; ++k) dst[n][k] = *(const PG8_LAS bf16x8*)(lds + PG8_SB(b, h) + boff + n * 2048 + k * 1024); } while (0)
; #define PG8_WAIT_V(n) asm volatile("s_waitcnt vmcnt(" #n ")" ::: "memory")
; #define PG8_WAIT_L(n) asm volatile("s_waitcnt lgkmcnt(" #n ")" ::: "memory")
; #define PG8_BAR __builtin_amdgcn_s_barrier()
; #define PG8_SCHED __builtin_amdgcn_sched_barrier(0)
; #define PG8_LDA(dst, b, h) do { _Pragma("unroll") for (int m = 0; m < 4; ++m) _Pragma("unroll") for (int k = 0; k < 2; ++k) dst[m][k] = *(const PG8_LAS bf16x8*)(lds + PG8_SA(b, h) + aoff + m * 2048 + k * 1024); } while (0)
; #define PG8_BAR __builtin_amdgcn_s_barrier()
; template <class Epi, class Sched, bool ALIGN_EPI = false, bool SP2 = false>
; __device__ __forceinline__ void gemm_phase(PG8_LAS unsigned char* lds, const Gemm g, const Sched& S, const Epi& E) {
;     ...
;             const bool last = (t == nt - 2);
;             const char* a1 = cA + (size_t)(t + 1) * kstep;
;             const char* a2 = last ? nA : cA + (size_t)(t + 2) * kstep; const char* b2 = last ? nB : cB + (size_t)(t + 2) * kstep;
;             const char* a3 = a2 + kstep; const char* b3 = b2 + kstep;
;             if (last && has_next) S.a_ready(nxt);
;             if constexpr (SP2) {
;             PG8_LDB(B0, 0, 0); PG8_LDB(B1, 0, 1); PG8_SCHED; PG8_LDA(At, 0, 0); PG8_STAGE(PG8_SA(1, 1), a1 + hstep, voffA);
;             PG8_WAIT_V(8); PG8_WAIT_L(0); PG8_BAR; PG8_MMA2(0); PG8_BAR; PG8_SCHED;
;             PG8_LDA(At, 0, 1); PG8_STAGE(PG8_SB(0, 0), b2, voffB); PG8_STAGE(PG8_SB(0, 1), b2 + hstep, voffB); PG8_STAGE(PG8_SA(0, 0), a2, voffA);
;             PG8_WAIT_V(8); PG8_WAIT_L(0); PG8_BAR; PG8_MMA2(1); PG8_BAR; PG8_SCHED;
.LBB0_833:
	ds_read_b128 v[130:133], v180
	ds_read_b128 v[134:137], v180 offset:1024
	ds_read_b128 v[138:141], v180 offset:2048
	ds_read_b128 v[142:145], v180 offset:3072
	ds_read_b128 v[146:149], v181
	ds_read_b128 v[150:153], v181 offset:1024
	ds_read_b128 v[154:157], v181 offset:2048
	ds_read_b128 v[158:161], v181 offset:3072
	s_add_u32 s24, s16, 0x100
	s_addc_u32 s25, s17, 0
	s_cmp_eq_u32 s87, 60
	s_cselect_b32 s28, s83, s24
	s_cselect_b32 s29, s55, s25
	s_cselect_b32 s26, s84, s85
	s_cselect_b32 s27, s53, s86
	s_add_u32 s2, s28, 0x80
	s_addc_u32 s3, s29, 0
	s_add_u32 s16, s16, 0x100080
	s_addc_u32 s17, s17, 0
	s_add_i32 m0, s69, 0xc000
	ds_read_b128 v[166:169], v182
	ds_read_b128 v[170:173], v182 offset:1024
	ds_read_b128 v[184:187], v182 offset:2048
	ds_read_b128 v[188:191], v182 offset:3072
	ds_read_b128 v[192:195], v182 offset:4096
	ds_read_b128 v[196:199], v182 offset:5120
	ds_read_b128 v[200:203], v182 offset:6144
	global_load_lds_dwordx4 v1, s[16:17]
	s_add_i32 m0, s69, 0xe000
	ds_read_b128 v[204:207], v182 offset:7168
	global_load_lds_dwordx4 v175, s[16:17]
	s_waitcnt vmcnt(8)
	s_waitcnt lgkmcnt(0)
	s_setprio 1
	s_waitcnt lgkmcnt(0)
	s_barrier
	v_mfma_f32_16x16x32_bf16 v[126:129], v[130:133], v[166:169], v[126:129]
	v_mfma_f32_16x16x32_bf16 v[122:125], v[138:141], v[166:169], v[122:125]
	v_mfma_f32_16x16x32_bf16 v[110:113], v[130:133], v[184:187], v[110:113]
	v_mfma_f32_16x16x32_bf16 v[106:109], v[138:141], v[184:187], v[106:109]
	v_mfma_f32_16x16x32_bf16 v[94:97], v[130:133], v[192:195], v[94:97]
	v_mfma_f32_16x16x32_bf16 v[90:93], v[138:141], v[192:195], v[90:93]
	v_mfma_f32_16x16x32_bf16 v[78:81], v[130:133], v[200:203], v[78:81]
	v_mfma_f32_16x16x32_bf16 v[74:77], v[138:141], v[200:203], v[74:77]
	v_mfma_f32_16x16x32_bf16 v[118:121], v[146:149], v[166:169], v[118:121]
	v_mfma_f32_16x16x32_bf16 v[114:117], v[154:157], v[166:169], v[114:117]
	v_mfma_f32_16x16x32_bf16 v[102:105], v[146:149], v[184:187], v[102:105]
	v_mfma_f32_16x16x32_bf16 v[98:101], v[154:157], v[184:187], v[98:101]
	v_mfma_f32_16x16x32_bf16 v[86:89], v[146:149], v[192:195], v[86:89]
	v_mfma_f32_16x16x32_bf16 v[82:85], v[154:157], v[192:195], v[82:85]
	v_mfma_f32_16x16x32_bf16 v[70:73], v[146:149], v[200:203], v[70:73]
	v_mfma_f32_16x16x32_bf16 v[66:69], v[154:157], v[200:203], v[66:69]
	v_mfma_f32_16x16x32_bf16 v[126:129], v[134:137], v[170:173], v[126:129]
	v_mfma_f32_16x16x32_bf16 v[122:125], v[142:145], v[170:173], v[122:125]
	v_mfma_f32_16x16x32_bf16 v[110:113], v[134:137], v[188:191], v[110:113]
	v_mfma_f32_16x16x32_bf16 v[106:109], v[142:145], v[188:191], v[106:109]
	v_mfma_f32_16x16x32_bf16 v[94:97], v[134:137], v[196:199], v[94:97]
	v_mfma_f32_16x16x32_bf16 v[90:93], v[142:145], v[196:199], v[90:93]
	v_mfma_f32_16x16x32_bf16 v[78:81], v[134:137], v[204:207], v[78:81]
	v_mfma_f32_16x16x32_bf16 v[74:77], v[142:145], v[204:207], v[74:77]
	v_mfma_f32_16x16x32_bf16 v[118:121], v[150:153], v[170:173], v[118:121]
	v_mfma_f32_16x16x32_bf16 v[114:117], v[158:161], v[170:173], v[114:117]
	v_mfma_f32_16x16x32_bf16 v[102:105], v[150:153], v[188:191], v[102:105]
	v_mfma_f32_16x16x32_bf16 v[98:101], v[158:161], v[188:191], v[98:101]
	v_mfma_f32_16x16x32_bf16 v[86:89], v[150:153], v[196:199], v[86:89]
	v_mfma_f32_16x16x32_bf16 v[82:85], v[158:161], v[196:199], v[82:85]
	v_mfma_f32_16x16x32_bf16 v[70:73], v[150:153], v[204:207], v[70:73]
	v_mfma_f32_16x16x32_bf16 v[66:69], v[158:161], v[204:207], v[66:69]
	s_setprio 0
	s_barrier
	s_add_i32 s88, s81, s73
	s_mov_b64 s[16:17], s[26:27]
	s_mov_b32 m0, s88
	ds_read_b128 v[166:169], v182 offset:16384
	ds_read_b128 v[170:173], v182 offset:17408
	ds_read_b128 v[184:187], v182 offset:18432
	global_load_lds_dwordx4 v174, s[16:17]
	s_add_i32 m0, s88, 0x2000
	ds_read_b128 v[188:191], v182 offset:19456
	global_load_lds_dwordx4 v176, s[16:17]
	s_add_u32 s16, s26, 0x100000
	s_addc_u32 s17, s27, 0
	s_add_i32 s88, s82, s73
	s_mov_b32 m0, s88
	ds_read_b128 v[192:195], v182 offset:20480
	global_load_lds_dwordx4 v174, s[16:17]
	s_add_i32 m0, s88, 0x2000
	ds_read_b128 v[196:199], v182 offset:21504
	global_load_lds_dwordx4 v176, s[16:17]
	s_mov_b64 s[16:17], s[28:29]
	s_mov_b32 m0, s69
	ds_read_b128 v[200:203], v182 offset:22528
	global_load_lds_dwordx4 v1, s[16:17]
	s_mov_b32 m0, s71
	ds_read_b128 v[204:207], v182 offset:23552
	global_load_lds_dwordx4 v175, s[16:17]
	s_waitcnt vmcnt(8)
	s_waitcnt lgkmcnt(0)
	s_setprio 1
	s_waitcnt lgkmcnt(0)
	s_barrier
	v_mfma_f32_16x16x32_bf16 v[62:65], v[130:133], v[166:169], v[62:65]
	v_mfma_f32_16x16x32_bf16 v[58:61], v[138:141], v[166:169], v[58:61]
	v_mfma_f32_16x16x32_bf16 v[46:49], v[130:133], v[184:187], v[46:49]
	v_mfma_f32_16x16x32_bf16 v[42:45], v[138:141], v[184:187], v[42:45]
	v_mfma_f32_16x16x32_bf16 v[30:33], v[130:133], v[192:195], v[30:33]
	v_mfma_f32_16x16x32_bf16 v[26:29], v[138:141], v[192:195], v[26:29]
	v_mfma_f32_16x16x32_bf16 v[14:17], v[130:133], v[200:203], v[14:17]
	v_mfma_f32_16x16x32_bf16 v[10:13], v[138:141], v[200:203], v[10:13]
	v_mfma_f32_16x16x32_bf16 v[54:57], v[146:149], v[166:169], v[54:57]
	v_mfma_f32_16x16x32_bf16 v[50:53], v[154:157], v[166:169], v[50:53]
	v_mfma_f32_16x16x32_bf16 v[38:41], v[146:149], v[184:187], v[38:41]
	v_mfma_f32_16x16x32_bf16 v[34:37], v[154:157], v[184:187], v[34:37]
	v_mfma_f32_16x16x32_bf16 v[22:25], v[146:149], v[192:195], v[22:25]
	v_mfma_f32_16x16x32_bf16 v[18:21], v[154:157], v[192:195], v[18:21]
	v_mfma_f32_16x16x32_bf16 v[6:9], v[146:149], v[200:203], v[6:9]
	v_mfma_f32_16x16x32_bf16 v[2:5], v[154:157], v[200:203], v[2:5]
	v_mfma_f32_16x16x32_bf16 v[62:65], v[134:137], v[170:173], v[62:65]
	v_mfma_f32_16x16x32_bf16 v[58:61], v[142:145], v[170:173], v[58:61]
	v_mfma_f32_16x16x32_bf16 v[46:49], v[134:137], v[188:191], v[46:49]
	v_mfma_f32_16x16x32_bf16 v[42:45], v[142:145], v[188:191], v[42:45]
	v_mfma_f32_16x16x32_bf16 v[30:33], v[134:137], v[196:199], v[30:33]
	v_mfma_f32_16x16x32_bf16 v[26:29], v[142:145], v[196:199], v[26:29]
	v_mfma_f32_16x16x32_bf16 v[14:17], v[134:137], v[204:207], v[14:17]
	v_mfma_f32_16x16x32_bf16 v[10:13], v[142:145], v[204:207], v[10:13]
	v_mfma_f32_16x16x32_bf16 v[54:57], v[150:153], v[170:173], v[54:57]
	v_mfma_f32_16x16x32_bf16 v[50:53], v[158:161], v[170:173], v[50:53]
	v_mfma_f32_16x16x32_bf16 v[38:41], v[150:153], v[188:191], v[38:41]
	v_mfma_f32_16x16x32_bf16 v[34:37], v[158:161], v[188:191], v[34:37]
	v_mfma_f32_16x16x32_bf16 v[22:25], v[150:153], v[196:199], v[22:25]
	v_mfma_f32_16x16x32_bf16 v[18:21], v[158:161], v[196:199], v[18:21]
	v_mfma_f32_16x16x32_bf16 v[6:9], v[150:153], v[204:207], v[6:9]
	v_mfma_f32_16x16x32_bf16 v[2:5], v[158:161], v[204:207], v[2:5]
	s_setprio 0
	s_barrier
; #define PG8_STAGE(bufoff, gbase, voff) do { const char* _gb = (const char*)(gbase); asm volatile("" : "+s"(_gb)); _Pragma("unroll") for (int _i = 0; _i < 2; ++_i) { asm volatile("" : "+v"((voff)[_i])); \
;         __builtin_amdgcn_global_load_lds((const unsigned*)(_gb + (voff)[_i]), (PG8_LAS unsigned*)(lds + (bufoff) + ldsw + _i * 8192), 16, 0, 0); } } while (0)
; #define PG8_LDA(dst, b, h) do { _Pragma("unroll") for (int m = 0; m < 4; ++m) _Pragma("unroll") for (int k = 0; k < 2; ++k) dst[m][k] = *(const PG8_LAS bf16x8*)(lds + PG8_SA(b, h) + aoff + m * 2048 + k * 1024); } while (0)
; #define PG8_LDB(dst, b, h) do { _Pragma("unroll") for (int n = 0; n < 2; ++n) _Pragma("unroll") for (int k = 0; k < 2; ++k) dst[n][k] = *(const PG8_LAS bf16x8*)(lds + PG8_SB(b, h) + boff + n * 2048 + k * 1024); } while (0)
; #define PG8_WAIT_V(n) asm volatile("s_waitcnt vmcnt(" #n ")" ::: "memory")
; #define PG8_WAIT_L(n) asm volatile("s_waitcnt lgkmcnt(" #n ")" ::: "memory")
; #define PG8_BAR __builtin_amdgcn_s_barrier()
; #define PG8_SCHED __builtin_amdgcn_sched_barrier(0)
; #define PG8_STAGE(bufoff, gbase, voff) do { const char* _gb = (const char*)(gbase); asm volatile("" : "+s"(_gb)); _Pragma("unroll") for (int _i = 0; _i < 2; ++_i) { asm volatile("" : "+v"((voff)[_i])); \
;         __builtin_amdgcn_global_load_lds((const unsigned*)(_gb + (voff)[_i]), (PG8_LAS unsigned*)(lds + (bufoff) + ldsw + _i * 8192), 16, 0, 0); } } while (0)
; #define PG8_LDA(dst, b, h) do { _Pragma("unroll") for (int m = 0; m < 4; ++m) _Pragma("unroll") for (int k = 0; k < 2; ++k) dst[m][k] = *(const PG8_LAS bf16x8*)(lds + PG8_SA(b, h) + aoff + m * 2048 + k * 1024); } while (0)
; template <class Epi, class Sched, bool ALIGN_EPI = false, bool SP2 = false>
; __device__ __forceinline__ void gemm_phase(PG8_LAS unsigned char* lds, const Gemm g, const Sched& S, const Epi& E) {
;     ...
;             PG8_LDB(B0, 1, 0); PG8_LDB(B1, 1, 1); PG8_SCHED; PG8_LDA(At, 1, 0); PG8_STAGE(PG8_SA(0, 1), a2 + hstep, voffA);
;             PG8_WAIT_V(8); PG8_WAIT_L(0); PG8_BAR; PG8_MMA2(0); PG8_BAR; PG8_SCHED;
;             PG8_LDA(At, 1, 1); PG8_STAGE(PG8_SB(1, 0), b3, voffB); PG8_STAGE(PG8_SB(1, 1), b3 + hstep, voffB); PG8_STAGE(PG8_SA(1, 0), a3, voffA);
;             PG8_WAIT_V(8); PG8_WAIT_L(0); PG8_BAR; PG8_MMA2(1); PG8_BAR; PG8_SCHED;
;     ...
;         if constexpr (ALIGN_EPI) { if (wr == 0) PG8_BAR; }
	s_add_i32 s88, 0, 0x18000
	s_add_i32 s89, 0, 0x1c000
	v_add_u32_e32 v142, s88, v178
	v_add_u32_e32 v158, s89, v178
	ds_read_b128 v[130:133], v142
	ds_read_b128 v[134:137], v142 offset:1024
	ds_read_b128 v[138:141], v142 offset:2048
	ds_read_b128 v[142:145], v142 offset:3072
	ds_read_b128 v[146:149], v158
	ds_read_b128 v[150:153], v158 offset:1024
	ds_read_b128 v[154:157], v158 offset:2048
	ds_read_b128 v[158:161], v158 offset:3072
	s_add_u32 s16, s28, 0x100000
	s_addc_u32 s17, s29, 0
	s_mov_b32 m0, s74
	ds_read_b128 v[166:169], v182 offset:32768
	ds_read_b128 v[170:173], v182 offset:33792
	ds_read_b128 v[184:187], v182 offset:34816
	ds_read_b128 v[188:191], v182 offset:35840
	ds_read_b128 v[192:195], v182 offset:36864
	ds_read_b128 v[196:199], v182 offset:37888
	ds_read_b128 v[200:203], v182 offset:38912
	global_load_lds_dwordx4 v1, s[16:17]
	s_mov_b32 m0, s75
	ds_read_b128 v[204:207], v182 offset:39936
	global_load_lds_dwordx4 v175, s[16:17]
	s_waitcnt vmcnt(8)
	s_waitcnt lgkmcnt(0)
	s_setprio 1
	s_waitcnt lgkmcnt(0)
	s_barrier
	v_mfma_f32_16x16x32_bf16 v[126:129], v[130:133], v[166:169], v[126:129]
	v_mfma_f32_16x16x32_bf16 v[122:125], v[138:141], v[166:169], v[122:125]
	v_mfma_f32_16x16x32_bf16 v[110:113], v[130:133], v[184:187], v[110:113]
	v_mfma_f32_16x16x32_bf16 v[106:109], v[138:141], v[184:187], v[106:109]
	v_mfma_f32_16x16x32_bf16 v[94:97], v[130:133], v[192:195], v[94:97]
	v_mfma_f32_16x16x32_bf16 v[90:93], v[138:141], v[192:195], v[90:93]
	v_mfma_f32_16x16x32_bf16 v[78:81], v[130:133], v[200:203], v[78:81]
	v_mfma_f32_16x16x32_bf16 v[74:77], v[138:141], v[200:203], v[74:77]
	v_mfma_f32_16x16x32_bf16 v[118:121], v[146:149], v[166:169], v[118:121]
	v_mfma_f32_16x16x32_bf16 v[114:117], v[154:157], v[166:169], v[114:117]
	v_mfma_f32_16x16x32_bf16 v[102:105], v[146:149], v[184:187], v[102:105]
	v_mfma_f32_16x16x32_bf16 v[98:101], v[154:157], v[184:187], v[98:101]
	v_mfma_f32_16x16x32_bf16 v[86:89], v[146:149], v[192:195], v[86:89]
	v_mfma_f32_16x16x32_bf16 v[82:85], v[154:157], v[192:195], v[82:85]
	v_mfma_f32_16x16x32_bf16 v[70:73], v[146:149], v[200:203], v[70:73]
	v_mfma_f32_16x16x32_bf16 v[66:69], v[154:157], v[200:203], v[66:69]
	v_mfma_f32_16x16x32_bf16 v[126:129], v[134:137], v[170:173], v[126:129]
	v_mfma_f32_16x16x32_bf16 v[122:125], v[142:145], v[170:173], v[122:125]
	v_mfma_f32_16x16x32_bf16 v[110:113], v[134:137], v[188:191], v[110:113]
	v_mfma_f32_16x16x32_bf16 v[106:109], v[142:145], v[188:191], v[106:109]
	v_mfma_f32_16x16x32_bf16 v[94:97], v[134:137], v[196:199], v[94:97]
	v_mfma_f32_16x16x32_bf16 v[90:93], v[142:145], v[196:199], v[90:93]
	v_mfma_f32_16x16x32_bf16 v[78:81], v[134:137], v[204:207], v[78:81]
	v_mfma_f32_16x16x32_bf16 v[74:77], v[142:145], v[204:207], v[74:77]
	v_mfma_f32_16x16x32_bf16 v[118:121], v[150:153], v[170:173], v[118:121]
	v_mfma_f32_16x16x32_bf16 v[114:117], v[158:161], v[170:173], v[114:117]
	v_mfma_f32_16x16x32_bf16 v[102:105], v[150:153], v[188:191], v[102:105]
	v_mfma_f32_16x16x32_bf16 v[98:101], v[158:161], v[188:191], v[98:101]
	v_mfma_f32_16x16x32_bf16 v[86:89], v[150:153], v[196:199], v[86:89]
	v_mfma_f32_16x16x32_bf16 v[82:85], v[158:161], v[196:199], v[82:85]
	v_mfma_f32_16x16x32_bf16 v[70:73], v[150:153], v[204:207], v[70:73]
	v_mfma_f32_16x16x32_bf16 v[66:69], v[158:161], v[204:207], v[66:69]
	s_setprio 0
	s_barrier
	s_add_u32 s16, s26, 0x80
	s_addc_u32 s17, s27, 0
	s_add_i32 s28, s88, s73
	s_mov_b32 m0, s28
	ds_read_b128 v[166:169], v182 offset:49152
	ds_read_b128 v[170:173], v182 offset:50176
	ds_read_b128 v[184:187], v182 offset:51200
	global_load_lds_dwordx4 v174, s[16:17]
	s_add_i32 m0, s28, 0x2000
	ds_read_b128 v[188:191], v182 offset:52224
	global_load_lds_dwordx4 v176, s[16:17]
	s_add_u32 s16, s26, 0x100080
	s_addc_u32 s17, s27, 0
	s_add_i32 s26, s89, s73
	s_mov_b32 m0, s26
	ds_read_b128 v[192:195], v182 offset:53248
	global_load_lds_dwordx4 v174, s[16:17]
	s_add_i32 m0, s26, 0x2000
	ds_read_b128 v[196:199], v182 offset:54272
	global_load_lds_dwordx4 v176, s[16:17]
	s_mov_b32 m0, s77
	ds_read_b128 v[200:203], v182 offset:55296
	global_load_lds_dwordx4 v1, s[2:3]
	s_mov_b32 m0, s78
	ds_read_b128 v[204:207], v182 offset:56320
	global_load_lds_dwordx4 v175, s[2:3]
	s_waitcnt vmcnt(8)
	s_waitcnt lgkmcnt(0)
	s_setprio 1
	s_waitcnt lgkmcnt(0)
	s_barrier
	v_mfma_f32_16x16x32_bf16 v[62:65], v[130:133], v[166:169], v[62:65]
	v_mfma_f32_16x16x32_bf16 v[58:61], v[138:141], v[166:169], v[58:61]
	v_mfma_f32_16x16x32_bf16 v[46:49], v[130:133], v[184:187], v[46:49]
	v_mfma_f32_16x16x32_bf16 v[42:45], v[138:141], v[184:187], v[42:45]
	v_mfma_f32_16x16x32_bf16 v[30:33], v[130:133], v[192:195], v[30:33]
	v_mfma_f32_16x16x32_bf16 v[26:29], v[138:141], v[192:195], v[26:29]
	v_mfma_f32_16x16x32_bf16 v[14:17], v[130:133], v[200:203], v[14:17]
	v_mfma_f32_16x16x32_bf16 v[10:13], v[138:141], v[200:203], v[10:13]
	v_mfma_f32_16x16x32_bf16 v[54:57], v[146:149], v[166:169], v[54:57]
	v_mfma_f32_16x16x32_bf16 v[50:53], v[154:157], v[166:169], v[50:53]
	v_mfma_f32_16x16x32_bf16 v[38:41], v[146:149], v[184:187], v[38:41]
	v_mfma_f32_16x16x32_bf16 v[34:37], v[154:157], v[184:187], v[34:37]
	v_mfma_f32_16x16x32_bf16 v[22:25], v[146:149], v[192:195], v[22:25]
	v_mfma_f32_16x16x32_bf16 v[18:21], v[154:157], v[192:195], v[18:21]
	v_mfma_f32_16x16x32_bf16 v[6:9], v[146:149], v[200:203], v[6:9]
	v_mfma_f32_16x16x32_bf16 v[2:5], v[154:157], v[200:203], v[2:5]
	v_mfma_f32_16x16x32_bf16 v[62:65], v[134:137], v[170:173], v[62:65]
	v_mfma_f32_16x16x32_bf16 v[58:61], v[142:145], v[170:173], v[58:61]
	v_mfma_f32_16x16x32_bf16 v[46:49], v[134:137], v[188:191], v[46:49]
	v_mfma_f32_16x16x32_bf16 v[42:45], v[142:145], v[188:191], v[42:45]
	v_mfma_f32_16x16x32_bf16 v[30:33], v[134:137], v[196:199], v[30:33]
	v_mfma_f32_16x16x32_bf16 v[26:29], v[142:145], v[196:199], v[26:29]
	v_mfma_f32_16x16x32_bf16 v[14:17], v[134:137], v[204:207], v[14:17]
	v_mfma_f32_16x16x32_bf16 v[10:13], v[142:145], v[204:207], v[10:13]
	v_mfma_f32_16x16x32_bf16 v[54:57], v[150:153], v[170:173], v[54:57]
	v_mfma_f32_16x16x32_bf16 v[50:53], v[158:161], v[170:173], v[50:53]
	v_mfma_f32_16x16x32_bf16 v[38:41], v[150:153], v[188:191], v[38:41]
	v_mfma_f32_16x16x32_bf16 v[34:37], v[158:161], v[188:191], v[34:37]
	v_mfma_f32_16x16x32_bf16 v[22:25], v[150:153], v[196:199], v[22:25]
	v_mfma_f32_16x16x32_bf16 v[18:21], v[158:161], v[196:199], v[18:21]
	v_mfma_f32_16x16x32_bf16 v[6:9], v[150:153], v[204:207], v[6:9]
	v_mfma_f32_16x16x32_bf16 v[2:5], v[158:161], v[204:207], v[2:5]
	s_setprio 0
	s_barrier
	s_add_i32 s87, s87, 2
	s_add_u32 s85, s85, 0x100
	s_addc_u32 s86, s86, 0
	s_cmp_gt_u32 s87, 61
	s_mov_b64 s[16:17], s[24:25]
	s_cbranch_scc0 .LBB0_833
	s_and_b64 vcc, exec, s[12:13]
	s_cbranch_vccz .LBB0_836
	s_barrier

; #define PG8_STAGE(bufoff, gbase, voff) do { const char* _gb = (const char*)(gbase); asm volatile("" : "+s"(_gb)); _Pragma("unroll") for (int _i = 0; _i < 2; ++_i) { asm volatile("" : "+v"((voff)[_i])); \
;         __builtin_amdgcn_global_load_lds((const unsigned*)(_gb + (voff)[_i]), (PG8_LAS unsigned*)(lds + (bufoff) + ldsw + _i * 8192), 16, 0, 0); } } while (0)
; #define PG8_LDA(dst, b, h) do { _Pragma("unroll") for (int m = 0; m < 4; ++m) _Pragma("unroll") for (int k = 0; k < 2; ++k) dst[m][k] = *(const PG8_LAS bf16x8*)(lds + PG8_SA(b, h) + aoff + m * 2048 + k * 1024); } while (0)
; #define PG8_LDB(dst, b, h) do { _Pragma("unroll") for (int n = 0; n < 2; ++n) _Pragma("unroll") for (int k = 0; k < 2; ++k) dst[n][k] = *(const PG8_LAS bf16x8*)(lds + PG8_SB(b, h) + boff + n * 2048 + k * 1024); } while (0)
; #define PG8_WAIT_V(n) asm volatile("s_waitcnt vmcnt(" #n ")" ::: "memory")
; #define PG8_WAIT_L(n) asm volatile("s_waitcnt lgkmcnt(" #n ")" ::: "memory")
; #define PG8_BAR __builtin_amdgcn_s_barrier()
; #define PG8_SCHED __builtin_amdgcn_sched_barrier(0)
; #define PG8_LDA(dst, b, h) do { _Pragma("unroll") for (int m = 0; m < 4; ++m) _Pragma("unroll") for (int k = 0; k < 2; ++k) dst[m][k] = *(const PG8_LAS bf16x8*)(lds + PG8_SA(b, h) + aoff + m * 2048 + k * 1024); } while (0)
; #define PG8_BAR __builtin_amdgcn_s_barrier()
; template <class Epi, class Sched, bool ALIGN_EPI = false, bool SP2 = false>
; __device__ __forceinline__ void gemm_phase(PG8_LAS unsigned char* lds, const Gemm g, const Sched& S, const Epi& E) {
;     ...
;             const bool last = (t == nt - 2);
;             const char* a1 = cA + (size_t)(t + 1) * kstep;
;             const char* a2 = last ? nA : cA + (size_t)(t + 2) * kstep; const char* b2 = last ? nB : cB + (size_t)(t + 2) * kstep;
;             const char* a3 = a2 + kstep; const char* b3 = b2 + kstep;
;             if (last && has_next) S.a_ready(nxt);
;             if constexpr (SP2) {
;             PG8_LDB(B0, 0, 0); PG8_LDB(B1, 0, 1); PG8_SCHED; PG8_LDA(At, 0, 0); PG8_STAGE(PG8_SA(1, 1), a1 + hstep, voffA);
;             PG8_WAIT_V(8); PG8_WAIT_L(0); PG8_BAR; PG8_MMA2(0); PG8_BAR; PG8_SCHED;
;             PG8_LDA(At, 0, 1); PG8_STAGE(PG8_SB(0, 0), b2, voffB); PG8_STAGE(PG8_SB(0, 1), b2 + hstep, voffB); PG8_STAGE(PG8_SA(0, 0), a2, voffA);
;             PG8_WAIT_V(8); PG8_WAIT_L(0); PG8_BAR; PG8_MMA2(1); PG8_BAR; PG8_SCHED;
.LBB0_933:
	v_add_u32_e32 v142, s78, v201
	v_add_u32_e32 v147, s79, v201
	s_nop 0
	ds_read_b128 v[6:9], v142
	ds_read_b128 v[62:65], v142 offset:1024
	ds_read_b128 v[138:141], v142 offset:2048
	ds_read_b128 v[142:145], v142 offset:3072
	ds_read_b128 v[164:167], v147
	ds_read_b128 v[168:171], v147 offset:1024
	ds_read_b128 v[172:175], v147 offset:2048
	ds_read_b128 v[176:179], v147 offset:3072
	s_add_u32 s14, s12, 0x100
	s_addc_u32 s15, s13, 0
	s_cmp_eq_u32 s83, 60
	s_cselect_b32 s18, s21, s14
	s_cselect_b32 s19, s20, s15
	s_cselect_b32 s16, s51, s62
	s_cselect_b32 s17, s49, s63
	s_add_u32 s2, s18, 0x80
	s_addc_u32 s3, s19, 0
	s_add_u32 s12, s12, 0x100080
	s_addc_u32 s13, s13, 0
	s_add_i32 m0, s33, 0xc000
	ds_read_b128 v[180:183], v219
	ds_read_b128 v[184:187], v219 offset:1024
	ds_read_b128 v[188:191], v219 offset:2048
	ds_read_b128 v[192:195], v219 offset:3072
	ds_read_b128 v[222:225], v219 offset:4096
	ds_read_b128 v[226:229], v219 offset:5120
	ds_read_b128 v[230:233], v219 offset:6144
	global_load_lds_dwordx4 v1, s[12:13]
	s_add_i32 m0, s33, 0xe000
	ds_read_b128 v[234:237], v219 offset:7168
	global_load_lds_dwordx4 v199, s[12:13]
	s_waitcnt vmcnt(8)
	s_waitcnt lgkmcnt(0)
	s_setprio 1
	s_waitcnt lgkmcnt(0)
	s_barrier
	v_mfma_f32_16x16x32_bf16 v[118:121], v[6:9], v[180:183], v[118:121]
	v_mfma_f32_16x16x32_bf16 v[114:117], v[138:141], v[180:183], v[114:117]
	v_mfma_f32_16x16x32_bf16 v[106:109], v[6:9], v[188:191], v[106:109]
	v_mfma_f32_16x16x32_bf16 v[86:89], v[138:141], v[188:191], v[86:89]
	v_mfma_f32_16x16x32_bf16 v[134:137], v[6:9], v[222:225], v[134:137]
	v_mfma_f32_16x16x32_bf16 v[90:93], v[138:141], v[222:225], v[90:93]
	v_mfma_f32_16x16x32_bf16 v[130:133], v[6:9], v[230:233], v[130:133]
	v_mfma_f32_16x16x32_bf16 v[110:113], v[138:141], v[230:233], v[110:113]
	v_mfma_f32_16x16x32_bf16 v[94:97], v[164:167], v[180:183], v[94:97]
	v_mfma_f32_16x16x32_bf16 v[82:85], v[172:175], v[180:183], v[82:85]
	v_mfma_f32_16x16x32_bf16 v[78:81], v[164:167], v[188:191], v[78:81]
	v_mfma_f32_16x16x32_bf16 v[74:77], v[172:175], v[188:191], v[74:77]
	v_mfma_f32_16x16x32_bf16 v[126:129], v[164:167], v[222:225], v[126:129]
	v_mfma_f32_16x16x32_bf16 v[98:101], v[172:175], v[222:225], v[98:101]
	v_mfma_f32_16x16x32_bf16 v[122:125], v[164:167], v[230:233], v[122:125]
	v_mfma_f32_16x16x32_bf16 v[102:105], v[172:175], v[230:233], v[102:105]
	v_mfma_f32_16x16x32_bf16 v[118:121], v[62:65], v[184:187], v[118:121]
	v_mfma_f32_16x16x32_bf16 v[114:117], v[142:145], v[184:187], v[114:117]
	v_mfma_f32_16x16x32_bf16 v[106:109], v[62:65], v[192:195], v[106:109]
	v_mfma_f32_16x16x32_bf16 v[86:89], v[142:145], v[192:195], v[86:89]
	v_mfma_f32_16x16x32_bf16 v[134:137], v[62:65], v[226:229], v[134:137]
	v_mfma_f32_16x16x32_bf16 v[90:93], v[142:145], v[226:229], v[90:93]
	v_mfma_f32_16x16x32_bf16 v[130:133], v[62:65], v[234:237], v[130:133]
	v_mfma_f32_16x16x32_bf16 v[110:113], v[142:145], v[234:237], v[110:113]
	v_mfma_f32_16x16x32_bf16 v[94:97], v[168:171], v[184:187], v[94:97]
	v_mfma_f32_16x16x32_bf16 v[82:85], v[176:179], v[184:187], v[82:85]
	v_mfma_f32_16x16x32_bf16 v[78:81], v[168:171], v[192:195], v[78:81]
	v_mfma_f32_16x16x32_bf16 v[74:77], v[176:179], v[192:195], v[74:77]
	v_mfma_f32_16x16x32_bf16 v[126:129], v[168:171], v[226:229], v[126:129]
	v_mfma_f32_16x16x32_bf16 v[98:101], v[176:179], v[226:229], v[98:101]
	v_mfma_f32_16x16x32_bf16 v[122:125], v[168:171], v[234:237], v[122:125]
	v_mfma_f32_16x16x32_bf16 v[102:105], v[176:179], v[234:237], v[102:105]
	s_setprio 0
	s_barrier
	s_add_i32 s84, s78, s25
	s_mov_b64 s[12:13], s[16:17]
	s_mov_b32 m0, s84
	ds_read_b128 v[180:183], v219 offset:16384
	ds_read_b128 v[184:187], v219 offset:17408
	ds_read_b128 v[188:191], v219 offset:18432
	global_load_lds_dwordx4 v198, s[12:13]
	s_add_i32 m0, s84, 0x2000
	ds_read_b128 v[192:195], v219 offset:19456
	global_load_lds_dwordx4 v200, s[12:13]
	s_add_u32 s12, s16, 0x100000
	s_addc_u32 s13, s17, 0
	s_add_i32 s84, s79, s25
	s_mov_b32 m0, s84
	ds_read_b128 v[222:225], v219 offset:20480
	global_load_lds_dwordx4 v198, s[12:13]
	s_add_i32 m0, s84, 0x2000
	ds_read_b128 v[226:229], v219 offset:21504
	global_load_lds_dwordx4 v200, s[12:13]
	s_mov_b64 s[12:13], s[18:19]
	s_mov_b32 m0, s33
	ds_read_b128 v[230:233], v219 offset:22528
	global_load_lds_dwordx4 v1, s[12:13]
	s_mov_b32 m0, s45
	ds_read_b128 v[234:237], v219 offset:23552
	global_load_lds_dwordx4 v199, s[12:13]
	s_waitcnt vmcnt(8)
	s_waitcnt lgkmcnt(0)
	s_setprio 1
	s_waitcnt lgkmcnt(0)
	s_barrier
	v_mfma_f32_16x16x32_bf16 v[34:37], v[6:9], v[180:183], v[34:37]
	v_mfma_f32_16x16x32_bf16 v[30:33], v[138:141], v[180:183], v[30:33]
	v_mfma_f32_16x16x32_bf16 v[26:29], v[6:9], v[188:191], v[26:29]
	v_mfma_f32_16x16x32_bf16 v[22:25], v[138:141], v[188:191], v[22:25]
	v_mfma_f32_16x16x32_bf16 v[70:73], v[6:9], v[222:225], v[70:73]
	v_mfma_f32_16x16x32_bf16 v[66:69], v[138:141], v[222:225], v[66:69]
	v_mfma_f32_16x16x32_bf16 v[50:53], v[138:141], v[230:233], v[50:53]
	v_mfma_f32_16x16x32_bf16 v[18:21], v[164:167], v[180:183], v[18:21]
	v_mfma_f32_16x16x32_bf16 v[14:17], v[172:175], v[180:183], v[14:17]
	v_mfma_f32_16x16x32_bf16 v[10:13], v[164:167], v[188:191], v[10:13]
	v_mfma_f32_16x16x32_bf16 v[2:5], v[172:175], v[188:191], v[2:5]
	v_mfma_f32_16x16x32_bf16 v[54:57], v[164:167], v[222:225], v[54:57]
	v_mfma_f32_16x16x32_bf16 v[46:49], v[172:175], v[222:225], v[46:49]
	v_mfma_f32_16x16x32_bf16 v[42:45], v[164:167], v[230:233], v[42:45]
	v_mfma_f32_16x16x32_bf16 v[38:41], v[172:175], v[230:233], v[38:41]
	v_mfma_f32_16x16x32_bf16 v[34:37], v[62:65], v[184:187], v[34:37]
	v_mfma_f32_16x16x32_bf16 v[30:33], v[142:145], v[184:187], v[30:33]
	v_mfma_f32_16x16x32_bf16 v[26:29], v[62:65], v[192:195], v[26:29]
	v_mfma_f32_16x16x32_bf16 v[22:25], v[142:145], v[192:195], v[22:25]
	v_mfma_f32_16x16x32_bf16 v[70:73], v[62:65], v[226:229], v[70:73]
	v_mfma_f32_16x16x32_bf16 v[66:69], v[142:145], v[226:229], v[66:69]
	v_mfma_f32_16x16x32_bf16 v[6:9], v[6:9], v[230:233], v[58:61]
	v_mfma_f32_16x16x32_bf16 v[50:53], v[142:145], v[234:237], v[50:53]
	v_mfma_f32_16x16x32_bf16 v[18:21], v[168:171], v[184:187], v[18:21]
	v_mfma_f32_16x16x32_bf16 v[14:17], v[176:179], v[184:187], v[14:17]
	v_mfma_f32_16x16x32_bf16 v[10:13], v[168:171], v[192:195], v[10:13]
	v_mfma_f32_16x16x32_bf16 v[2:5], v[176:179], v[192:195], v[2:5]
	v_mfma_f32_16x16x32_bf16 v[54:57], v[168:171], v[226:229], v[54:57]
	v_mfma_f32_16x16x32_bf16 v[46:49], v[176:179], v[226:229], v[46:49]
	v_mfma_f32_16x16x32_bf16 v[42:45], v[168:171], v[234:237], v[42:45]
	v_mfma_f32_16x16x32_bf16 v[38:41], v[176:179], v[234:237], v[38:41]
	v_mfma_f32_16x16x32_bf16 v[6:9], v[62:65], v[234:237], v[6:9]
	s_setprio 0
	s_barrier
; #define PG8_STAGE(bufoff, gbase, voff) do { const char* _gb = (const char*)(gbase); asm volatile("" : "+s"(_gb)); _Pragma("unroll") for (int _i = 0; _i < 2; ++_i) { asm volatile("" : "+v"((voff)[_i])); \
;         __builtin_amdgcn_global_load_lds((const unsigned*)(_gb + (voff)[_i]), (PG8_LAS unsigned*)(lds + (bufoff) + ldsw + _i * 8192), 16, 0, 0); } } while (0)
; #define PG8_LDA(dst, b, h) do { _Pragma("unroll") for (int m = 0; m < 4; ++m) _Pragma("unroll") for (int k = 0; k < 2; ++k) dst[m][k] = *(const PG8_LAS bf16x8*)(lds + PG8_SA(b, h) + aoff + m * 2048 + k * 1024); } while (0)
; #define PG8_LDB(dst, b, h) do { _Pragma("unroll") for (int n = 0; n < 2; ++n) _Pragma("unroll") for (int k = 0; k < 2; ++k) dst[n][k] = *(const PG8_LAS bf16x8*)(lds + PG8_SB(b, h) + boff + n * 2048 + k * 1024); } while (0)
; #define PG8_WAIT_V(n) asm volatile("s_waitcnt vmcnt(" #n ")" ::: "memory")
; #define PG8_WAIT_L(n) asm volatile("s_waitcnt lgkmcnt(" #n ")" ::: "memory")
; #define PG8_BAR __builtin_amdgcn_s_barrier()
; #define PG8_SCHED __builtin_amdgcn_sched_barrier(0)
; #define PG8_STAGE(bufoff, gbase, voff) do { const char* _gb = (const char*)(gbase); asm volatile("" : "+s"(_gb)); _Pragma("unroll") for (int _i = 0; _i < 2; ++_i) { asm volatile("" : "+v"((voff)[_i])); \
;         __builtin_amdgcn_global_load_lds((const unsigned*)(_gb + (voff)[_i]), (PG8_LAS unsigned*)(lds + (bufoff) + ldsw + _i * 8192), 16, 0, 0); } } while (0)
; #define PG8_LDA(dst, b, h) do { _Pragma("unroll") for (int m = 0; m < 4; ++m) _Pragma("unroll") for (int k = 0; k < 2; ++k) dst[m][k] = *(const PG8_LAS bf16x8*)(lds + PG8_SA(b, h) + aoff + m * 2048 + k * 1024); } while (0)
; template <class Epi, class Sched, bool ALIGN_EPI = false, bool SP2 = false>
; __device__ __forceinline__ void gemm_phase(PG8_LAS unsigned char* lds, const Gemm g, const Sched& S, const Epi& E) {
;     ...
;             PG8_LDB(B0, 1, 0); PG8_LDB(B1, 1, 1); PG8_SCHED; PG8_LDA(At, 1, 0); PG8_STAGE(PG8_SA(0, 1), a2 + hstep, voffA);
;             PG8_WAIT_V(8); PG8_WAIT_L(0); PG8_BAR; PG8_MMA2(0); PG8_BAR; PG8_SCHED;
;             PG8_LDA(At, 1, 1); PG8_STAGE(PG8_SB(1, 0), b3, voffB); PG8_STAGE(PG8_SB(1, 1), b3 + hstep, voffB); PG8_STAGE(PG8_SA(1, 0), a3, voffA);
;             PG8_WAIT_V(8); PG8_WAIT_L(0); PG8_BAR; PG8_MMA2(1); PG8_BAR; PG8_SCHED;
;     ...
;         if constexpr (ALIGN_EPI) { if (wr == 0) PG8_BAR; }
	s_add_i32 s84, 0, 0x18000
	s_add_i32 s85, 0, 0x1c000
	v_add_u32_e32 v142, s84, v201
	v_add_u32_e32 v147, s85, v201
	ds_read_b128 v[58:61], v142
	ds_read_b128 v[62:65], v142 offset:1024
	ds_read_b128 v[138:141], v142 offset:2048
	ds_read_b128 v[142:145], v142 offset:3072
	ds_read_b128 v[164:167], v147
	ds_read_b128 v[168:171], v147 offset:1024
	ds_read_b128 v[172:175], v147 offset:2048
	ds_read_b128 v[176:179], v147 offset:3072
	s_add_u32 s12, s18, 0x100000
	s_addc_u32 s13, s19, 0
	s_mov_b32 m0, s47
	ds_read_b128 v[180:183], v219 offset:32768
	ds_read_b128 v[184:187], v219 offset:33792
	ds_read_b128 v[188:191], v219 offset:34816
	ds_read_b128 v[192:195], v219 offset:35840
	ds_read_b128 v[222:225], v219 offset:36864
	ds_read_b128 v[226:229], v219 offset:37888
	ds_read_b128 v[230:233], v219 offset:38912
	global_load_lds_dwordx4 v1, s[12:13]
	s_mov_b32 m0, s87
	ds_read_b128 v[234:237], v219 offset:39936
	global_load_lds_dwordx4 v199, s[12:13]
	s_waitcnt vmcnt(8)
	s_waitcnt lgkmcnt(0)
	s_setprio 1
	s_waitcnt lgkmcnt(0)
	s_barrier
	v_mfma_f32_16x16x32_bf16 v[118:121], v[58:61], v[180:183], v[118:121]
	v_mfma_f32_16x16x32_bf16 v[114:117], v[138:141], v[180:183], v[114:117]
	v_mfma_f32_16x16x32_bf16 v[106:109], v[58:61], v[188:191], v[106:109]
	v_mfma_f32_16x16x32_bf16 v[86:89], v[138:141], v[188:191], v[86:89]
	v_mfma_f32_16x16x32_bf16 v[134:137], v[58:61], v[222:225], v[134:137]
	v_mfma_f32_16x16x32_bf16 v[90:93], v[138:141], v[222:225], v[90:93]
	v_mfma_f32_16x16x32_bf16 v[130:133], v[58:61], v[230:233], v[130:133]
	v_mfma_f32_16x16x32_bf16 v[110:113], v[138:141], v[230:233], v[110:113]
	v_mfma_f32_16x16x32_bf16 v[94:97], v[164:167], v[180:183], v[94:97]
	v_mfma_f32_16x16x32_bf16 v[82:85], v[172:175], v[180:183], v[82:85]
	v_mfma_f32_16x16x32_bf16 v[78:81], v[164:167], v[188:191], v[78:81]
	v_mfma_f32_16x16x32_bf16 v[74:77], v[172:175], v[188:191], v[74:77]
	v_mfma_f32_16x16x32_bf16 v[126:129], v[164:167], v[222:225], v[126:129]
	v_mfma_f32_16x16x32_bf16 v[98:101], v[172:175], v[222:225], v[98:101]
	v_mfma_f32_16x16x32_bf16 v[122:125], v[164:167], v[230:233], v[122:125]
	v_mfma_f32_16x16x32_bf16 v[102:105], v[172:175], v[230:233], v[102:105]
	v_mfma_f32_16x16x32_bf16 v[118:121], v[62:65], v[184:187], v[118:121]
	v_mfma_f32_16x16x32_bf16 v[114:117], v[142:145], v[184:187], v[114:117]
	v_mfma_f32_16x16x32_bf16 v[106:109], v[62:65], v[192:195], v[106:109]
	v_mfma_f32_16x16x32_bf16 v[86:89], v[142:145], v[192:195], v[86:89]
	v_mfma_f32_16x16x32_bf16 v[134:137], v[62:65], v[226:229], v[134:137]
	v_mfma_f32_16x16x32_bf16 v[90:93], v[142:145], v[226:229], v[90:93]
	v_mfma_f32_16x16x32_bf16 v[130:133], v[62:65], v[234:237], v[130:133]
	v_mfma_f32_16x16x32_bf16 v[110:113], v[142:145], v[234:237], v[110:113]
	v_mfma_f32_16x16x32_bf16 v[94:97], v[168:171], v[184:187], v[94:97]
	v_mfma_f32_16x16x32_bf16 v[82:85], v[176:179], v[184:187], v[82:85]
	v_mfma_f32_16x16x32_bf16 v[78:81], v[168:171], v[192:195], v[78:81]
	v_mfma_f32_16x16x32_bf16 v[74:77], v[176:179], v[192:195], v[74:77]
	v_mfma_f32_16x16x32_bf16 v[126:129], v[168:171], v[226:229], v[126:129]
	v_mfma_f32_16x16x32_bf16 v[98:101], v[176:179], v[226:229], v[98:101]
	v_mfma_f32_16x16x32_bf16 v[122:125], v[168:171], v[234:237], v[122:125]
	v_mfma_f32_16x16x32_bf16 v[102:105], v[176:179], v[234:237], v[102:105]
	s_setprio 0
	s_barrier
	s_add_u32 s12, s16, 0x80
	s_addc_u32 s13, s17, 0
	s_add_i32 s18, s84, s25
	s_mov_b32 m0, s18
	ds_read_b128 v[180:183], v219 offset:49152
	ds_read_b128 v[184:187], v219 offset:50176
	ds_read_b128 v[188:191], v219 offset:51200
	global_load_lds_dwordx4 v198, s[12:13]
	s_add_i32 m0, s18, 0x2000
	ds_read_b128 v[192:195], v219 offset:52224
	global_load_lds_dwordx4 v200, s[12:13]
	s_add_u32 s12, s16, 0x100080
	s_addc_u32 s13, s17, 0
	s_add_i32 s16, s85, s25
	s_mov_b32 m0, s16
	ds_read_b128 v[222:225], v219 offset:53248
	global_load_lds_dwordx4 v198, s[12:13]
	s_add_i32 m0, s16, 0x2000
	ds_read_b128 v[226:229], v219 offset:54272
	global_load_lds_dwordx4 v200, s[12:13]
	s_mov_b32 m0, s71
	ds_read_b128 v[230:233], v219 offset:55296
	global_load_lds_dwordx4 v1, s[2:3]
	s_mov_b32 m0, s72
	ds_read_b128 v[234:237], v219 offset:56320
	global_load_lds_dwordx4 v199, s[2:3]
	s_waitcnt vmcnt(8)
	s_waitcnt lgkmcnt(0)
	s_setprio 1
	s_waitcnt lgkmcnt(0)
	s_barrier
	v_mfma_f32_16x16x32_bf16 v[6:9], v[58:61], v[230:233], v[6:9]
	v_mfma_f32_16x16x32_bf16 v[34:37], v[58:61], v[180:183], v[34:37]
	v_mfma_f32_16x16x32_bf16 v[26:29], v[58:61], v[188:191], v[26:29]
	v_mfma_f32_16x16x32_bf16 v[70:73], v[58:61], v[222:225], v[70:73]
	v_mfma_f32_16x16x32_bf16 v[58:61], v[62:65], v[234:237], v[6:9]
	v_mfma_f32_16x16x32_bf16 v[6:9], v[138:141], v[230:233], v[50:53]
	v_mfma_f32_16x16x32_bf16 v[50:53], v[142:145], v[234:237], v[6:9]
	v_mfma_f32_16x16x32_bf16 v[6:9], v[164:167], v[180:183], v[18:21]
	v_mfma_f32_16x16x32_bf16 v[18:21], v[168:171], v[184:187], v[6:9]
	v_mfma_f32_16x16x32_bf16 v[6:9], v[172:175], v[180:183], v[14:17]
	v_mfma_f32_16x16x32_bf16 v[14:17], v[176:179], v[184:187], v[6:9]
	v_mfma_f32_16x16x32_bf16 v[6:9], v[164:167], v[188:191], v[10:13]
	v_mfma_f32_16x16x32_bf16 v[10:13], v[168:171], v[192:195], v[6:9]
	v_mfma_f32_16x16x32_bf16 v[6:9], v[164:167], v[222:225], v[54:57]
	v_mfma_f32_16x16x32_bf16 v[54:57], v[168:171], v[226:229], v[6:9]
	v_mfma_f32_16x16x32_bf16 v[6:9], v[172:175], v[222:225], v[46:49]
	v_mfma_f32_16x16x32_bf16 v[46:49], v[176:179], v[226:229], v[6:9]
	v_mfma_f32_16x16x32_bf16 v[6:9], v[164:167], v[230:233], v[42:45]
	v_mfma_f32_16x16x32_bf16 v[30:33], v[138:141], v[180:183], v[30:33]
	v_mfma_f32_16x16x32_bf16 v[22:25], v[138:141], v[188:191], v[22:25]
	v_mfma_f32_16x16x32_bf16 v[66:69], v[138:141], v[222:225], v[66:69]
	v_mfma_f32_16x16x32_bf16 v[2:5], v[172:175], v[188:191], v[2:5]
	v_mfma_f32_16x16x32_bf16 v[42:45], v[168:171], v[234:237], v[6:9]
	v_mfma_f32_16x16x32_bf16 v[6:9], v[172:175], v[230:233], v[38:41]
	v_mfma_f32_16x16x32_bf16 v[34:37], v[62:65], v[184:187], v[34:37]
	v_mfma_f32_16x16x32_bf16 v[30:33], v[142:145], v[184:187], v[30:33]
	v_mfma_f32_16x16x32_bf16 v[26:29], v[62:65], v[192:195], v[26:29]
	v_mfma_f32_16x16x32_bf16 v[22:25], v[142:145], v[192:195], v[22:25]
	v_mfma_f32_16x16x32_bf16 v[70:73], v[62:65], v[226:229], v[70:73]
	v_mfma_f32_16x16x32_bf16 v[66:69], v[142:145], v[226:229], v[66:69]
	v_mfma_f32_16x16x32_bf16 v[2:5], v[176:179], v[192:195], v[2:5]
	v_mfma_f32_16x16x32_bf16 v[38:41], v[176:179], v[234:237], v[6:9]
	s_setprio 0
	s_barrier
	s_add_i32 s83, s83, 2
	s_add_u32 s62, s62, 0x100
	s_addc_u32 s63, s63, 0
	s_cmp_gt_u32 s83, 61
	s_mov_b64 s[12:13], s[14:15]
	s_cbranch_scc0 .LBB0_933
	s_and_b64 vcc, exec, s[38:39]
	s_cbranch_vccz .LBB0_936
	s_barrier

; #define PG8_STAGE(bufoff, gbase, voff) do { const char* _gb = (const char*)(gbase); asm volatile("" : "+s"(_gb)); _Pragma("unroll") for (int _i = 0; _i < 2; ++_i) { asm volatile("" : "+v"((voff)[_i])); \
;         __builtin_amdgcn_global_load_lds((const unsigned*)(_gb + (voff)[_i]), (PG8_LAS unsigned*)(lds + (bufoff) + ldsw + _i * 8192), 16, 0, 0); } } while (0)
; #define PG8_LDA(dst, b, h) do { _Pragma("unroll") for (int m = 0; m < 4; ++m) _Pragma("unroll") for (int k = 0; k < 2; ++k) dst[m][k] = *(const PG8_LAS bf16x8*)(lds + PG8_SA(b, h) + aoff + m * 2048 + k * 1024); } while (0)
; #define PG8_LDB(dst, b, h) do { _Pragma("unroll") for (int n = 0; n < 2; ++n) _Pragma("unroll") for (int k = 0; k < 2; ++k) dst[n][k] = *(const PG8_LAS bf16x8*)(lds + PG8_SB(b, h) + boff + n * 2048 + k * 1024); } while (0)
; #define PG8_WAIT_V(n) asm volatile("s_waitcnt vmcnt(" #n ")" ::: "memory")
; #define PG8_WAIT_L(n) asm volatile("s_waitcnt lgkmcnt(" #n ")" ::: "memory")
; #define PG8_BAR __builtin_amdgcn_s_barrier()
; #define PG8_SCHED __builtin_amdgcn_sched_barrier(0)
; #define PG8_LDA(dst, b, h) do { _Pragma("unroll") for (int m = 0; m < 4; ++m) _Pragma("unroll") for (int k = 0; k < 2; ++k) dst[m][k] = *(const PG8_LAS bf16x8*)(lds + PG8_SA(b, h) + aoff + m * 2048 + k * 1024); } while (0)
; #define PG8_BAR __builtin_amdgcn_s_barrier()
; template <class Epi, class Sched, bool ALIGN_EPI = false, bool SP2 = false>
; __device__ __forceinline__ void gemm_phase(PG8_LAS unsigned char* lds, const Gemm g, const Sched& S, const Epi& E) {
;     ...
;             const bool last = (t == nt - 2);
;             const char* a1 = cA + (size_t)(t + 1) * kstep;
;             const char* a2 = last ? nA : cA + (size_t)(t + 2) * kstep; const char* b2 = last ? nB : cB + (size_t)(t + 2) * kstep;
;             const char* a3 = a2 + kstep; const char* b3 = b2 + kstep;
;             if (last && has_next) S.a_ready(nxt);
;             if constexpr (SP2) {
;             PG8_LDB(B0, 0, 0); PG8_LDB(B1, 0, 1); PG8_SCHED; PG8_LDA(At, 0, 0); PG8_STAGE(PG8_SA(1, 1), a1 + hstep, voffA);
;             PG8_WAIT_V(8); PG8_WAIT_L(0); PG8_BAR; PG8_MMA2(0); PG8_BAR; PG8_SCHED;
;             PG8_LDA(At, 0, 1); PG8_STAGE(PG8_SB(0, 0), b2, voffB); PG8_STAGE(PG8_SB(0, 1), b2 + hstep, voffB); PG8_STAGE(PG8_SA(0, 0), a2, voffA);
;             PG8_WAIT_V(8); PG8_WAIT_L(0); PG8_BAR; PG8_MMA2(1); PG8_BAR; PG8_SCHED;
.LBB0_1125:
	ds_read_b128 v[130:133], v162
	ds_read_b128 v[134:137], v162 offset:1024
	ds_read_b128 v[138:141], v162 offset:2048
	ds_read_b128 v[142:145], v162 offset:3072
	ds_read_b128 v[150:153], v163
	ds_read_b128 v[166:169], v163 offset:1024
	ds_read_b128 v[170:173], v163 offset:2048
	ds_read_b128 v[174:177], v163 offset:3072
	s_add_u32 s20, s16, 0x100
	s_addc_u32 s21, s17, 0
	s_cmpk_eq_i32 s53, 0xbc
	s_cselect_b32 s26, s6, s20
	s_cselect_b32 s27, s7, s21
	s_cselect_b32 s24, s18, s51
	s_cselect_b32 s25, s19, s52
	s_add_u32 s2, s26, 0x80
	s_addc_u32 s3, s27, 0
	s_add_u32 s16, s16, 0x300080
	s_addc_u32 s17, s17, 0
	s_add_i32 m0, s34, 0xc000
	ds_read_b128 v[178:181], v164
	ds_read_b128 v[182:185], v164 offset:1024
	ds_read_b128 v[186:189], v164 offset:2048
	ds_read_b128 v[190:193], v164 offset:3072
	ds_read_b128 v[194:197], v164 offset:4096
	ds_read_b128 v[198:201], v164 offset:5120
	ds_read_b128 v[202:205], v164 offset:6144
	global_load_lds_dwordx4 v1, s[16:17]
	s_add_i32 m0, s34, 0xe000
	ds_read_b128 v[206:209], v164 offset:7168
	global_load_lds_dwordx4 v157, s[16:17]
	s_waitcnt vmcnt(8)
	s_waitcnt lgkmcnt(0)
	s_setprio 1
	s_waitcnt lgkmcnt(0)
	s_barrier
	v_mfma_f32_16x16x32_bf16 v[126:129], v[130:133], v[178:181], v[126:129]
	v_mfma_f32_16x16x32_bf16 v[122:125], v[138:141], v[178:181], v[122:125]
	v_mfma_f32_16x16x32_bf16 v[110:113], v[130:133], v[186:189], v[110:113]
	v_mfma_f32_16x16x32_bf16 v[106:109], v[138:141], v[186:189], v[106:109]
	v_mfma_f32_16x16x32_bf16 v[94:97], v[130:133], v[194:197], v[94:97]
	v_mfma_f32_16x16x32_bf16 v[90:93], v[138:141], v[194:197], v[90:93]
	v_mfma_f32_16x16x32_bf16 v[78:81], v[130:133], v[202:205], v[78:81]
	v_mfma_f32_16x16x32_bf16 v[74:77], v[138:141], v[202:205], v[74:77]
	v_mfma_f32_16x16x32_bf16 v[118:121], v[150:153], v[178:181], v[118:121]
	v_mfma_f32_16x16x32_bf16 v[114:117], v[170:173], v[178:181], v[114:117]
	v_mfma_f32_16x16x32_bf16 v[102:105], v[150:153], v[186:189], v[102:105]
	v_mfma_f32_16x16x32_bf16 v[98:101], v[170:173], v[186:189], v[98:101]
	v_mfma_f32_16x16x32_bf16 v[86:89], v[150:153], v[194:197], v[86:89]
	v_mfma_f32_16x16x32_bf16 v[82:85], v[170:173], v[194:197], v[82:85]
	v_mfma_f32_16x16x32_bf16 v[70:73], v[150:153], v[202:205], v[70:73]
	v_mfma_f32_16x16x32_bf16 v[66:69], v[170:173], v[202:205], v[66:69]
	v_mfma_f32_16x16x32_bf16 v[126:129], v[134:137], v[182:185], v[126:129]
	v_mfma_f32_16x16x32_bf16 v[122:125], v[142:145], v[182:185], v[122:125]
	v_mfma_f32_16x16x32_bf16 v[110:113], v[134:137], v[190:193], v[110:113]
	v_mfma_f32_16x16x32_bf16 v[106:109], v[142:145], v[190:193], v[106:109]
	v_mfma_f32_16x16x32_bf16 v[94:97], v[134:137], v[198:201], v[94:97]
	v_mfma_f32_16x16x32_bf16 v[90:93], v[142:145], v[198:201], v[90:93]
	v_mfma_f32_16x16x32_bf16 v[78:81], v[134:137], v[206:209], v[78:81]
	v_mfma_f32_16x16x32_bf16 v[74:77], v[142:145], v[206:209], v[74:77]
	v_mfma_f32_16x16x32_bf16 v[118:121], v[166:169], v[182:185], v[118:121]
	v_mfma_f32_16x16x32_bf16 v[114:117], v[174:177], v[182:185], v[114:117]
	v_mfma_f32_16x16x32_bf16 v[102:105], v[166:169], v[190:193], v[102:105]
	v_mfma_f32_16x16x32_bf16 v[98:101], v[174:177], v[190:193], v[98:101]
	v_mfma_f32_16x16x32_bf16 v[86:89], v[166:169], v[198:201], v[86:89]
	v_mfma_f32_16x16x32_bf16 v[82:85], v[174:177], v[198:201], v[82:85]
	v_mfma_f32_16x16x32_bf16 v[70:73], v[166:169], v[206:209], v[70:73]
	v_mfma_f32_16x16x32_bf16 v[66:69], v[174:177], v[206:209], v[66:69]
	s_setprio 0
	s_barrier
	s_add_i32 s54, s43, s33
	s_mov_b64 s[16:17], s[24:25]
	s_mov_b32 m0, s54
	ds_read_b128 v[178:181], v164 offset:16384
	ds_read_b128 v[182:185], v164 offset:17408
	ds_read_b128 v[186:189], v164 offset:18432
	global_load_lds_dwordx4 v156, s[16:17]
	s_add_i32 m0, s54, 0x2000
	ds_read_b128 v[190:193], v164 offset:19456
	global_load_lds_dwordx4 v158, s[16:17]
	s_add_u32 s16, s24, 0x300000
	s_addc_u32 s17, s25, 0
	s_add_i32 s54, s44, s33
	s_mov_b32 m0, s54
	ds_read_b128 v[194:197], v164 offset:20480
	global_load_lds_dwordx4 v156, s[16:17]
	s_add_i32 m0, s54, 0x2000
	ds_read_b128 v[198:201], v164 offset:21504
	global_load_lds_dwordx4 v158, s[16:17]
	s_mov_b64 s[16:17], s[26:27]
	s_mov_b32 m0, s34
	ds_read_b128 v[202:205], v164 offset:22528
	global_load_lds_dwordx4 v1, s[16:17]
	s_mov_b32 m0, s35
	ds_read_b128 v[206:209], v164 offset:23552
	global_load_lds_dwordx4 v157, s[16:17]
	s_waitcnt vmcnt(8)
	s_waitcnt lgkmcnt(0)
	s_setprio 1
	s_waitcnt lgkmcnt(0)
	s_barrier
	v_mfma_f32_16x16x32_bf16 v[62:65], v[130:133], v[178:181], v[62:65]
	v_mfma_f32_16x16x32_bf16 v[58:61], v[138:141], v[178:181], v[58:61]
	v_mfma_f32_16x16x32_bf16 v[46:49], v[130:133], v[186:189], v[46:49]
	v_mfma_f32_16x16x32_bf16 v[42:45], v[138:141], v[186:189], v[42:45]
	v_mfma_f32_16x16x32_bf16 v[30:33], v[130:133], v[194:197], v[30:33]
	v_mfma_f32_16x16x32_bf16 v[26:29], v[138:141], v[194:197], v[26:29]
	v_mfma_f32_16x16x32_bf16 v[14:17], v[130:133], v[202:205], v[14:17]
	v_mfma_f32_16x16x32_bf16 v[10:13], v[138:141], v[202:205], v[10:13]
	v_mfma_f32_16x16x32_bf16 v[54:57], v[150:153], v[178:181], v[54:57]
	v_mfma_f32_16x16x32_bf16 v[50:53], v[170:173], v[178:181], v[50:53]
	v_mfma_f32_16x16x32_bf16 v[38:41], v[150:153], v[186:189], v[38:41]
	v_mfma_f32_16x16x32_bf16 v[34:37], v[170:173], v[186:189], v[34:37]
	v_mfma_f32_16x16x32_bf16 v[22:25], v[150:153], v[194:197], v[22:25]
	v_mfma_f32_16x16x32_bf16 v[18:21], v[170:173], v[194:197], v[18:21]
	v_mfma_f32_16x16x32_bf16 v[6:9], v[150:153], v[202:205], v[6:9]
	v_mfma_f32_16x16x32_bf16 v[2:5], v[170:173], v[202:205], v[2:5]
	v_mfma_f32_16x16x32_bf16 v[62:65], v[134:137], v[182:185], v[62:65]
	v_mfma_f32_16x16x32_bf16 v[58:61], v[142:145], v[182:185], v[58:61]
	v_mfma_f32_16x16x32_bf16 v[46:49], v[134:137], v[190:193], v[46:49]
	v_mfma_f32_16x16x32_bf16 v[42:45], v[142:145], v[190:193], v[42:45]
	v_mfma_f32_16x16x32_bf16 v[30:33], v[134:137], v[198:201], v[30:33]
	v_mfma_f32_16x16x32_bf16 v[26:29], v[142:145], v[198:201], v[26:29]
	v_mfma_f32_16x16x32_bf16 v[14:17], v[134:137], v[206:209], v[14:17]
	v_mfma_f32_16x16x32_bf16 v[10:13], v[142:145], v[206:209], v[10:13]
	v_mfma_f32_16x16x32_bf16 v[54:57], v[166:169], v[182:185], v[54:57]
	v_mfma_f32_16x16x32_bf16 v[50:53], v[174:177], v[182:185], v[50:53]
	v_mfma_f32_16x16x32_bf16 v[38:41], v[166:169], v[190:193], v[38:41]
	v_mfma_f32_16x16x32_bf16 v[34:37], v[174:177], v[190:193], v[34:37]
	v_mfma_f32_16x16x32_bf16 v[22:25], v[166:169], v[198:201], v[22:25]
	v_mfma_f32_16x16x32_bf16 v[18:21], v[174:177], v[198:201], v[18:21]
	v_mfma_f32_16x16x32_bf16 v[6:9], v[166:169], v[206:209], v[6:9]
	v_mfma_f32_16x16x32_bf16 v[2:5], v[174:177], v[206:209], v[2:5]
	s_setprio 0
	s_barrier
; #define PG8_STAGE(bufoff, gbase, voff) do { const char* _gb = (const char*)(gbase); asm volatile("" : "+s"(_gb)); _Pragma("unroll") for (int _i = 0; _i < 2; ++_i) { asm volatile("" : "+v"((voff)[_i])); \
;         __builtin_amdgcn_global_load_lds((const unsigned*)(_gb + (voff)[_i]), (PG8_LAS unsigned*)(lds + (bufoff) + ldsw + _i * 8192), 16, 0, 0); } } while (0)
; #define PG8_LDA(dst, b, h) do { _Pragma("unroll") for (int m = 0; m < 4; ++m) _Pragma("unroll") for (int k = 0; k < 2; ++k) dst[m][k] = *(const PG8_LAS bf16x8*)(lds + PG8_SA(b, h) + aoff + m * 2048 + k * 1024); } while (0)
; #define PG8_LDB(dst, b, h) do { _Pragma("unroll") for (int n = 0; n < 2; ++n) _Pragma("unroll") for (int k = 0; k < 2; ++k) dst[n][k] = *(const PG8_LAS bf16x8*)(lds + PG8_SB(b, h) + boff + n * 2048 + k * 1024); } while (0)
; #define PG8_WAIT_V(n) asm volatile("s_waitcnt vmcnt(" #n ")" ::: "memory")
; #define PG8_WAIT_L(n) asm volatile("s_waitcnt lgkmcnt(" #n ")" ::: "memory")
; #define PG8_BAR __builtin_amdgcn_s_barrier()
; #define PG8_SCHED __builtin_amdgcn_sched_barrier(0)
; #define PG8_STAGE(bufoff, gbase, voff) do { const char* _gb = (const char*)(gbase); asm volatile("" : "+s"(_gb)); _Pragma("unroll") for (int _i = 0; _i < 2; ++_i) { asm volatile("" : "+v"((voff)[_i])); \
;         __builtin_amdgcn_global_load_lds((const unsigned*)(_gb + (voff)[_i]), (PG8_LAS unsigned*)(lds + (bufoff) + ldsw + _i * 8192), 16, 0, 0); } } while (0)
; #define PG8_LDA(dst, b, h) do { _Pragma("unroll") for (int m = 0; m < 4; ++m) _Pragma("unroll") for (int k = 0; k < 2; ++k) dst[m][k] = *(const PG8_LAS bf16x8*)(lds + PG8_SA(b, h) + aoff + m * 2048 + k * 1024); } while (0)
; template <class Epi, class Sched, bool ALIGN_EPI = false, bool SP2 = false>
; __device__ __forceinline__ void gemm_phase(PG8_LAS unsigned char* lds, const Gemm g, const Sched& S, const Epi& E) {
;     ...
;             PG8_LDB(B0, 1, 0); PG8_LDB(B1, 1, 1); PG8_SCHED; PG8_LDA(At, 1, 0); PG8_STAGE(PG8_SA(0, 1), a2 + hstep, voffA);
;             PG8_WAIT_V(8); PG8_WAIT_L(0); PG8_BAR; PG8_MMA2(0); PG8_BAR; PG8_SCHED;
;             PG8_LDA(At, 1, 1); PG8_STAGE(PG8_SB(1, 0), b3, voffB); PG8_STAGE(PG8_SB(1, 1), b3 + hstep, voffB); PG8_STAGE(PG8_SA(1, 0), a3, voffA);
;             PG8_WAIT_V(8); PG8_WAIT_L(0); PG8_BAR; PG8_MMA2(1); PG8_BAR; PG8_SCHED;
;     ...
;         if constexpr (ALIGN_EPI) { if (wr == 0) PG8_BAR; }
	s_add_i32 s54, 0, 0x18000
	s_add_i32 s55, 0, 0x1c000
	v_add_u32_e32 v142, s54, v160
	v_add_u32_e32 v154, s55, v160
	ds_read_b128 v[130:133], v142
	ds_read_b128 v[134:137], v142 offset:1024
	ds_read_b128 v[138:141], v142 offset:2048
	ds_read_b128 v[142:145], v142 offset:3072
	ds_read_b128 v[150:153], v154
	ds_read_b128 v[166:169], v154 offset:1024
	ds_read_b128 v[170:173], v154 offset:2048
	ds_read_b128 v[174:177], v154 offset:3072
	s_add_u32 s16, s26, 0x300000
	s_addc_u32 s17, s27, 0
	s_mov_b32 m0, s36
	ds_read_b128 v[178:181], v164 offset:32768
	ds_read_b128 v[182:185], v164 offset:33792
	ds_read_b128 v[186:189], v164 offset:34816
	ds_read_b128 v[190:193], v164 offset:35840
	ds_read_b128 v[194:197], v164 offset:36864
	ds_read_b128 v[198:201], v164 offset:37888
	ds_read_b128 v[202:205], v164 offset:38912
	global_load_lds_dwordx4 v1, s[16:17]
	s_mov_b32 m0, s37
	ds_read_b128 v[206:209], v164 offset:39936
	global_load_lds_dwordx4 v157, s[16:17]
	s_waitcnt vmcnt(8)
	s_waitcnt lgkmcnt(0)
	s_setprio 1
	s_waitcnt lgkmcnt(0)
	s_barrier
	v_mfma_f32_16x16x32_bf16 v[126:129], v[130:133], v[178:181], v[126:129]
	v_mfma_f32_16x16x32_bf16 v[122:125], v[138:141], v[178:181], v[122:125]
	v_mfma_f32_16x16x32_bf16 v[110:113], v[130:133], v[186:189], v[110:113]
	v_mfma_f32_16x16x32_bf16 v[106:109], v[138:141], v[186:189], v[106:109]
	v_mfma_f32_16x16x32_bf16 v[94:97], v[130:133], v[194:197], v[94:97]
	v_mfma_f32_16x16x32_bf16 v[90:93], v[138:141], v[194:197], v[90:93]
	v_mfma_f32_16x16x32_bf16 v[78:81], v[130:133], v[202:205], v[78:81]
	v_mfma_f32_16x16x32_bf16 v[74:77], v[138:141], v[202:205], v[74:77]
	v_mfma_f32_16x16x32_bf16 v[118:121], v[150:153], v[178:181], v[118:121]
	v_mfma_f32_16x16x32_bf16 v[114:117], v[170:173], v[178:181], v[114:117]
	v_mfma_f32_16x16x32_bf16 v[102:105], v[150:153], v[186:189], v[102:105]
	v_mfma_f32_16x16x32_bf16 v[98:101], v[170:173], v[186:189], v[98:101]
	v_mfma_f32_16x16x32_bf16 v[86:89], v[150:153], v[194:197], v[86:89]
	v_mfma_f32_16x16x32_bf16 v[82:85], v[170:173], v[194:197], v[82:85]
	v_mfma_f32_16x16x32_bf16 v[70:73], v[150:153], v[202:205], v[70:73]
	v_mfma_f32_16x16x32_bf16 v[66:69], v[170:173], v[202:205], v[66:69]
	v_mfma_f32_16x16x32_bf16 v[126:129], v[134:137], v[182:185], v[126:129]
	v_mfma_f32_16x16x32_bf16 v[122:125], v[142:145], v[182:185], v[122:125]
	v_mfma_f32_16x16x32_bf16 v[110:113], v[134:137], v[190:193], v[110:113]
	v_mfma_f32_16x16x32_bf16 v[106:109], v[142:145], v[190:193], v[106:109]
	v_mfma_f32_16x16x32_bf16 v[94:97], v[134:137], v[198:201], v[94:97]
	v_mfma_f32_16x16x32_bf16 v[90:93], v[142:145], v[198:201], v[90:93]
	v_mfma_f32_16x16x32_bf16 v[78:81], v[134:137], v[206:209], v[78:81]
	v_mfma_f32_16x16x32_bf16 v[74:77], v[142:145], v[206:209], v[74:77]
	v_mfma_f32_16x16x32_bf16 v[118:121], v[166:169], v[182:185], v[118:121]
	v_mfma_f32_16x16x32_bf16 v[114:117], v[174:177], v[182:185], v[114:117]
	v_mfma_f32_16x16x32_bf16 v[102:105], v[166:169], v[190:193], v[102:105]
	v_mfma_f32_16x16x32_bf16 v[98:101], v[174:177], v[190:193], v[98:101]
	v_mfma_f32_16x16x32_bf16 v[86:89], v[166:169], v[198:201], v[86:89]
	v_mfma_f32_16x16x32_bf16 v[82:85], v[174:177], v[198:201], v[82:85]
	v_mfma_f32_16x16x32_bf16 v[70:73], v[166:169], v[206:209], v[70:73]
	v_mfma_f32_16x16x32_bf16 v[66:69], v[174:177], v[206:209], v[66:69]
	s_setprio 0
	s_barrier
	s_add_u32 s16, s24, 0x80
	s_addc_u32 s17, s25, 0
	s_add_i32 s26, s54, s33
	s_mov_b32 m0, s26
	ds_read_b128 v[178:181], v164 offset:49152
	ds_read_b128 v[182:185], v164 offset:50176
	ds_read_b128 v[186:189], v164 offset:51200
	global_load_lds_dwordx4 v156, s[16:17]
	s_add_i32 m0, s26, 0x2000
	ds_read_b128 v[190:193], v164 offset:52224
	global_load_lds_dwordx4 v158, s[16:17]
	s_add_u32 s16, s24, 0x300080
	s_addc_u32 s17, s25, 0
	s_add_i32 s24, s55, s33
	s_mov_b32 m0, s24
	ds_read_b128 v[194:197], v164 offset:53248
	global_load_lds_dwordx4 v156, s[16:17]
	s_add_i32 m0, s24, 0x2000
	ds_read_b128 v[198:201], v164 offset:54272
	global_load_lds_dwordx4 v158, s[16:17]
	s_mov_b32 m0, s39
	ds_read_b128 v[202:205], v164 offset:55296
	global_load_lds_dwordx4 v1, s[2:3]
	s_mov_b32 m0, s40
	ds_read_b128 v[206:209], v164 offset:56320
	global_load_lds_dwordx4 v157, s[2:3]
	s_waitcnt vmcnt(8)
	s_waitcnt lgkmcnt(0)
	s_setprio 1
	s_waitcnt lgkmcnt(0)
	s_barrier
	v_mfma_f32_16x16x32_bf16 v[62:65], v[130:133], v[178:181], v[62:65]
	v_mfma_f32_16x16x32_bf16 v[58:61], v[138:141], v[178:181], v[58:61]
	v_mfma_f32_16x16x32_bf16 v[46:49], v[130:133], v[186:189], v[46:49]
	v_mfma_f32_16x16x32_bf16 v[42:45], v[138:141], v[186:189], v[42:45]
	v_mfma_f32_16x16x32_bf16 v[30:33], v[130:133], v[194:197], v[30:33]
	v_mfma_f32_16x16x32_bf16 v[26:29], v[138:141], v[194:197], v[26:29]
	v_mfma_f32_16x16x32_bf16 v[14:17], v[130:133], v[202:205], v[14:17]
	v_mfma_f32_16x16x32_bf16 v[10:13], v[138:141], v[202:205], v[10:13]
	v_mfma_f32_16x16x32_bf16 v[54:57], v[150:153], v[178:181], v[54:57]
	v_mfma_f32_16x16x32_bf16 v[50:53], v[170:173], v[178:181], v[50:53]
	v_mfma_f32_16x16x32_bf16 v[38:41], v[150:153], v[186:189], v[38:41]
	v_mfma_f32_16x16x32_bf16 v[34:37], v[170:173], v[186:189], v[34:37]
	v_mfma_f32_16x16x32_bf16 v[22:25], v[150:153], v[194:197], v[22:25]
	v_mfma_f32_16x16x32_bf16 v[18:21], v[170:173], v[194:197], v[18:21]
	v_mfma_f32_16x16x32_bf16 v[6:9], v[150:153], v[202:205], v[6:9]
	v_mfma_f32_16x16x32_bf16 v[2:5], v[170:173], v[202:205], v[2:5]
	v_mfma_f32_16x16x32_bf16 v[62:65], v[134:137], v[182:185], v[62:65]
	v_mfma_f32_16x16x32_bf16 v[58:61], v[142:145], v[182:185], v[58:61]
	v_mfma_f32_16x16x32_bf16 v[46:49], v[134:137], v[190:193], v[46:49]
	v_mfma_f32_16x16x32_bf16 v[42:45], v[142:145], v[190:193], v[42:45]
	v_mfma_f32_16x16x32_bf16 v[30:33], v[134:137], v[198:201], v[30:33]
	v_mfma_f32_16x16x32_bf16 v[26:29], v[142:145], v[198:201], v[26:29]
	v_mfma_f32_16x16x32_bf16 v[14:17], v[134:137], v[206:209], v[14:17]
	v_mfma_f32_16x16x32_bf16 v[10:13], v[142:145], v[206:209], v[10:13]
	v_mfma_f32_16x16x32_bf16 v[54:57], v[166:169], v[182:185], v[54:57]
	v_mfma_f32_16x16x32_bf16 v[50:53], v[174:177], v[182:185], v[50:53]
	v_mfma_f32_16x16x32_bf16 v[38:41], v[166:169], v[190:193], v[38:41]
	v_mfma_f32_16x16x32_bf16 v[34:37], v[174:177], v[190:193], v[34:37]
	v_mfma_f32_16x16x32_bf16 v[22:25], v[166:169], v[198:201], v[22:25]
	v_mfma_f32_16x16x32_bf16 v[18:21], v[174:177], v[198:201], v[18:21]
	v_mfma_f32_16x16x32_bf16 v[6:9], v[166:169], v[206:209], v[6:9]
	v_mfma_f32_16x16x32_bf16 v[2:5], v[174:177], v[206:209], v[2:5]
	s_setprio 0
	s_barrier
	s_add_i32 s53, s53, 2
	s_add_u32 s51, s51, 0x100
	s_addc_u32 s52, s52, 0
	s_cmpk_gt_u32 s53, 0xbd
	s_mov_b64 s[16:17], s[20:21]
	s_cbranch_scc0 .LBB0_1125
	s_and_b64 vcc, exec, s[14:15]
	s_cbranch_vccz .LBB0_1128
	s_barrier

; #define PG8_STAGE(bufoff, gbase, voff) do { const char* _gb = (const char*)(gbase); asm volatile("" : "+s"(_gb)); _Pragma("unroll") for (int _i = 0; _i < 2; ++_i) { asm volatile("" : "+v"((voff)[_i])); \
;         __builtin_amdgcn_global_load_lds((const unsigned*)(_gb + (voff)[_i]), (PG8_LAS unsigned*)(lds + (bufoff) + ldsw + _i * 8192), 16, 0, 0); } } while (0)
; #define PG8_LDA(dst, b, h) do { _Pragma("unroll") for (int m = 0; m < 4; ++m) _Pragma("unroll") for (int k = 0; k < 2; ++k) dst[m][k] = *(const PG8_LAS bf16x8*)(lds + PG8_SA(b, h) + aoff + m * 2048 + k * 1024); } while (0)
; #define PG8_LDB(dst, b, h) do { _Pragma("unroll") for (int n = 0; n < 2; ++n) _Pragma("unroll") for (int k = 0; k < 2; ++k) dst[n][k] = *(const PG8_LAS bf16x8*)(lds + PG8_SB(b, h) + boff + n * 2048 + k * 1024); } while (0)
; #define PG8_WAIT_V(n) asm volatile("s_waitcnt vmcnt(" #n ")" ::: "memory")
; #define PG8_WAIT_L(n) asm volatile("s_waitcnt lgkmcnt(" #n ")" ::: "memory")
; #define PG8_BAR __builtin_amdgcn_s_barrier()
; #define PG8_SCHED __builtin_amdgcn_sched_barrier(0)
; #define PG8_LDA(dst, b, h) do { _Pragma("unroll") for (int m = 0; m < 4; ++m) _Pragma("unroll") for (int k = 0; k < 2; ++k) dst[m][k] = *(const PG8_LAS bf16x8*)(lds + PG8_SA(b, h) + aoff + m * 2048 + k * 1024); } while (0)
; #define PG8_BAR __builtin_amdgcn_s_barrier()
; template <class Epi, class Sched, bool ALIGN_EPI = false, bool SP2 = false>
; __device__ __forceinline__ void gemm_phase(PG8_LAS unsigned char* lds, const Gemm g, const Sched& S, const Epi& E) {
;     ...
;             const bool last = (t == nt - 2);
;             const char* a1 = cA + (size_t)(t + 1) * kstep;
;             const char* a2 = last ? nA : cA + (size_t)(t + 2) * kstep; const char* b2 = last ? nB : cB + (size_t)(t + 2) * kstep;
;             const char* a3 = a2 + kstep; const char* b3 = b2 + kstep;
;             if (last && has_next) S.a_ready(nxt);
;             if constexpr (SP2) {
;             PG8_LDB(B0, 0, 0); PG8_LDB(B1, 0, 1); PG8_SCHED; PG8_LDA(At, 0, 0); PG8_STAGE(PG8_SA(1, 1), a1 + hstep, voffA);
;             PG8_WAIT_V(8); PG8_WAIT_L(0); PG8_BAR; PG8_MMA2(0); PG8_BAR; PG8_SCHED;
;             PG8_LDA(At, 0, 1); PG8_STAGE(PG8_SB(0, 0), b2, voffB); PG8_STAGE(PG8_SB(0, 1), b2 + hstep, voffB); PG8_STAGE(PG8_SA(0, 0), a2, voffA);
;             PG8_WAIT_V(8); PG8_WAIT_L(0); PG8_BAR; PG8_MMA2(1); PG8_BAR; PG8_SCHED;
.LBB0_1217:
	ds_read_b128 v[128:131], v175
	ds_read_b128 v[132:135], v175 offset:1024
	ds_read_b128 v[136:139], v175 offset:2048
	ds_read_b128 v[140:143], v175 offset:3072
	ds_read_b128 v[152:155], v176
	ds_read_b128 v[156:159], v176 offset:1024
	ds_read_b128 v[160:163], v176 offset:2048
	ds_read_b128 v[184:187], v176 offset:3072
	s_add_u32 s28, s6, 0x100
	s_addc_u32 s29, s7, 0
	s_cmpk_eq_i32 s58, 0xbc
	s_cselect_b32 s36, s57, s28
	s_cselect_b32 s37, s56, s29
	s_cselect_b32 s34, s8, s4
	s_cselect_b32 s35, s9, s5
	s_add_u32 s30, s36, 0x80
	s_addc_u32 s31, s37, 0
	s_add_u32 s6, s6, 0x300080
	s_addc_u32 s7, s7, 0
	s_add_i32 m0, s41, 0xc000
	ds_read_b128 v[188:191], v177
	ds_read_b128 v[192:195], v177 offset:1024
	ds_read_b128 v[196:199], v177 offset:2048
	ds_read_b128 v[200:203], v177 offset:3072
	ds_read_b128 v[204:207], v177 offset:4096
	ds_read_b128 v[208:211], v177 offset:5120
	ds_read_b128 v[212:215], v177 offset:6144
	global_load_lds_dwordx4 v167, s[6:7]
	s_add_i32 m0, s41, 0xe000
	ds_read_b128 v[216:219], v177 offset:7168
	global_load_lds_dwordx4 v171, s[6:7]
	s_waitcnt vmcnt(8)
	s_waitcnt lgkmcnt(0)
	s_setprio 1
	s_waitcnt lgkmcnt(0)
	s_barrier
	v_mfma_f32_16x16x32_bf16 v[124:127], v[128:131], v[188:191], v[124:127]
	v_mfma_f32_16x16x32_bf16 v[120:123], v[136:139], v[188:191], v[120:123]
	v_mfma_f32_16x16x32_bf16 v[108:111], v[128:131], v[196:199], v[108:111]
	v_mfma_f32_16x16x32_bf16 v[104:107], v[136:139], v[196:199], v[104:107]
	v_mfma_f32_16x16x32_bf16 v[92:95], v[128:131], v[204:207], v[92:95]
	v_mfma_f32_16x16x32_bf16 v[88:91], v[136:139], v[204:207], v[88:91]
	v_mfma_f32_16x16x32_bf16 v[76:79], v[128:131], v[212:215], v[76:79]
	v_mfma_f32_16x16x32_bf16 v[72:75], v[136:139], v[212:215], v[72:75]
	v_mfma_f32_16x16x32_bf16 v[116:119], v[152:155], v[188:191], v[116:119]
	v_mfma_f32_16x16x32_bf16 v[112:115], v[160:163], v[188:191], v[112:115]
	v_mfma_f32_16x16x32_bf16 v[100:103], v[152:155], v[196:199], v[100:103]
	v_mfma_f32_16x16x32_bf16 v[96:99], v[160:163], v[196:199], v[96:99]
	v_mfma_f32_16x16x32_bf16 v[84:87], v[152:155], v[204:207], v[84:87]
	v_mfma_f32_16x16x32_bf16 v[80:83], v[160:163], v[204:207], v[80:83]
	v_mfma_f32_16x16x32_bf16 v[68:71], v[152:155], v[212:215], v[68:71]
	v_mfma_f32_16x16x32_bf16 v[64:67], v[160:163], v[212:215], v[64:67]
	v_mfma_f32_16x16x32_bf16 v[124:127], v[132:135], v[192:195], v[124:127]
	v_mfma_f32_16x16x32_bf16 v[120:123], v[140:143], v[192:195], v[120:123]
	v_mfma_f32_16x16x32_bf16 v[108:111], v[132:135], v[200:203], v[108:111]
	v_mfma_f32_16x16x32_bf16 v[104:107], v[140:143], v[200:203], v[104:107]
	v_mfma_f32_16x16x32_bf16 v[92:95], v[132:135], v[208:211], v[92:95]
	v_mfma_f32_16x16x32_bf16 v[88:91], v[140:143], v[208:211], v[88:91]
	v_mfma_f32_16x16x32_bf16 v[76:79], v[132:135], v[216:219], v[76:79]
	v_mfma_f32_16x16x32_bf16 v[72:75], v[140:143], v[216:219], v[72:75]
	v_mfma_f32_16x16x32_bf16 v[116:119], v[156:159], v[192:195], v[116:119]
	v_mfma_f32_16x16x32_bf16 v[112:115], v[184:187], v[192:195], v[112:115]
	v_mfma_f32_16x16x32_bf16 v[100:103], v[156:159], v[200:203], v[100:103]
	v_mfma_f32_16x16x32_bf16 v[96:99], v[184:187], v[200:203], v[96:99]
	v_mfma_f32_16x16x32_bf16 v[84:87], v[156:159], v[208:211], v[84:87]
	v_mfma_f32_16x16x32_bf16 v[80:83], v[184:187], v[208:211], v[80:83]
	v_mfma_f32_16x16x32_bf16 v[68:71], v[156:159], v[216:219], v[68:71]
	v_mfma_f32_16x16x32_bf16 v[64:67], v[184:187], v[216:219], v[64:67]
	s_setprio 0
	s_barrier
	s_add_i32 s59, s49, s39
	s_mov_b64 s[6:7], s[34:35]
	s_mov_b32 m0, s59
	ds_read_b128 v[188:191], v177 offset:16384
	ds_read_b128 v[192:195], v177 offset:17408
	ds_read_b128 v[196:199], v177 offset:18432
	global_load_lds_dwordx4 v169, s[6:7]
	s_add_i32 m0, s59, 0x2000
	ds_read_b128 v[200:203], v177 offset:19456
	global_load_lds_dwordx4 v172, s[6:7]
	s_add_u32 s6, s34, 0x300000
	s_addc_u32 s7, s35, 0
	s_add_i32 s59, s50, s39
	s_mov_b32 m0, s59
	ds_read_b128 v[204:207], v177 offset:20480
	global_load_lds_dwordx4 v169, s[6:7]
	s_add_i32 m0, s59, 0x2000
	ds_read_b128 v[208:211], v177 offset:21504
	global_load_lds_dwordx4 v172, s[6:7]
	s_mov_b64 s[6:7], s[36:37]
	s_mov_b32 m0, s41
	ds_read_b128 v[212:215], v177 offset:22528
	global_load_lds_dwordx4 v167, s[6:7]
	s_mov_b32 m0, s42
	ds_read_b128 v[216:219], v177 offset:23552
	global_load_lds_dwordx4 v171, s[6:7]
	s_waitcnt vmcnt(8)
	s_waitcnt lgkmcnt(0)
	s_setprio 1
	s_waitcnt lgkmcnt(0)
	s_barrier
	v_mfma_f32_16x16x32_bf16 v[60:63], v[128:131], v[188:191], v[60:63]
	v_mfma_f32_16x16x32_bf16 v[56:59], v[136:139], v[188:191], v[56:59]
	v_mfma_f32_16x16x32_bf16 v[44:47], v[128:131], v[196:199], v[44:47]
	v_mfma_f32_16x16x32_bf16 v[40:43], v[136:139], v[196:199], v[40:43]
	v_mfma_f32_16x16x32_bf16 v[28:31], v[128:131], v[204:207], v[28:31]
	v_mfma_f32_16x16x32_bf16 v[24:27], v[136:139], v[204:207], v[24:27]
	v_mfma_f32_16x16x32_bf16 v[12:15], v[128:131], v[212:215], v[12:15]
	v_mfma_f32_16x16x32_bf16 v[8:11], v[136:139], v[212:215], v[8:11]
	v_mfma_f32_16x16x32_bf16 v[52:55], v[152:155], v[188:191], v[52:55]
	v_mfma_f32_16x16x32_bf16 v[48:51], v[160:163], v[188:191], v[48:51]
	v_mfma_f32_16x16x32_bf16 v[36:39], v[152:155], v[196:199], v[36:39]
	v_mfma_f32_16x16x32_bf16 v[32:35], v[160:163], v[196:199], v[32:35]
	v_mfma_f32_16x16x32_bf16 v[20:23], v[152:155], v[204:207], v[20:23]
	v_mfma_f32_16x16x32_bf16 v[16:19], v[160:163], v[204:207], v[16:19]
	v_mfma_f32_16x16x32_bf16 v[4:7], v[152:155], v[212:215], v[4:7]
	v_mfma_f32_16x16x32_bf16 v[0:3], v[160:163], v[212:215], v[0:3]
	v_mfma_f32_16x16x32_bf16 v[60:63], v[132:135], v[192:195], v[60:63]
	v_mfma_f32_16x16x32_bf16 v[56:59], v[140:143], v[192:195], v[56:59]
	v_mfma_f32_16x16x32_bf16 v[44:47], v[132:135], v[200:203], v[44:47]
	v_mfma_f32_16x16x32_bf16 v[40:43], v[140:143], v[200:203], v[40:43]
	v_mfma_f32_16x16x32_bf16 v[28:31], v[132:135], v[208:211], v[28:31]
	v_mfma_f32_16x16x32_bf16 v[24:27], v[140:143], v[208:211], v[24:27]
	v_mfma_f32_16x16x32_bf16 v[12:15], v[132:135], v[216:219], v[12:15]
	v_mfma_f32_16x16x32_bf16 v[8:11], v[140:143], v[216:219], v[8:11]
	v_mfma_f32_16x16x32_bf16 v[52:55], v[156:159], v[192:195], v[52:55]
	v_mfma_f32_16x16x32_bf16 v[48:51], v[184:187], v[192:195], v[48:51]
	v_mfma_f32_16x16x32_bf16 v[36:39], v[156:159], v[200:203], v[36:39]
	v_mfma_f32_16x16x32_bf16 v[32:35], v[184:187], v[200:203], v[32:35]
	v_mfma_f32_16x16x32_bf16 v[20:23], v[156:159], v[208:211], v[20:23]
	v_mfma_f32_16x16x32_bf16 v[16:19], v[184:187], v[208:211], v[16:19]
	v_mfma_f32_16x16x32_bf16 v[4:7], v[156:159], v[216:219], v[4:7]
	v_mfma_f32_16x16x32_bf16 v[0:3], v[184:187], v[216:219], v[0:3]
	s_setprio 0
	s_barrier
; #define PG8_STAGE(bufoff, gbase, voff) do { const char* _gb = (const char*)(gbase); asm volatile("" : "+s"(_gb)); _Pragma("unroll") for (int _i = 0; _i < 2; ++_i) { asm volatile("" : "+v"((voff)[_i])); \
;         __builtin_amdgcn_global_load_lds((const unsigned*)(_gb + (voff)[_i]), (PG8_LAS unsigned*)(lds + (bufoff) + ldsw + _i * 8192), 16, 0, 0); } } while (0)
; #define PG8_LDA(dst, b, h) do { _Pragma("unroll") for (int m = 0; m < 4; ++m) _Pragma("unroll") for (int k = 0; k < 2; ++k) dst[m][k] = *(const PG8_LAS bf16x8*)(lds + PG8_SA(b, h) + aoff + m * 2048 + k * 1024); } while (0)
; #define PG8_LDB(dst, b, h) do { _Pragma("unroll") for (int n = 0; n < 2; ++n) _Pragma("unroll") for (int k = 0; k < 2; ++k) dst[n][k] = *(const PG8_LAS bf16x8*)(lds + PG8_SB(b, h) + boff + n * 2048 + k * 1024); } while (0)
; #define PG8_WAIT_V(n) asm volatile("s_waitcnt vmcnt(" #n ")" ::: "memory")
; #define PG8_WAIT_L(n) asm volatile("s_waitcnt lgkmcnt(" #n ")" ::: "memory")
; #define PG8_BAR __builtin_amdgcn_s_barrier()
; #define PG8_SCHED __builtin_amdgcn_sched_barrier(0)
; #define PG8_STAGE(bufoff, gbase, voff) do { const char* _gb = (const char*)(gbase); asm volatile("" : "+s"(_gb)); _Pragma("unroll") for (int _i = 0; _i < 2; ++_i) { asm volatile("" : "+v"((voff)[_i])); \
;         __builtin_amdgcn_global_load_lds((const unsigned*)(_gb + (voff)[_i]), (PG8_LAS unsigned*)(lds + (bufoff) + ldsw + _i * 8192), 16, 0, 0); } } while (0)
; #define PG8_LDA(dst, b, h) do { _Pragma("unroll") for (int m = 0; m < 4; ++m) _Pragma("unroll") for (int k = 0; k < 2; ++k) dst[m][k] = *(const PG8_LAS bf16x8*)(lds + PG8_SA(b, h) + aoff + m * 2048 + k * 1024); } while (0)
; #define PG8_WAIT_V(n) asm volatile("s_waitcnt vmcnt(" #n ")" ::: "memory")
; template <class Epi, class Sched, bool ALIGN_EPI = false, bool SP2 = false>
; __device__ __forceinline__ void gemm_phase(PG8_LAS unsigned char* lds, const Gemm g, const Sched& S, const Epi& E) {
;     ...
;             PG8_LDB(B0, 1, 0); PG8_LDB(B1, 1, 1); PG8_SCHED; PG8_LDA(At, 1, 0); PG8_STAGE(PG8_SA(0, 1), a2 + hstep, voffA);
;             PG8_WAIT_V(8); PG8_WAIT_L(0); PG8_BAR; PG8_MMA2(0); PG8_BAR; PG8_SCHED;
;             PG8_LDA(At, 1, 1); PG8_STAGE(PG8_SB(1, 0), b3, voffB); PG8_STAGE(PG8_SB(1, 1), b3 + hstep, voffB); PG8_STAGE(PG8_SA(1, 0), a3, voffA);
;             PG8_WAIT_V(8); PG8_WAIT_L(0); PG8_BAR; PG8_MMA2(1); PG8_BAR; PG8_SCHED;
	s_add_i32 s59, 0, 0x18000
	s_add_i32 s60, 0, 0x1c000
	v_add_u32_e32 v140, s59, v174
	v_add_u32_e32 v164, s60, v174
	ds_read_b128 v[128:131], v140
	ds_read_b128 v[132:135], v140 offset:1024
	ds_read_b128 v[136:139], v140 offset:2048
	ds_read_b128 v[140:143], v140 offset:3072
	ds_read_b128 v[152:155], v164
	ds_read_b128 v[156:159], v164 offset:1024
	ds_read_b128 v[160:163], v164 offset:2048
	ds_read_b128 v[184:187], v164 offset:3072
	s_add_u32 s6, s36, 0x300000
	s_addc_u32 s7, s37, 0
	s_mov_b32 m0, s43
	ds_read_b128 v[188:191], v177 offset:32768
	ds_read_b128 v[192:195], v177 offset:33792
	ds_read_b128 v[196:199], v177 offset:34816
	ds_read_b128 v[200:203], v177 offset:35840
	ds_read_b128 v[204:207], v177 offset:36864
	ds_read_b128 v[208:211], v177 offset:37888
	ds_read_b128 v[212:215], v177 offset:38912
	global_load_lds_dwordx4 v167, s[6:7]
	s_mov_b32 m0, s44
	ds_read_b128 v[216:219], v177 offset:39936
	global_load_lds_dwordx4 v171, s[6:7]
	s_waitcnt vmcnt(8)
	s_waitcnt lgkmcnt(0)
	s_setprio 1
	s_waitcnt lgkmcnt(0)
	s_barrier
	v_mfma_f32_16x16x32_bf16 v[124:127], v[128:131], v[188:191], v[124:127]
	v_mfma_f32_16x16x32_bf16 v[120:123], v[136:139], v[188:191], v[120:123]
	v_mfma_f32_16x16x32_bf16 v[108:111], v[128:131], v[196:199], v[108:111]
	v_mfma_f32_16x16x32_bf16 v[104:107], v[136:139], v[196:199], v[104:107]
	v_mfma_f32_16x16x32_bf16 v[92:95], v[128:131], v[204:207], v[92:95]
	v_mfma_f32_16x16x32_bf16 v[88:91], v[136:139], v[204:207], v[88:91]
	v_mfma_f32_16x16x32_bf16 v[76:79], v[128:131], v[212:215], v[76:79]
	v_mfma_f32_16x16x32_bf16 v[72:75], v[136:139], v[212:215], v[72:75]
	v_mfma_f32_16x16x32_bf16 v[116:119], v[152:155], v[188:191], v[116:119]
	v_mfma_f32_16x16x32_bf16 v[112:115], v[160:163], v[188:191], v[112:115]
	v_mfma_f32_16x16x32_bf16 v[100:103], v[152:155], v[196:199], v[100:103]
	v_mfma_f32_16x16x32_bf16 v[96:99], v[160:163], v[196:199], v[96:99]
	v_mfma_f32_16x16x32_bf16 v[84:87], v[152:155], v[204:207], v[84:87]
	v_mfma_f32_16x16x32_bf16 v[80:83], v[160:163], v[204:207], v[80:83]
	v_mfma_f32_16x16x32_bf16 v[68:71], v[152:155], v[212:215], v[68:71]
	v_mfma_f32_16x16x32_bf16 v[64:67], v[160:163], v[212:215], v[64:67]
	v_mfma_f32_16x16x32_bf16 v[124:127], v[132:135], v[192:195], v[124:127]
	v_mfma_f32_16x16x32_bf16 v[120:123], v[140:143], v[192:195], v[120:123]
	v_mfma_f32_16x16x32_bf16 v[108:111], v[132:135], v[200:203], v[108:111]
	v_mfma_f32_16x16x32_bf16 v[104:107], v[140:143], v[200:203], v[104:107]
	v_mfma_f32_16x16x32_bf16 v[92:95], v[132:135], v[208:211], v[92:95]
	v_mfma_f32_16x16x32_bf16 v[88:91], v[140:143], v[208:211], v[88:91]
	v_mfma_f32_16x16x32_bf16 v[76:79], v[132:135], v[216:219], v[76:79]
	v_mfma_f32_16x16x32_bf16 v[72:75], v[140:143], v[216:219], v[72:75]
	v_mfma_f32_16x16x32_bf16 v[116:119], v[156:159], v[192:195], v[116:119]
	v_mfma_f32_16x16x32_bf16 v[112:115], v[184:187], v[192:195], v[112:115]
	v_mfma_f32_16x16x32_bf16 v[100:103], v[156:159], v[200:203], v[100:103]
	v_mfma_f32_16x16x32_bf16 v[96:99], v[184:187], v[200:203], v[96:99]
	v_mfma_f32_16x16x32_bf16 v[84:87], v[156:159], v[208:211], v[84:87]
	v_mfma_f32_16x16x32_bf16 v[80:83], v[184:187], v[208:211], v[80:83]
	v_mfma_f32_16x16x32_bf16 v[68:71], v[156:159], v[216:219], v[68:71]
	v_mfma_f32_16x16x32_bf16 v[64:67], v[184:187], v[216:219], v[64:67]
	s_setprio 0
	s_barrier
	s_add_u32 s6, s34, 0x80
	s_addc_u32 s7, s35, 0
	s_add_i32 s36, s59, s39
	s_mov_b32 m0, s36
	ds_read_b128 v[188:191], v177 offset:49152
	ds_read_b128 v[192:195], v177 offset:50176
	ds_read_b128 v[196:199], v177 offset:51200
	global_load_lds_dwordx4 v169, s[6:7]
	s_add_i32 m0, s36, 0x2000
	ds_read_b128 v[200:203], v177 offset:52224
	global_load_lds_dwordx4 v172, s[6:7]
	s_add_u32 s6, s34, 0x300080
	s_addc_u32 s7, s35, 0
	s_add_i32 s34, s60, s39
	s_mov_b32 m0, s34
	ds_read_b128 v[204:207], v177 offset:53248
	global_load_lds_dwordx4 v169, s[6:7]
	s_add_i32 m0, s34, 0x2000
	ds_read_b128 v[208:211], v177 offset:54272
	global_load_lds_dwordx4 v172, s[6:7]
	s_mov_b32 m0, s47
	ds_read_b128 v[212:215], v177 offset:55296
	global_load_lds_dwordx4 v167, s[30:31]
	s_mov_b32 m0, s48
	ds_read_b128 v[216:219], v177 offset:56320
	global_load_lds_dwordx4 v171, s[30:31]
	s_waitcnt vmcnt(8)
	s_waitcnt lgkmcnt(0)
	s_setprio 1
	s_waitcnt lgkmcnt(0)
	s_barrier
	v_mfma_f32_16x16x32_bf16 v[60:63], v[128:131], v[188:191], v[60:63]
	v_mfma_f32_16x16x32_bf16 v[56:59], v[136:139], v[188:191], v[56:59]
	v_mfma_f32_16x16x32_bf16 v[44:47], v[128:131], v[196:199], v[44:47]
	v_mfma_f32_16x16x32_bf16 v[40:43], v[136:139], v[196:199], v[40:43]
	v_mfma_f32_16x16x32_bf16 v[28:31], v[128:131], v[204:207], v[28:31]
	v_mfma_f32_16x16x32_bf16 v[24:27], v[136:139], v[204:207], v[24:27]
	v_mfma_f32_16x16x32_bf16 v[12:15], v[128:131], v[212:215], v[12:15]
	v_mfma_f32_16x16x32_bf16 v[8:11], v[136:139], v[212:215], v[8:11]
	v_mfma_f32_16x16x32_bf16 v[52:55], v[152:155], v[188:191], v[52:55]
	v_mfma_f32_16x16x32_bf16 v[48:51], v[160:163], v[188:191], v[48:51]
	v_mfma_f32_16x16x32_bf16 v[36:39], v[152:155], v[196:199], v[36:39]
	v_mfma_f32_16x16x32_bf16 v[32:35], v[160:163], v[196:199], v[32:35]
	v_mfma_f32_16x16x32_bf16 v[20:23], v[152:155], v[204:207], v[20:23]
	v_mfma_f32_16x16x32_bf16 v[16:19], v[160:163], v[204:207], v[16:19]
	v_mfma_f32_16x16x32_bf16 v[4:7], v[152:155], v[212:215], v[4:7]
	v_mfma_f32_16x16x32_bf16 v[0:3], v[160:163], v[212:215], v[0:3]
	v_mfma_f32_16x16x32_bf16 v[60:63], v[132:135], v[192:195], v[60:63]
	v_mfma_f32_16x16x32_bf16 v[56:59], v[140:143], v[192:195], v[56:59]
	v_mfma_f32_16x16x32_bf16 v[44:47], v[132:135], v[200:203], v[44:47]
	v_mfma_f32_16x16x32_bf16 v[40:43], v[140:143], v[200:203], v[40:43]
	v_mfma_f32_16x16x32_bf16 v[28:31], v[132:135], v[208:211], v[28:31]
	v_mfma_f32_16x16x32_bf16 v[24:27], v[140:143], v[208:211], v[24:27]
	v_mfma_f32_16x16x32_bf16 v[12:15], v[132:135], v[216:219], v[12:15]
	v_mfma_f32_16x16x32_bf16 v[8:11], v[140:143], v[216:219], v[8:11]
	v_mfma_f32_16x16x32_bf16 v[52:55], v[156:159], v[192:195], v[52:55]
	v_mfma_f32_16x16x32_bf16 v[48:51], v[184:187], v[192:195], v[48:51]
	v_mfma_f32_16x16x32_bf16 v[36:39], v[156:159], v[200:203], v[36:39]
	v_mfma_f32_16x16x32_bf16 v[32:35], v[184:187], v[200:203], v[32:35]
	v_mfma_f32_16x16x32_bf16 v[20:23], v[156:159], v[208:211], v[20:23]
	v_mfma_f32_16x16x32_bf16 v[16:19], v[184:187], v[208:211], v[16:19]
	v_mfma_f32_16x16x32_bf16 v[4:7], v[156:159], v[216:219], v[4:7]
	v_mfma_f32_16x16x32_bf16 v[0:3], v[184:187], v[216:219], v[0:3]
	s_setprio 0
	s_barrier
	s_add_i32 s58, s58, 2
	s_add_u32 s4, s4, 0x100
	s_addc_u32 s5, s5, 0
	s_cmpk_gt_u32 s58, 0xbd
	s_mov_b64 s[6:7], s[28:29]
	s_cbranch_scc0 .LBB0_1217
	s_and_b64 vcc, exec, s[18:19]
	s_cbranch_vccz .LBB0_1220
	s_barrier
